# EpiRes0 load hoist + K-loop MFMA-run code placement (nops in load-segment slack so each MFMA run starts at 4 mod 16)
# baseline (speedup 1.0000x reference)
; #define PG8_STAGE(bufoff, gbase, voff) do { _Pragma("unroll") for (int _i = 0; _i < 2; ++_i) \
;         __builtin_amdgcn_global_load_lds((const unsigned*)((const char*)(gbase) + (voff)[_i]), (LAS unsigned*)(lds + (bufoff) + ldsw + _i * 8192), 16, 0, 0); } while (0)
; #define PG8_LDA(dst, b, h) do { _Pragma("unroll") for (int m = 0; m < 4; ++m) _Pragma("unroll") for (int k = 0; k < 2; ++k) dst[m][k] = *(const LAS bf16x8*)(lds + PG8_SA(b, h) + aoff + m * 2048 + k * 1024); } while (0)
; #define PG8_LDB(dst, b, h) do { _Pragma("unroll") for (int n = 0; n < 2; ++n) _Pragma("unroll") for (int k = 0; k < 2; ++k) dst[n][k] = *(const LAS bf16x8*)(lds + PG8_SB(b, h) + boff + n * 2048 + k * 1024); } while (0)
; #define PG8_MMA(ai, bj, At, Bt) do { __builtin_amdgcn_s_setprio(1); _Pragma("unroll") for (int m = 0; m < 4; ++m) _Pragma("unroll") for (int n = 0; n < 2; ++n) _Pragma("unroll") for (int k = 0; k < 2; ++k) \
;         acc[ai][bj][m][n] = __builtin_amdgcn_mfma_f32_16x16x32_bf16(Bt[n][k], At[m][k], acc[ai][bj][m][n], 0, 0, 0); __builtin_amdgcn_s_setprio(0); } while (0)
; #define PG8_WAIT_V(n) asm volatile("s_waitcnt vmcnt(" #n ")" ::: "memory")
; template <class Epi, class Sched>
; __device__ __forceinline__ void gemm_phase(LAS unsigned char* lds, const Gemm g, const Sched& S, const Epi& E) {
;     ...
;         const bool has_next = S.next(ui + 1, nxt);
;         const char* nA = has_next ? (const char*)g.A + (size_t)nxt.pm * tstepA : cA; const char* nB = has_next ? (const char*)g.Bt + (size_t)nxt.pn * tstepB : cB;
;         for (int t = 0; t < nt; t += 2) {
;             const bool last = (t == nt - 2);
;             const char* a1 = cA + (size_t)(t + 1) * kstep;
;             const char* a2 = last ? nA : cA + (size_t)(t + 2) * kstep; const char* b2 = last ? nB : cB + (size_t)(t + 2) * kstep;
;             const char* a3 = a2 + kstep; const char* b3 = b2 + kstep;
;             PG8_LDB(B0, 0, 0); PG8_LDB(B1, 0, 1); PG8_SCHED; PG8_LDA(At, 0, 0); PG8_STAGE(PG8_SA(1, 1), a1 + hstepA, voffA);
;             PG8_WAIT_V(8); PG8_WAIT_L(0); PG8_BAR; PG8_MMA(0, 0, At, B0); PG8_MMA(0, 1, At, B1); PG8_BAR; PG8_SCHED;
;             PG8_LDA(At, 0, 1); PG8_STAGE(PG8_SB(0, 0), b2, voffB); PG8_STAGE(PG8_SB(0, 1), b2 + hstepB, voffB); PG8_STAGE(PG8_SA(0, 0), a2, voffA);
;             PG8_WAIT_V(8); PG8_WAIT_L(0); PG8_BAR; PG8_MMA(1, 0, At, B0); PG8_MMA(1, 1, At, B1); PG8_BAR; PG8_SCHED;
.LBB0_3336:
	s_add_u32 s41, s34, s40
	s_addc_u32 s46, s35, 0
	s_add_u32 s44, s41, 0x100
	s_addc_u32 s45, s46, 0
	s_and_b64 s[42:43], s[38:39], exec
	s_cselect_b32 s43, s23, s45
	s_cselect_b32 s42, s71, s44
	s_add_u32 s40, s30, s40
	s_addc_u32 s44, s31, 0
	s_add_u32 s40, s40, 0x100
	s_addc_u32 s44, s44, 0
	s_and_b64 s[38:39], s[38:39], exec
	s_cselect_b32 s45, s21, s44
	s_cselect_b32 s44, s72, s40
	s_add_u32 s48, s41, 0x10080
	ds_read_b128 v[144:147], v141
	ds_read_b128 v[148:151], v141 offset:1024
	ds_read_b128 v[152:155], v141 offset:2048
	ds_read_b128 v[156:159], v141 offset:3072
	ds_read_b128 v[160:163], v142
	ds_read_b128 v[164:167], v142 offset:1024
	ds_read_b128 v[168:171], v142 offset:2048
	ds_read_b128 v[172:175], v142 offset:3072
	s_addc_u32 s49, s46, 0
	s_add_i32 s80, s62, s52
	s_add_i32 m0, s53, 0xc000
	s_add_i32 s83, s53, 0xe000
	s_add_i32 s77, s80, 0x2000
	s_add_u32 s46, s44, 0x40000
	s_addc_u32 s47, s45, 0
	s_add_i32 s79, s63, s52
	s_add_i32 s78, s79, 0x2000
	s_add_i32 s76, 0, 0x18000
	s_add_i32 s75, 0, 0x1c000
	s_add_u32 s40, s42, 0x10000
	s_addc_u32 s41, s43, 0
	s_add_i32 s74, s76, s52
	s_add_i32 s73, s74, 0x2000
	s_add_u32 s38, s44, 0x40080
	s_addc_u32 s39, s45, 0
	s_add_i32 s82, s75, s52
	s_add_i32 s81, s82, 0x2000
	v_lshl_add_u64 v[136:137], s[48:49], 0, v[128:129]
	ds_read_b128 v[176:179], v143
	ds_read_b128 v[180:183], v143 offset:1024
	ds_read_b128 v[184:187], v143 offset:2048
	ds_read_b128 v[188:191], v143 offset:3072
	ds_read_b128 v[196:199], v143 offset:4096
	ds_read_b128 v[200:203], v143 offset:5120
	ds_read_b128 v[204:207], v143 offset:6144
	ds_read_b128 v[208:211], v143 offset:7168
	global_load_lds_dwordx4 v[136:137], off
	v_lshl_add_u64 v[136:137], s[48:49], 0, v[132:133]
	s_mov_b32 m0, s83
	s_nop 0
	global_load_lds_dwordx4 v[136:137], off
	s_nop 0
	s_nop 0
	s_waitcnt vmcnt(8)
	s_waitcnt lgkmcnt(0)
	s_barrier
	s_setprio 1
	s_waitcnt lgkmcnt(0)
	v_mfma_f32_16x16x32_bf16 v[124:127], v[144:147], v[176:179], v[124:127]
	v_mfma_f32_16x16x32_bf16 v[120:123], v[152:155], v[176:179], v[120:123]
	v_mfma_f32_16x16x32_bf16 v[112:115], v[144:147], v[184:187], v[112:115]
	v_mfma_f32_16x16x32_bf16 v[104:107], v[152:155], v[184:187], v[104:107]
	v_mfma_f32_16x16x32_bf16 v[96:99], v[144:147], v[196:199], v[96:99]
	v_mfma_f32_16x16x32_bf16 v[88:91], v[152:155], v[196:199], v[88:91]
	v_mfma_f32_16x16x32_bf16 v[80:83], v[144:147], v[204:207], v[80:83]
	v_mfma_f32_16x16x32_bf16 v[72:75], v[152:155], v[204:207], v[72:75]
	v_mfma_f32_16x16x32_bf16 v[124:127], v[148:151], v[180:183], v[124:127]
	v_mfma_f32_16x16x32_bf16 v[120:123], v[156:159], v[180:183], v[120:123]
	v_mfma_f32_16x16x32_bf16 v[112:115], v[148:151], v[188:191], v[112:115]
	v_mfma_f32_16x16x32_bf16 v[104:107], v[156:159], v[188:191], v[104:107]
	v_mfma_f32_16x16x32_bf16 v[96:99], v[148:151], v[200:203], v[96:99]
	v_mfma_f32_16x16x32_bf16 v[88:91], v[156:159], v[200:203], v[88:91]
	v_mfma_f32_16x16x32_bf16 v[80:83], v[148:151], v[208:211], v[80:83]
	v_mfma_f32_16x16x32_bf16 v[72:75], v[156:159], v[208:211], v[72:75]
	s_setprio 0
	s_setprio 1
	v_mfma_f32_16x16x32_bf16 v[116:119], v[160:163], v[176:179], v[116:119]
	v_mfma_f32_16x16x32_bf16 v[108:111], v[168:171], v[176:179], v[108:111]
	v_mfma_f32_16x16x32_bf16 v[100:103], v[160:163], v[184:187], v[100:103]
	v_mfma_f32_16x16x32_bf16 v[92:95], v[168:171], v[184:187], v[92:95]
	v_mfma_f32_16x16x32_bf16 v[84:87], v[160:163], v[196:199], v[84:87]
	v_mfma_f32_16x16x32_bf16 v[76:79], v[168:171], v[196:199], v[76:79]
	v_mfma_f32_16x16x32_bf16 v[68:71], v[160:163], v[204:207], v[68:71]
	v_mfma_f32_16x16x32_bf16 v[64:67], v[168:171], v[204:207], v[64:67]
	v_mfma_f32_16x16x32_bf16 v[116:119], v[164:167], v[180:183], v[116:119]
	v_mfma_f32_16x16x32_bf16 v[108:111], v[172:175], v[180:183], v[108:111]
	v_mfma_f32_16x16x32_bf16 v[100:103], v[164:167], v[188:191], v[100:103]
	v_mfma_f32_16x16x32_bf16 v[92:95], v[172:175], v[188:191], v[92:95]
	v_mfma_f32_16x16x32_bf16 v[84:87], v[164:167], v[200:203], v[84:87]
	v_mfma_f32_16x16x32_bf16 v[76:79], v[172:175], v[200:203], v[76:79]
	v_mfma_f32_16x16x32_bf16 v[68:71], v[164:167], v[208:211], v[68:71]
	v_mfma_f32_16x16x32_bf16 v[64:67], v[172:175], v[208:211], v[64:67]
	s_setprio 0
	s_barrier
	s_mov_b32 m0, s80
	v_lshl_add_u64 v[136:137], s[44:45], 0, v[130:131]
	ds_read_b128 v[176:179], v143 offset:16384
	ds_read_b128 v[180:183], v143 offset:17408
	ds_read_b128 v[184:187], v143 offset:18432
	ds_read_b128 v[188:191], v143 offset:19456
	ds_read_b128 v[196:199], v143 offset:20480
	ds_read_b128 v[200:203], v143 offset:21504
	ds_read_b128 v[204:207], v143 offset:22528
	ds_read_b128 v[208:211], v143 offset:23552
	global_load_lds_dwordx4 v[136:137], off
	v_lshl_add_u64 v[192:193], s[44:45], 0, v[134:135]
	s_mov_b32 m0, s77
	v_lshl_add_u64 v[212:213], s[46:47], 0, v[130:131]
	global_load_lds_dwordx4 v[192:193], off
	s_mov_b32 m0, s79
	v_lshl_add_u64 v[214:215], s[42:43], 0, v[132:133]
	global_load_lds_dwordx4 v[212:213], off
	v_lshl_add_u64 v[212:213], s[46:47], 0, v[134:135]
	s_mov_b32 m0, s78
	s_nop 0
	global_load_lds_dwordx4 v[212:213], off
	v_lshl_add_u64 v[212:213], s[42:43], 0, v[128:129]
	s_mov_b32 m0, s53
	s_nop 0
	global_load_lds_dwordx4 v[212:213], off
	s_mov_b32 m0, s54
	s_nop 0
	global_load_lds_dwordx4 v[214:215], off
	s_nop 0
	s_nop 0
	s_waitcnt vmcnt(8)
	s_waitcnt lgkmcnt(0)
	s_barrier
; #define PG8_STAGE(bufoff, gbase, voff) do { _Pragma("unroll") for (int _i = 0; _i < 2; ++_i) \
;         __builtin_amdgcn_global_load_lds((const unsigned*)((const char*)(gbase) + (voff)[_i]), (LAS unsigned*)(lds + (bufoff) + ldsw + _i * 8192), 16, 0, 0); } while (0)
; #define PG8_LDA(dst, b, h) do { _Pragma("unroll") for (int m = 0; m < 4; ++m) _Pragma("unroll") for (int k = 0; k < 2; ++k) dst[m][k] = *(const LAS bf16x8*)(lds + PG8_SA(b, h) + aoff + m * 2048 + k * 1024); } while (0)
; #define PG8_LDB(dst, b, h) do { _Pragma("unroll") for (int n = 0; n < 2; ++n) _Pragma("unroll") for (int k = 0; k < 2; ++k) dst[n][k] = *(const LAS bf16x8*)(lds + PG8_SB(b, h) + boff + n * 2048 + k * 1024); } while (0)
; #define PG8_MMA(ai, bj, At, Bt) do { __builtin_amdgcn_s_setprio(1); _Pragma("unroll") for (int m = 0; m < 4; ++m) _Pragma("unroll") for (int n = 0; n < 2; ++n) _Pragma("unroll") for (int k = 0; k < 2; ++k) \
;         acc[ai][bj][m][n] = __builtin_amdgcn_mfma_f32_16x16x32_bf16(Bt[n][k], At[m][k], acc[ai][bj][m][n], 0, 0, 0); __builtin_amdgcn_s_setprio(0); } while (0)
; #define PG8_WAIT_V(n) asm volatile("s_waitcnt vmcnt(" #n ")" ::: "memory")
; #define PG8_WAIT_L(n) asm volatile("s_waitcnt lgkmcnt(" #n ")" ::: "memory")
; #define PG8_BAR __builtin_amdgcn_s_barrier()
; #define PG8_SCHED __builtin_amdgcn_sched_barrier(0)
; template <class Epi, class Sched>
; __device__ __forceinline__ void gemm_phase(LAS unsigned char* lds, const Gemm g, const Sched& S, const Epi& E) {
;     ...
;             PG8_WAIT_V(8); PG8_WAIT_L(0); PG8_BAR; PG8_MMA(1, 0, At, B0); PG8_MMA(1, 1, At, B1); PG8_BAR; PG8_SCHED;
;             PG8_LDB(B0, 1, 0); PG8_LDB(B1, 1, 1); PG8_SCHED; PG8_LDA(At, 1, 0); PG8_STAGE(PG8_SA(0, 1), a2 + hstepA, voffA);
;             PG8_WAIT_V(8); PG8_WAIT_L(0); PG8_BAR; PG8_MMA(0, 0, At, B0); PG8_MMA(0, 1, At, B1); PG8_BAR; PG8_SCHED;
	s_setprio 1
	s_waitcnt lgkmcnt(0)
	v_mfma_f32_16x16x32_bf16 v[60:63], v[144:147], v[176:179], v[60:63]
	v_mfma_f32_16x16x32_bf16 v[56:59], v[152:155], v[176:179], v[56:59]
	v_mfma_f32_16x16x32_bf16 v[48:51], v[144:147], v[184:187], v[48:51]
	v_mfma_f32_16x16x32_bf16 v[40:43], v[152:155], v[184:187], v[40:43]
	v_mfma_f32_16x16x32_bf16 v[32:35], v[144:147], v[196:199], v[32:35]
	v_mfma_f32_16x16x32_bf16 v[24:27], v[152:155], v[196:199], v[24:27]
	v_mfma_f32_16x16x32_bf16 v[16:19], v[144:147], v[204:207], v[16:19]
	v_mfma_f32_16x16x32_bf16 v[8:11], v[152:155], v[204:207], v[8:11]
	v_mfma_f32_16x16x32_bf16 v[60:63], v[148:151], v[180:183], v[60:63]
	v_mfma_f32_16x16x32_bf16 v[56:59], v[156:159], v[180:183], v[56:59]
	v_mfma_f32_16x16x32_bf16 v[48:51], v[148:151], v[188:191], v[48:51]
	v_mfma_f32_16x16x32_bf16 v[40:43], v[156:159], v[188:191], v[40:43]
	v_mfma_f32_16x16x32_bf16 v[32:35], v[148:151], v[200:203], v[32:35]
	v_mfma_f32_16x16x32_bf16 v[24:27], v[156:159], v[200:203], v[24:27]
	v_mfma_f32_16x16x32_bf16 v[16:19], v[148:151], v[208:211], v[16:19]
	v_mfma_f32_16x16x32_bf16 v[8:11], v[156:159], v[208:211], v[8:11]
	s_setprio 0
	s_setprio 1
	v_mfma_f32_16x16x32_bf16 v[52:55], v[160:163], v[176:179], v[52:55]
	v_mfma_f32_16x16x32_bf16 v[44:47], v[168:171], v[176:179], v[44:47]
	v_mfma_f32_16x16x32_bf16 v[36:39], v[160:163], v[184:187], v[36:39]
	v_mfma_f32_16x16x32_bf16 v[28:31], v[168:171], v[184:187], v[28:31]
	v_mfma_f32_16x16x32_bf16 v[20:23], v[160:163], v[196:199], v[20:23]
	v_mfma_f32_16x16x32_bf16 v[12:15], v[168:171], v[196:199], v[12:15]
	v_mfma_f32_16x16x32_bf16 v[4:7], v[160:163], v[204:207], v[4:7]
	v_mfma_f32_16x16x32_bf16 v[0:3], v[168:171], v[204:207], v[0:3]
	v_mfma_f32_16x16x32_bf16 v[52:55], v[164:167], v[180:183], v[52:55]
	v_mfma_f32_16x16x32_bf16 v[44:47], v[172:175], v[180:183], v[44:47]
	v_mfma_f32_16x16x32_bf16 v[36:39], v[164:167], v[188:191], v[36:39]
	v_mfma_f32_16x16x32_bf16 v[28:31], v[172:175], v[188:191], v[28:31]
	v_mfma_f32_16x16x32_bf16 v[20:23], v[164:167], v[200:203], v[20:23]
	v_mfma_f32_16x16x32_bf16 v[12:15], v[172:175], v[200:203], v[12:15]
	v_mfma_f32_16x16x32_bf16 v[4:7], v[164:167], v[208:211], v[4:7]
	v_mfma_f32_16x16x32_bf16 v[0:3], v[172:175], v[208:211], v[0:3]
	s_setprio 0
	s_barrier
	v_add_u32_e32 v156, s76, v140
	v_add_u32_e32 v172, s75, v140
	ds_read_b128 v[144:147], v156
	ds_read_b128 v[148:151], v156 offset:1024
	ds_read_b128 v[152:155], v156 offset:2048
	ds_read_b128 v[156:159], v156 offset:3072
	ds_read_b128 v[160:163], v172
	ds_read_b128 v[164:167], v172 offset:1024
	ds_read_b128 v[168:171], v172 offset:2048
	ds_read_b128 v[172:175], v172 offset:3072
	s_mov_b32 m0, s55
	v_lshl_add_u64 v[216:217], s[40:41], 0, v[128:129]
	ds_read_b128 v[176:179], v143 offset:32768
	ds_read_b128 v[180:183], v143 offset:33792
	ds_read_b128 v[184:187], v143 offset:34816
	ds_read_b128 v[188:191], v143 offset:35840
	ds_read_b128 v[196:199], v143 offset:36864
	ds_read_b128 v[200:203], v143 offset:37888
	ds_read_b128 v[204:207], v143 offset:38912
	ds_read_b128 v[208:211], v143 offset:39936
	global_load_lds_dwordx4 v[216:217], off
	v_lshl_add_u64 v[216:217], s[40:41], 0, v[132:133]
	s_mov_b32 m0, s56
	s_nop 0
	global_load_lds_dwordx4 v[216:217], off
	s_nop 0
	s_nop 0
	s_waitcnt vmcnt(8)
	s_waitcnt lgkmcnt(0)
	s_barrier
	s_setprio 1
	s_waitcnt lgkmcnt(0)
	v_mfma_f32_16x16x32_bf16 v[124:127], v[144:147], v[176:179], v[124:127]
	v_mfma_f32_16x16x32_bf16 v[120:123], v[152:155], v[176:179], v[120:123]
	v_mfma_f32_16x16x32_bf16 v[112:115], v[144:147], v[184:187], v[112:115]
	v_mfma_f32_16x16x32_bf16 v[104:107], v[152:155], v[184:187], v[104:107]
	v_mfma_f32_16x16x32_bf16 v[96:99], v[144:147], v[196:199], v[96:99]
	v_mfma_f32_16x16x32_bf16 v[88:91], v[152:155], v[196:199], v[88:91]
	v_mfma_f32_16x16x32_bf16 v[80:83], v[144:147], v[204:207], v[80:83]
	v_mfma_f32_16x16x32_bf16 v[72:75], v[152:155], v[204:207], v[72:75]
	v_mfma_f32_16x16x32_bf16 v[124:127], v[148:151], v[180:183], v[124:127]
	v_mfma_f32_16x16x32_bf16 v[120:123], v[156:159], v[180:183], v[120:123]
	v_mfma_f32_16x16x32_bf16 v[112:115], v[148:151], v[188:191], v[112:115]
	v_mfma_f32_16x16x32_bf16 v[104:107], v[156:159], v[188:191], v[104:107]
	v_mfma_f32_16x16x32_bf16 v[96:99], v[148:151], v[200:203], v[96:99]
	v_mfma_f32_16x16x32_bf16 v[88:91], v[156:159], v[200:203], v[88:91]
	v_mfma_f32_16x16x32_bf16 v[80:83], v[148:151], v[208:211], v[80:83]
	v_mfma_f32_16x16x32_bf16 v[72:75], v[156:159], v[208:211], v[72:75]
	s_setprio 0
	s_setprio 1
	v_mfma_f32_16x16x32_bf16 v[116:119], v[160:163], v[176:179], v[116:119]
	v_mfma_f32_16x16x32_bf16 v[108:111], v[168:171], v[176:179], v[108:111]
	v_mfma_f32_16x16x32_bf16 v[100:103], v[160:163], v[184:187], v[100:103]
	v_mfma_f32_16x16x32_bf16 v[92:95], v[168:171], v[184:187], v[92:95]
	v_mfma_f32_16x16x32_bf16 v[84:87], v[160:163], v[196:199], v[84:87]
	v_mfma_f32_16x16x32_bf16 v[76:79], v[168:171], v[196:199], v[76:79]
	v_mfma_f32_16x16x32_bf16 v[68:71], v[160:163], v[204:207], v[68:71]
	v_mfma_f32_16x16x32_bf16 v[64:67], v[168:171], v[204:207], v[64:67]
	v_mfma_f32_16x16x32_bf16 v[116:119], v[164:167], v[180:183], v[116:119]
	v_mfma_f32_16x16x32_bf16 v[108:111], v[172:175], v[180:183], v[108:111]
	v_mfma_f32_16x16x32_bf16 v[100:103], v[164:167], v[188:191], v[100:103]
	v_mfma_f32_16x16x32_bf16 v[92:95], v[172:175], v[188:191], v[92:95]
	v_mfma_f32_16x16x32_bf16 v[84:87], v[164:167], v[200:203], v[84:87]
	v_mfma_f32_16x16x32_bf16 v[76:79], v[172:175], v[200:203], v[76:79]
	v_mfma_f32_16x16x32_bf16 v[68:71], v[164:167], v[208:211], v[68:71]
	v_mfma_f32_16x16x32_bf16 v[64:67], v[172:175], v[208:211], v[64:67]
	s_setprio 0
	s_barrier
; #define PG8_STAGE(bufoff, gbase, voff) do { _Pragma("unroll") for (int _i = 0; _i < 2; ++_i) \
;         __builtin_amdgcn_global_load_lds((const unsigned*)((const char*)(gbase) + (voff)[_i]), (LAS unsigned*)(lds + (bufoff) + ldsw + _i * 8192), 16, 0, 0); } while (0)
; #define PG8_LDA(dst, b, h) do { _Pragma("unroll") for (int m = 0; m < 4; ++m) _Pragma("unroll") for (int k = 0; k < 2; ++k) dst[m][k] = *(const LAS bf16x8*)(lds + PG8_SA(b, h) + aoff + m * 2048 + k * 1024); } while (0)
; #define PG8_MMA(ai, bj, At, Bt) do { __builtin_amdgcn_s_setprio(1); _Pragma("unroll") for (int m = 0; m < 4; ++m) _Pragma("unroll") for (int n = 0; n < 2; ++n) _Pragma("unroll") for (int k = 0; k < 2; ++k) \
;         acc[ai][bj][m][n] = __builtin_amdgcn_mfma_f32_16x16x32_bf16(Bt[n][k], At[m][k], acc[ai][bj][m][n], 0, 0, 0); __builtin_amdgcn_s_setprio(0); } while (0)
; #define PG8_WAIT_V(n) asm volatile("s_waitcnt vmcnt(" #n ")" ::: "memory")
; #define PG8_WAIT_L(n) asm volatile("s_waitcnt lgkmcnt(" #n ")" ::: "memory")
; #define PG8_BAR __builtin_amdgcn_s_barrier()
; #define PG8_SCHED __builtin_amdgcn_sched_barrier(0)
; template <class Epi, class Sched>
; __device__ __forceinline__ void gemm_phase(LAS unsigned char* lds, const Gemm g, const Sched& S, const Epi& E) {
;     ...
;             PG8_LDA(At, 1, 1); PG8_STAGE(PG8_SB(1, 0), b3, voffB); PG8_STAGE(PG8_SB(1, 1), b3 + hstepB, voffB); PG8_STAGE(PG8_SA(1, 0), a3, voffA);
;             PG8_WAIT_V(8); PG8_WAIT_L(0); PG8_BAR; PG8_MMA(1, 0, At, B0); PG8_MMA(1, 1, At, B1); PG8_BAR; PG8_SCHED;
;         }
;         if (wr == 0) PG8_BAR;
	s_mov_b32 m0, s74
	v_lshl_add_u64 v[136:137], v[136:137], 0, s[8:9]
	ds_read_b128 v[176:179], v143 offset:49152
	ds_read_b128 v[180:183], v143 offset:50176
	ds_read_b128 v[184:187], v143 offset:51200
	ds_read_b128 v[188:191], v143 offset:52224
	ds_read_b128 v[196:199], v143 offset:53248
	ds_read_b128 v[200:203], v143 offset:54272
	ds_read_b128 v[204:207], v143 offset:55296
	ds_read_b128 v[208:211], v143 offset:56320
	global_load_lds_dwordx4 v[136:137], off
	v_lshl_add_u64 v[136:137], v[192:193], 0, s[8:9]
	s_mov_b32 m0, s73
	s_nop 0
	global_load_lds_dwordx4 v[136:137], off
	v_lshl_add_u64 v[136:137], s[38:39], 0, v[130:131]
	s_mov_b32 m0, s82
	s_nop 0
	global_load_lds_dwordx4 v[136:137], off
	v_lshl_add_u64 v[136:137], s[38:39], 0, v[134:135]
	s_mov_b32 m0, s81
	s_nop 0
	global_load_lds_dwordx4 v[136:137], off
	v_lshl_add_u64 v[136:137], v[212:213], 0, s[8:9]
	s_mov_b32 m0, s59
	s_nop 0
	global_load_lds_dwordx4 v[136:137], off
	v_lshl_add_u64 v[136:137], v[214:215], 0, s[8:9]
	s_mov_b32 m0, s60
	s_nop 0
	global_load_lds_dwordx4 v[136:137], off
	s_waitcnt vmcnt(8)
	s_waitcnt lgkmcnt(0)
	s_barrier
	s_setprio 1
	s_waitcnt lgkmcnt(0)
	v_mfma_f32_16x16x32_bf16 v[60:63], v[144:147], v[176:179], v[60:63]
	v_mfma_f32_16x16x32_bf16 v[56:59], v[152:155], v[176:179], v[56:59]
	v_mfma_f32_16x16x32_bf16 v[48:51], v[144:147], v[184:187], v[48:51]
	v_mfma_f32_16x16x32_bf16 v[40:43], v[152:155], v[184:187], v[40:43]
	v_mfma_f32_16x16x32_bf16 v[32:35], v[144:147], v[196:199], v[32:35]
	v_mfma_f32_16x16x32_bf16 v[24:27], v[152:155], v[196:199], v[24:27]
	v_mfma_f32_16x16x32_bf16 v[16:19], v[144:147], v[204:207], v[16:19]
	v_mfma_f32_16x16x32_bf16 v[8:11], v[152:155], v[204:207], v[8:11]
	v_mfma_f32_16x16x32_bf16 v[60:63], v[148:151], v[180:183], v[60:63]
	v_mfma_f32_16x16x32_bf16 v[56:59], v[156:159], v[180:183], v[56:59]
	v_mfma_f32_16x16x32_bf16 v[48:51], v[148:151], v[188:191], v[48:51]
	v_mfma_f32_16x16x32_bf16 v[40:43], v[156:159], v[188:191], v[40:43]
	v_mfma_f32_16x16x32_bf16 v[32:35], v[148:151], v[200:203], v[32:35]
	v_mfma_f32_16x16x32_bf16 v[24:27], v[156:159], v[200:203], v[24:27]
	v_mfma_f32_16x16x32_bf16 v[16:19], v[148:151], v[208:211], v[16:19]
	v_mfma_f32_16x16x32_bf16 v[8:11], v[156:159], v[208:211], v[8:11]
	s_setprio 0
	s_setprio 1
	v_mfma_f32_16x16x32_bf16 v[52:55], v[160:163], v[176:179], v[52:55]
	v_mfma_f32_16x16x32_bf16 v[44:47], v[168:171], v[176:179], v[44:47]
	v_mfma_f32_16x16x32_bf16 v[36:39], v[160:163], v[184:187], v[36:39]
	v_mfma_f32_16x16x32_bf16 v[28:31], v[168:171], v[184:187], v[28:31]
	v_mfma_f32_16x16x32_bf16 v[20:23], v[160:163], v[196:199], v[20:23]
	v_mfma_f32_16x16x32_bf16 v[12:15], v[168:171], v[196:199], v[12:15]
	v_mfma_f32_16x16x32_bf16 v[4:7], v[160:163], v[204:207], v[4:7]
	v_mfma_f32_16x16x32_bf16 v[0:3], v[168:171], v[204:207], v[0:3]
	v_mfma_f32_16x16x32_bf16 v[52:55], v[164:167], v[180:183], v[52:55]
	v_mfma_f32_16x16x32_bf16 v[44:47], v[172:175], v[180:183], v[44:47]
	v_mfma_f32_16x16x32_bf16 v[36:39], v[164:167], v[188:191], v[36:39]
	v_mfma_f32_16x16x32_bf16 v[28:31], v[172:175], v[188:191], v[28:31]
	v_mfma_f32_16x16x32_bf16 v[20:23], v[164:167], v[200:203], v[20:23]
	v_mfma_f32_16x16x32_bf16 v[12:15], v[172:175], v[200:203], v[12:15]
	v_mfma_f32_16x16x32_bf16 v[4:7], v[164:167], v[208:211], v[4:7]
	v_mfma_f32_16x16x32_bf16 v[0:3], v[172:175], v[208:211], v[0:3]
	s_setprio 0
	s_barrier
	s_movk_i32 s40, 0x100
	s_andn2_b64 vcc, exec, s[36:37]
	s_mov_b64 s[38:39], -1
	s_mov_b64 s[36:37], 0
	s_cbranch_vccz .LBB0_3336
	s_and_b64 vcc, exec, s[10:11]
	s_cbranch_vccz .LBB0_3339
	s_barrier

; #define PG8_STAGE(bufoff, gbase, voff) do { _Pragma("unroll") for (int _i = 0; _i < 2; ++_i) \
;         __builtin_amdgcn_global_load_lds((const unsigned*)((const char*)(gbase) + (voff)[_i]), (LAS unsigned*)(lds + (bufoff) + ldsw + _i * 8192), 16, 0, 0); } while (0)
; #define PG8_LDA(dst, b, h) do { _Pragma("unroll") for (int m = 0; m < 4; ++m) _Pragma("unroll") for (int k = 0; k < 2; ++k) dst[m][k] = *(const LAS bf16x8*)(lds + PG8_SA(b, h) + aoff + m * 2048 + k * 1024); } while (0)
; #define PG8_LDB(dst, b, h) do { _Pragma("unroll") for (int n = 0; n < 2; ++n) _Pragma("unroll") for (int k = 0; k < 2; ++k) dst[n][k] = *(const LAS bf16x8*)(lds + PG8_SB(b, h) + boff + n * 2048 + k * 1024); } while (0)
; #define PG8_MMA(ai, bj, At, Bt) do { __builtin_amdgcn_s_setprio(1); _Pragma("unroll") for (int m = 0; m < 4; ++m) _Pragma("unroll") for (int n = 0; n < 2; ++n) _Pragma("unroll") for (int k = 0; k < 2; ++k) \
;         acc[ai][bj][m][n] = __builtin_amdgcn_mfma_f32_16x16x32_bf16(Bt[n][k], At[m][k], acc[ai][bj][m][n], 0, 0, 0); __builtin_amdgcn_s_setprio(0); } while (0)
; #define PG8_WAIT_V(n) asm volatile("s_waitcnt vmcnt(" #n ")" ::: "memory")
; #define PG8_WAIT_L(n) asm volatile("s_waitcnt lgkmcnt(" #n ")" ::: "memory")
; #define PG8_BAR __builtin_amdgcn_s_barrier()
; #define PG8_SCHED __builtin_amdgcn_sched_barrier(0)
; template <class Epi, class Sched>
; __device__ __forceinline__ void gemm_phase(LAS unsigned char* lds, const Gemm g, const Sched& S, const Epi& E) {
;     ...
;         for (int t = 0; t < nt; t += 2) {
;             const bool last = (t == nt - 2);
;             const char* a1 = cA + (size_t)(t + 1) * kstep;
;             const char* a2 = last ? nA : cA + (size_t)(t + 2) * kstep; const char* b2 = last ? nB : cB + (size_t)(t + 2) * kstep;
;             const char* a3 = a2 + kstep; const char* b3 = b2 + kstep;
;             PG8_LDB(B0, 0, 0); PG8_LDB(B1, 0, 1); PG8_SCHED; PG8_LDA(At, 0, 0); PG8_STAGE(PG8_SA(1, 1), a1 + hstepA, voffA);
;             PG8_WAIT_V(8); PG8_WAIT_L(0); PG8_BAR; PG8_MMA(0, 0, At, B0); PG8_MMA(0, 1, At, B1); PG8_BAR; PG8_SCHED;
;             PG8_LDA(At, 0, 1); PG8_STAGE(PG8_SB(0, 0), b2, voffB); PG8_STAGE(PG8_SB(0, 1), b2 + hstepB, voffB); PG8_STAGE(PG8_SA(0, 0), a2, voffA);
.LBB0_3415:
	s_add_u32 s20, s18, 0xfff80080
	s_addc_u32 s21, s19, -1
	s_add_i32 s47, 0, 0x10000
	s_cmp_eq_u32 s46, 28
	s_cselect_b32 s23, s11, s21
	s_cselect_b32 s22, s17, s20
	s_cselect_b32 s21, s7, s45
	s_cselect_b32 s20, s24, s25
	s_add_i32 s50, 0, 0x14000
	v_add_u32_e32 v170, s47, v1
	v_add_u32_e32 v183, s50, v1
	s_waitcnt lgkmcnt(0)
	ds_read_b128 v[142:145], v170
	ds_read_b128 v[162:165], v170 offset:1024
	ds_read_b128 v[166:169], v170 offset:2048
	ds_read_b128 v[170:173], v170 offset:3072
	ds_read_b128 v[174:177], v183
	ds_read_b128 v[178:181], v183 offset:1024
	ds_read_b128 v[184:187], v183 offset:2048
	ds_read_b128 v[188:191], v183 offset:3072
	v_lshl_add_u64 v[192:193], s[18:19], 0, v[138:139]
	s_add_i32 m0, s31, 0xc000
	ds_read_b128 v[208:211], v182
	ds_read_b128 v[212:215], v182 offset:1024
	ds_read_b128 v[216:219], v182 offset:2048
	ds_read_b128 v[220:223], v182 offset:3072
	ds_read_b128 v[224:227], v182 offset:4096
	ds_read_b128 v[228:231], v182 offset:5120
	ds_read_b128 v[232:235], v182 offset:6144
	ds_read_b128 v[236:239], v182 offset:7168
	global_load_lds_dwordx4 v[192:193], off
	v_lshl_add_u64 v[192:193], s[18:19], 0, v[140:141]
	s_add_i32 m0, s31, 0xe000
	s_nop 0
	global_load_lds_dwordx4 v[192:193], off
	s_nop 0
	s_nop 0
	s_waitcnt vmcnt(8)
	s_waitcnt lgkmcnt(0)
	s_barrier
	s_setprio 1
	s_waitcnt lgkmcnt(0)
	v_mfma_f32_16x16x32_bf16 v[126:129], v[142:145], v[208:211], v[126:129]
	v_mfma_f32_16x16x32_bf16 v[122:125], v[166:169], v[208:211], v[122:125]
	v_mfma_f32_16x16x32_bf16 v[110:113], v[142:145], v[216:219], v[110:113]
	v_mfma_f32_16x16x32_bf16 v[106:109], v[166:169], v[216:219], v[106:109]
	v_mfma_f32_16x16x32_bf16 v[98:101], v[142:145], v[224:227], v[98:101]
	v_mfma_f32_16x16x32_bf16 v[90:93], v[166:169], v[224:227], v[90:93]
	v_mfma_f32_16x16x32_bf16 v[82:85], v[142:145], v[232:235], v[82:85]
	v_mfma_f32_16x16x32_bf16 v[74:77], v[166:169], v[232:235], v[74:77]
	v_mfma_f32_16x16x32_bf16 v[126:129], v[162:165], v[212:215], v[126:129]
	v_mfma_f32_16x16x32_bf16 v[122:125], v[170:173], v[212:215], v[122:125]
	v_mfma_f32_16x16x32_bf16 v[110:113], v[162:165], v[220:223], v[110:113]
	v_mfma_f32_16x16x32_bf16 v[106:109], v[170:173], v[220:223], v[106:109]
	v_mfma_f32_16x16x32_bf16 v[98:101], v[162:165], v[228:231], v[98:101]
	v_mfma_f32_16x16x32_bf16 v[90:93], v[170:173], v[228:231], v[90:93]
	v_mfma_f32_16x16x32_bf16 v[82:85], v[162:165], v[236:239], v[82:85]
	v_mfma_f32_16x16x32_bf16 v[74:77], v[170:173], v[236:239], v[74:77]
	s_setprio 0
	s_setprio 1
	v_mfma_f32_16x16x32_bf16 v[118:121], v[174:177], v[208:211], v[118:121]
	v_mfma_f32_16x16x32_bf16 v[114:117], v[184:187], v[208:211], v[114:117]
	v_mfma_f32_16x16x32_bf16 v[102:105], v[174:177], v[216:219], v[102:105]
	v_mfma_f32_16x16x32_bf16 v[94:97], v[184:187], v[216:219], v[94:97]
	v_mfma_f32_16x16x32_bf16 v[86:89], v[174:177], v[224:227], v[86:89]
	v_mfma_f32_16x16x32_bf16 v[78:81], v[184:187], v[224:227], v[78:81]
	v_mfma_f32_16x16x32_bf16 v[70:73], v[174:177], v[232:235], v[70:73]
	v_mfma_f32_16x16x32_bf16 v[66:69], v[184:187], v[232:235], v[66:69]
	v_mfma_f32_16x16x32_bf16 v[118:121], v[178:181], v[212:215], v[118:121]
	v_mfma_f32_16x16x32_bf16 v[114:117], v[188:191], v[212:215], v[114:117]
	v_mfma_f32_16x16x32_bf16 v[102:105], v[178:181], v[220:223], v[102:105]
	v_mfma_f32_16x16x32_bf16 v[94:97], v[188:191], v[220:223], v[94:97]
	v_mfma_f32_16x16x32_bf16 v[86:89], v[178:181], v[228:231], v[86:89]
	v_mfma_f32_16x16x32_bf16 v[78:81], v[188:191], v[228:231], v[78:81]
	v_mfma_f32_16x16x32_bf16 v[70:73], v[178:181], v[236:239], v[70:73]
	v_mfma_f32_16x16x32_bf16 v[66:69], v[188:191], v[236:239], v[66:69]
	s_setprio 0
	s_barrier
	s_add_i32 s47, s47, s30
	v_lshl_add_u64 v[192:193], s[20:21], 0, v[134:135]
	s_mov_b32 m0, s47
	ds_read_b128 v[208:211], v182 offset:16384
	ds_read_b128 v[212:215], v182 offset:17408
	ds_read_b128 v[216:219], v182 offset:18432
	ds_read_b128 v[220:223], v182 offset:19456
	ds_read_b128 v[224:227], v182 offset:20480
	ds_read_b128 v[228:231], v182 offset:21504
	ds_read_b128 v[232:235], v182 offset:22528
	ds_read_b128 v[236:239], v182 offset:23552
	global_load_lds_dwordx4 v[192:193], off
	s_add_i32 m0, s47, 0x2000
	s_add_u32 s48, s20, 0x80000
	v_lshl_add_u64 v[240:241], s[20:21], 0, v[130:131]
	s_addc_u32 s49, s21, 0
	s_add_i32 s47, s50, s30
	global_load_lds_dwordx4 v[240:241], off
	v_lshl_add_u64 v[242:243], s[48:49], 0, v[134:135]
	s_mov_b32 m0, s47
	v_lshl_add_u64 v[244:245], s[22:23], 0, v[132:133]
	global_load_lds_dwordx4 v[242:243], off
	v_lshl_add_u64 v[242:243], s[48:49], 0, v[130:131]
	s_add_i32 m0, s47, 0x2000
	s_nop 0
	global_load_lds_dwordx4 v[242:243], off
	v_lshl_add_u64 v[242:243], s[22:23], 0, v[136:137]
	s_mov_b32 m0, s31
	s_nop 0
	global_load_lds_dwordx4 v[242:243], off
	s_mov_b32 m0, s33
	s_nop 0
	global_load_lds_dwordx4 v[244:245], off
	s_nop 0
	s_nop 0
	s_nop 0
	s_waitcnt vmcnt(8)
	s_waitcnt lgkmcnt(0)
	s_barrier
; #define PG8_STAGE(bufoff, gbase, voff) do { _Pragma("unroll") for (int _i = 0; _i < 2; ++_i) \
;         __builtin_amdgcn_global_load_lds((const unsigned*)((const char*)(gbase) + (voff)[_i]), (LAS unsigned*)(lds + (bufoff) + ldsw + _i * 8192), 16, 0, 0); } while (0)
; #define PG8_LDA(dst, b, h) do { _Pragma("unroll") for (int m = 0; m < 4; ++m) _Pragma("unroll") for (int k = 0; k < 2; ++k) dst[m][k] = *(const LAS bf16x8*)(lds + PG8_SA(b, h) + aoff + m * 2048 + k * 1024); } while (0)
; #define PG8_LDB(dst, b, h) do { _Pragma("unroll") for (int n = 0; n < 2; ++n) _Pragma("unroll") for (int k = 0; k < 2; ++k) dst[n][k] = *(const LAS bf16x8*)(lds + PG8_SB(b, h) + boff + n * 2048 + k * 1024); } while (0)
; #define PG8_MMA(ai, bj, At, Bt) do { __builtin_amdgcn_s_setprio(1); _Pragma("unroll") for (int m = 0; m < 4; ++m) _Pragma("unroll") for (int n = 0; n < 2; ++n) _Pragma("unroll") for (int k = 0; k < 2; ++k) \
;         acc[ai][bj][m][n] = __builtin_amdgcn_mfma_f32_16x16x32_bf16(Bt[n][k], At[m][k], acc[ai][bj][m][n], 0, 0, 0); __builtin_amdgcn_s_setprio(0); } while (0)
; #define PG8_WAIT_V(n) asm volatile("s_waitcnt vmcnt(" #n ")" ::: "memory")
; #define PG8_WAIT_L(n) asm volatile("s_waitcnt lgkmcnt(" #n ")" ::: "memory")
; #define PG8_BAR __builtin_amdgcn_s_barrier()
; #define PG8_SCHED __builtin_amdgcn_sched_barrier(0)
; template <class Epi, class Sched>
; __device__ __forceinline__ void gemm_phase(LAS unsigned char* lds, const Gemm g, const Sched& S, const Epi& E) {
;     ...
;             PG8_WAIT_V(8); PG8_WAIT_L(0); PG8_BAR; PG8_MMA(1, 0, At, B0); PG8_MMA(1, 1, At, B1); PG8_BAR; PG8_SCHED;
;             PG8_LDB(B0, 1, 0); PG8_LDB(B1, 1, 1); PG8_SCHED; PG8_LDA(At, 1, 0); PG8_STAGE(PG8_SA(0, 1), a2 + hstepA, voffA);
;             PG8_WAIT_V(8); PG8_WAIT_L(0); PG8_BAR; PG8_MMA(0, 0, At, B0); PG8_MMA(0, 1, At, B1); PG8_BAR; PG8_SCHED;
	s_setprio 1
	s_waitcnt lgkmcnt(0)
	v_mfma_f32_16x16x32_bf16 v[62:65], v[142:145], v[208:211], v[62:65]
	v_mfma_f32_16x16x32_bf16 v[58:61], v[166:169], v[208:211], v[58:61]
	v_mfma_f32_16x16x32_bf16 v[50:53], v[142:145], v[216:219], v[50:53]
	v_mfma_f32_16x16x32_bf16 v[42:45], v[166:169], v[216:219], v[42:45]
	v_mfma_f32_16x16x32_bf16 v[34:37], v[142:145], v[224:227], v[34:37]
	v_mfma_f32_16x16x32_bf16 v[26:29], v[166:169], v[224:227], v[26:29]
	v_mfma_f32_16x16x32_bf16 v[18:21], v[142:145], v[232:235], v[18:21]
	v_mfma_f32_16x16x32_bf16 v[10:13], v[166:169], v[232:235], v[10:13]
	v_mfma_f32_16x16x32_bf16 v[62:65], v[162:165], v[212:215], v[62:65]
	v_mfma_f32_16x16x32_bf16 v[58:61], v[170:173], v[212:215], v[58:61]
	v_mfma_f32_16x16x32_bf16 v[50:53], v[162:165], v[220:223], v[50:53]
	v_mfma_f32_16x16x32_bf16 v[42:45], v[170:173], v[220:223], v[42:45]
	v_mfma_f32_16x16x32_bf16 v[34:37], v[162:165], v[228:231], v[34:37]
	v_mfma_f32_16x16x32_bf16 v[26:29], v[170:173], v[228:231], v[26:29]
	v_mfma_f32_16x16x32_bf16 v[18:21], v[162:165], v[236:239], v[18:21]
	v_mfma_f32_16x16x32_bf16 v[10:13], v[170:173], v[236:239], v[10:13]
	s_setprio 0
	s_setprio 1
	v_mfma_f32_16x16x32_bf16 v[54:57], v[174:177], v[208:211], v[54:57]
	v_mfma_f32_16x16x32_bf16 v[46:49], v[184:187], v[208:211], v[46:49]
	v_mfma_f32_16x16x32_bf16 v[38:41], v[174:177], v[216:219], v[38:41]
	v_mfma_f32_16x16x32_bf16 v[30:33], v[184:187], v[216:219], v[30:33]
	v_mfma_f32_16x16x32_bf16 v[22:25], v[174:177], v[224:227], v[22:25]
	v_mfma_f32_16x16x32_bf16 v[14:17], v[184:187], v[224:227], v[14:17]
	v_mfma_f32_16x16x32_bf16 v[6:9], v[174:177], v[232:235], v[6:9]
	v_mfma_f32_16x16x32_bf16 v[2:5], v[184:187], v[232:235], v[2:5]
	v_mfma_f32_16x16x32_bf16 v[54:57], v[178:181], v[212:215], v[54:57]
	v_mfma_f32_16x16x32_bf16 v[46:49], v[188:191], v[212:215], v[46:49]
	v_mfma_f32_16x16x32_bf16 v[38:41], v[178:181], v[220:223], v[38:41]
	v_mfma_f32_16x16x32_bf16 v[30:33], v[188:191], v[220:223], v[30:33]
	v_mfma_f32_16x16x32_bf16 v[22:25], v[178:181], v[228:231], v[22:25]
	v_mfma_f32_16x16x32_bf16 v[14:17], v[188:191], v[228:231], v[14:17]
	v_mfma_f32_16x16x32_bf16 v[6:9], v[178:181], v[236:239], v[6:9]
	v_mfma_f32_16x16x32_bf16 v[2:5], v[188:191], v[236:239], v[2:5]
	s_setprio 0
	s_barrier
	s_add_i32 s47, 0, 0x18000
	s_add_i32 s48, 0, 0x1c000
	v_add_u32_e32 v170, s47, v1
	v_add_u32_e32 v183, s48, v1
	ds_read_b128 v[142:145], v170
	ds_read_b128 v[162:165], v170 offset:1024
	ds_read_b128 v[166:169], v170 offset:2048
	ds_read_b128 v[170:173], v170 offset:3072
	ds_read_b128 v[174:177], v183
	ds_read_b128 v[178:181], v183 offset:1024
	ds_read_b128 v[184:187], v183 offset:2048
	ds_read_b128 v[188:191], v183 offset:3072
	s_add_u32 s22, s22, 0x80000
	s_addc_u32 s23, s23, 0
	s_mov_b32 m0, s34
	v_lshl_add_u64 v[246:247], s[22:23], 0, v[136:137]
	ds_read_b128 v[208:211], v182 offset:32768
	ds_read_b128 v[212:215], v182 offset:33792
	ds_read_b128 v[216:219], v182 offset:34816
	ds_read_b128 v[220:223], v182 offset:35840
	ds_read_b128 v[224:227], v182 offset:36864
	ds_read_b128 v[228:231], v182 offset:37888
	ds_read_b128 v[232:235], v182 offset:38912
	ds_read_b128 v[236:239], v182 offset:39936
	global_load_lds_dwordx4 v[246:247], off
	v_lshl_add_u64 v[246:247], s[22:23], 0, v[132:133]
	s_mov_b32 m0, s35
	s_nop 0
	global_load_lds_dwordx4 v[246:247], off
	s_nop 0
	s_nop 0
	s_nop 0
	s_waitcnt vmcnt(8)
	s_waitcnt lgkmcnt(0)
	s_barrier
	s_setprio 1
	s_waitcnt lgkmcnt(0)
	v_mfma_f32_16x16x32_bf16 v[126:129], v[142:145], v[208:211], v[126:129]
	v_mfma_f32_16x16x32_bf16 v[122:125], v[166:169], v[208:211], v[122:125]
	v_mfma_f32_16x16x32_bf16 v[110:113], v[142:145], v[216:219], v[110:113]
	v_mfma_f32_16x16x32_bf16 v[106:109], v[166:169], v[216:219], v[106:109]
	v_mfma_f32_16x16x32_bf16 v[98:101], v[142:145], v[224:227], v[98:101]
	v_mfma_f32_16x16x32_bf16 v[90:93], v[166:169], v[224:227], v[90:93]
	v_mfma_f32_16x16x32_bf16 v[82:85], v[142:145], v[232:235], v[82:85]
	v_mfma_f32_16x16x32_bf16 v[74:77], v[166:169], v[232:235], v[74:77]
	v_mfma_f32_16x16x32_bf16 v[126:129], v[162:165], v[212:215], v[126:129]
	v_mfma_f32_16x16x32_bf16 v[122:125], v[170:173], v[212:215], v[122:125]
	v_mfma_f32_16x16x32_bf16 v[110:113], v[162:165], v[220:223], v[110:113]
	v_mfma_f32_16x16x32_bf16 v[106:109], v[170:173], v[220:223], v[106:109]
	v_mfma_f32_16x16x32_bf16 v[98:101], v[162:165], v[228:231], v[98:101]
	v_mfma_f32_16x16x32_bf16 v[90:93], v[170:173], v[228:231], v[90:93]
	v_mfma_f32_16x16x32_bf16 v[82:85], v[162:165], v[236:239], v[82:85]
	v_mfma_f32_16x16x32_bf16 v[74:77], v[170:173], v[236:239], v[74:77]
	s_setprio 0
	s_setprio 1
	v_mfma_f32_16x16x32_bf16 v[118:121], v[174:177], v[208:211], v[118:121]
	v_mfma_f32_16x16x32_bf16 v[114:117], v[184:187], v[208:211], v[114:117]
	v_mfma_f32_16x16x32_bf16 v[102:105], v[174:177], v[216:219], v[102:105]
	v_mfma_f32_16x16x32_bf16 v[94:97], v[184:187], v[216:219], v[94:97]
	v_mfma_f32_16x16x32_bf16 v[86:89], v[174:177], v[224:227], v[86:89]
	v_mfma_f32_16x16x32_bf16 v[78:81], v[184:187], v[224:227], v[78:81]
	v_mfma_f32_16x16x32_bf16 v[70:73], v[174:177], v[232:235], v[70:73]
	v_mfma_f32_16x16x32_bf16 v[66:69], v[184:187], v[232:235], v[66:69]
	v_mfma_f32_16x16x32_bf16 v[118:121], v[178:181], v[212:215], v[118:121]
	v_mfma_f32_16x16x32_bf16 v[114:117], v[188:191], v[212:215], v[114:117]
	v_mfma_f32_16x16x32_bf16 v[102:105], v[178:181], v[220:223], v[102:105]
	v_mfma_f32_16x16x32_bf16 v[94:97], v[188:191], v[220:223], v[94:97]
	v_mfma_f32_16x16x32_bf16 v[86:89], v[178:181], v[228:231], v[86:89]
	v_mfma_f32_16x16x32_bf16 v[78:81], v[188:191], v[228:231], v[78:81]
	v_mfma_f32_16x16x32_bf16 v[70:73], v[178:181], v[236:239], v[70:73]
	v_mfma_f32_16x16x32_bf16 v[66:69], v[188:191], v[236:239], v[66:69]
	s_setprio 0
	s_barrier
; #define PG8_STAGE(bufoff, gbase, voff) do { _Pragma("unroll") for (int _i = 0; _i < 2; ++_i) \
;         __builtin_amdgcn_global_load_lds((const unsigned*)((const char*)(gbase) + (voff)[_i]), (LAS unsigned*)(lds + (bufoff) + ldsw + _i * 8192), 16, 0, 0); } while (0)
; #define PG8_LDA(dst, b, h) do { _Pragma("unroll") for (int m = 0; m < 4; ++m) _Pragma("unroll") for (int k = 0; k < 2; ++k) dst[m][k] = *(const LAS bf16x8*)(lds + PG8_SA(b, h) + aoff + m * 2048 + k * 1024); } while (0)
; #define PG8_MMA(ai, bj, At, Bt) do { __builtin_amdgcn_s_setprio(1); _Pragma("unroll") for (int m = 0; m < 4; ++m) _Pragma("unroll") for (int n = 0; n < 2; ++n) _Pragma("unroll") for (int k = 0; k < 2; ++k) \
;         acc[ai][bj][m][n] = __builtin_amdgcn_mfma_f32_16x16x32_bf16(Bt[n][k], At[m][k], acc[ai][bj][m][n], 0, 0, 0); __builtin_amdgcn_s_setprio(0); } while (0)
; #define PG8_WAIT_V(n) asm volatile("s_waitcnt vmcnt(" #n ")" ::: "memory")
; #define PG8_WAIT_L(n) asm volatile("s_waitcnt lgkmcnt(" #n ")" ::: "memory")
; #define PG8_BAR __builtin_amdgcn_s_barrier()
; #define PG8_SCHED __builtin_amdgcn_sched_barrier(0)
; template <class Epi, class Sched>
; __device__ __forceinline__ void gemm_phase(LAS unsigned char* lds, const Gemm g, const Sched& S, const Epi& E) {
;     ...
;             PG8_LDA(At, 1, 1); PG8_STAGE(PG8_SB(1, 0), b3, voffB); PG8_STAGE(PG8_SB(1, 1), b3 + hstepB, voffB); PG8_STAGE(PG8_SA(1, 0), a3, voffA);
;             PG8_WAIT_V(8); PG8_WAIT_L(0); PG8_BAR; PG8_MMA(1, 0, At, B0); PG8_MMA(1, 1, At, B1); PG8_BAR; PG8_SCHED;
;         }
;         if (wr == 0) PG8_BAR;
	s_add_i32 s22, s47, s30
	v_lshl_add_u64 v[192:193], v[192:193], 0, s[56:57]
	s_mov_b32 m0, s22
	ds_read_b128 v[208:211], v182 offset:49152
	ds_read_b128 v[212:215], v182 offset:50176
	ds_read_b128 v[216:219], v182 offset:51200
	ds_read_b128 v[220:223], v182 offset:52224
	ds_read_b128 v[224:227], v182 offset:53248
	ds_read_b128 v[228:231], v182 offset:54272
	ds_read_b128 v[232:235], v182 offset:55296
	ds_read_b128 v[236:239], v182 offset:56320
	global_load_lds_dwordx4 v[192:193], off
	s_add_i32 m0, s22, 0x2000
	s_add_u32 s20, s20, 0x80080
	v_lshl_add_u64 v[192:193], v[240:241], 0, s[56:57]
	s_addc_u32 s21, s21, 0
	s_add_i32 s22, s48, s30
	global_load_lds_dwordx4 v[192:193], off
	v_lshl_add_u64 v[192:193], s[20:21], 0, v[134:135]
	s_mov_b32 m0, s22
	s_nop 0
	global_load_lds_dwordx4 v[192:193], off
	v_lshl_add_u64 v[192:193], s[20:21], 0, v[130:131]
	s_add_i32 m0, s22, 0x2000
	s_nop 0
	global_load_lds_dwordx4 v[192:193], off
	v_lshl_add_u64 v[192:193], v[242:243], 0, s[56:57]
	s_mov_b32 m0, s40
	s_nop 0
	global_load_lds_dwordx4 v[192:193], off
	v_lshl_add_u64 v[192:193], v[244:245], 0, s[56:57]
	s_mov_b32 m0, s41
	s_nop 0
	global_load_lds_dwordx4 v[192:193], off
	s_nop 0
	s_nop 0
	s_waitcnt vmcnt(8)
	s_waitcnt lgkmcnt(0)
	s_barrier
	s_setprio 1
	s_waitcnt lgkmcnt(0)
	v_mfma_f32_16x16x32_bf16 v[62:65], v[142:145], v[208:211], v[62:65]
	v_mfma_f32_16x16x32_bf16 v[58:61], v[166:169], v[208:211], v[58:61]
	v_mfma_f32_16x16x32_bf16 v[50:53], v[142:145], v[216:219], v[50:53]
	v_mfma_f32_16x16x32_bf16 v[42:45], v[166:169], v[216:219], v[42:45]
	v_mfma_f32_16x16x32_bf16 v[34:37], v[142:145], v[224:227], v[34:37]
	v_mfma_f32_16x16x32_bf16 v[26:29], v[166:169], v[224:227], v[26:29]
	v_mfma_f32_16x16x32_bf16 v[18:21], v[142:145], v[232:235], v[18:21]
	v_mfma_f32_16x16x32_bf16 v[10:13], v[166:169], v[232:235], v[10:13]
	v_mfma_f32_16x16x32_bf16 v[62:65], v[162:165], v[212:215], v[62:65]
	v_mfma_f32_16x16x32_bf16 v[58:61], v[170:173], v[212:215], v[58:61]
	v_mfma_f32_16x16x32_bf16 v[50:53], v[162:165], v[220:223], v[50:53]
	v_mfma_f32_16x16x32_bf16 v[42:45], v[170:173], v[220:223], v[42:45]
	v_mfma_f32_16x16x32_bf16 v[34:37], v[162:165], v[228:231], v[34:37]
	v_mfma_f32_16x16x32_bf16 v[26:29], v[170:173], v[228:231], v[26:29]
	v_mfma_f32_16x16x32_bf16 v[18:21], v[162:165], v[236:239], v[18:21]
	v_mfma_f32_16x16x32_bf16 v[10:13], v[170:173], v[236:239], v[10:13]
	s_setprio 0
	s_setprio 1
	v_mfma_f32_16x16x32_bf16 v[54:57], v[174:177], v[208:211], v[54:57]
	v_mfma_f32_16x16x32_bf16 v[46:49], v[184:187], v[208:211], v[46:49]
	v_mfma_f32_16x16x32_bf16 v[38:41], v[174:177], v[216:219], v[38:41]
	v_mfma_f32_16x16x32_bf16 v[30:33], v[184:187], v[216:219], v[30:33]
	v_mfma_f32_16x16x32_bf16 v[22:25], v[174:177], v[224:227], v[22:25]
	v_mfma_f32_16x16x32_bf16 v[14:17], v[184:187], v[224:227], v[14:17]
	v_mfma_f32_16x16x32_bf16 v[6:9], v[174:177], v[232:235], v[6:9]
	v_mfma_f32_16x16x32_bf16 v[2:5], v[184:187], v[232:235], v[2:5]
	v_mfma_f32_16x16x32_bf16 v[54:57], v[178:181], v[212:215], v[54:57]
	v_mfma_f32_16x16x32_bf16 v[46:49], v[188:191], v[212:215], v[46:49]
	v_mfma_f32_16x16x32_bf16 v[38:41], v[178:181], v[220:223], v[38:41]
	v_mfma_f32_16x16x32_bf16 v[30:33], v[188:191], v[220:223], v[30:33]
	v_mfma_f32_16x16x32_bf16 v[22:25], v[178:181], v[228:231], v[22:25]
	v_mfma_f32_16x16x32_bf16 v[14:17], v[188:191], v[228:231], v[14:17]
	v_mfma_f32_16x16x32_bf16 v[6:9], v[178:181], v[236:239], v[6:9]
	v_mfma_f32_16x16x32_bf16 v[2:5], v[188:191], v[236:239], v[2:5]
	s_setprio 0
	s_barrier
	s_add_i32 s46, s46, 2
	s_add_u32 s18, s18, 0x100
	s_addc_u32 s19, s19, 0
	s_add_u32 s25, s25, 0x100
	s_addc_u32 s45, s45, 0
	s_cmp_gt_u32 s46, 29
	s_cbranch_scc0 .LBB0_3415
	s_and_b64 vcc, exec, s[4:5]
	s_cbranch_vccz .LBB0_3418
	s_barrier

; #define PG8_STAGE(bufoff, gbase, voff) do { _Pragma("unroll") for (int _i = 0; _i < 2; ++_i) \
;         __builtin_amdgcn_global_load_lds((const unsigned*)((const char*)(gbase) + (voff)[_i]), (LAS unsigned*)(lds + (bufoff) + ldsw + _i * 8192), 16, 0, 0); } while (0)
; #define PG8_LDA(dst, b, h) do { _Pragma("unroll") for (int m = 0; m < 4; ++m) _Pragma("unroll") for (int k = 0; k < 2; ++k) dst[m][k] = *(const LAS bf16x8*)(lds + PG8_SA(b, h) + aoff + m * 2048 + k * 1024); } while (0)
; #define PG8_LDB(dst, b, h) do { _Pragma("unroll") for (int n = 0; n < 2; ++n) _Pragma("unroll") for (int k = 0; k < 2; ++k) dst[n][k] = *(const LAS bf16x8*)(lds + PG8_SB(b, h) + boff + n * 2048 + k * 1024); } while (0)
; #define PG8_MMA(ai, bj, At, Bt) do { __builtin_amdgcn_s_setprio(1); _Pragma("unroll") for (int m = 0; m < 4; ++m) _Pragma("unroll") for (int n = 0; n < 2; ++n) _Pragma("unroll") for (int k = 0; k < 2; ++k) \
;         acc[ai][bj][m][n] = __builtin_amdgcn_mfma_f32_16x16x32_bf16(Bt[n][k], At[m][k], acc[ai][bj][m][n], 0, 0, 0); __builtin_amdgcn_s_setprio(0); } while (0)
; #define PG8_WAIT_V(n) asm volatile("s_waitcnt vmcnt(" #n ")" ::: "memory")
; #define PG8_WAIT_L(n) asm volatile("s_waitcnt lgkmcnt(" #n ")" ::: "memory")
; #define PG8_BAR __builtin_amdgcn_s_barrier()
; #define PG8_SCHED __builtin_amdgcn_sched_barrier(0)
; template <class Epi, class Sched>
; __device__ __forceinline__ void gemm_phase(LAS unsigned char* lds, const Gemm g, const Sched& S, const Epi& E) {
;     ...
;         for (int t = 0; t < nt; t += 2) {
;             const bool last = (t == nt - 2);
;             const char* a1 = cA + (size_t)(t + 1) * kstep;
;             const char* a2 = last ? nA : cA + (size_t)(t + 2) * kstep; const char* b2 = last ? nB : cB + (size_t)(t + 2) * kstep;
;             const char* a3 = a2 + kstep; const char* b3 = b2 + kstep;
;             PG8_LDB(B0, 0, 0); PG8_LDB(B1, 0, 1); PG8_SCHED; PG8_LDA(At, 0, 0); PG8_STAGE(PG8_SA(1, 1), a1 + hstepA, voffA);
;             PG8_WAIT_V(8); PG8_WAIT_L(0); PG8_BAR; PG8_MMA(0, 0, At, B0); PG8_MMA(0, 1, At, B1); PG8_BAR; PG8_SCHED;
;             PG8_LDA(At, 0, 1); PG8_STAGE(PG8_SB(0, 0), b2, voffB); PG8_STAGE(PG8_SB(0, 1), b2 + hstepB, voffB); PG8_STAGE(PG8_SA(0, 0), a2, voffA);
.LBB0_3449:
	s_add_u32 s18, s16, 0xfff80080
	s_addc_u32 s19, s17, -1
	s_add_i32 s46, 0, 0x10000
	s_cmp_eq_u32 s45, 28
	s_cselect_b32 s21, s11, s19
	s_cselect_b32 s20, s41, s18
	v_add_u32_e32 v167, s46, v1
	s_cselect_b32 s19, s9, s44
	s_cselect_b32 s18, s42, s43
	s_add_i32 s48, 0, 0x14000
	s_waitcnt lgkmcnt(0)
	ds_read_b128 v[142:145], v167
	ds_read_b128 v[162:165], v167 offset:1024
	ds_read_b128 v[168:171], v167 offset:2048
	ds_read_b128 v[172:175], v167 offset:3072
	v_add_u32_e32 v167, s48, v1
	ds_read_b128 v[176:179], v167
	ds_read_b128 v[180:183], v167 offset:1024
	ds_read_b128 v[184:187], v167 offset:2048
	ds_read_b128 v[188:191], v167 offset:3072
	v_lshl_add_u64 v[192:193], s[16:17], 0, v[138:139]
	s_add_i32 m0, s27, 0xc000
	ds_read_b128 v[208:211], v166
	ds_read_b128 v[212:215], v166 offset:1024
	ds_read_b128 v[216:219], v166 offset:2048
	ds_read_b128 v[220:223], v166 offset:3072
	ds_read_b128 v[224:227], v166 offset:4096
	ds_read_b128 v[228:231], v166 offset:5120
	ds_read_b128 v[232:235], v166 offset:6144
	ds_read_b128 v[236:239], v166 offset:7168
	global_load_lds_dwordx4 v[192:193], off
	v_lshl_add_u64 v[192:193], s[16:17], 0, v[140:141]
	s_add_i32 m0, s27, 0xe000
	s_nop 0
	global_load_lds_dwordx4 v[192:193], off
	s_nop 0
	s_nop 0
	s_nop 0
	s_waitcnt vmcnt(8)
	s_waitcnt lgkmcnt(0)
	s_barrier
	s_setprio 1
	s_waitcnt lgkmcnt(0)
	v_mfma_f32_16x16x32_bf16 v[126:129], v[142:145], v[208:211], v[126:129]
	v_mfma_f32_16x16x32_bf16 v[122:125], v[168:171], v[208:211], v[122:125]
	v_mfma_f32_16x16x32_bf16 v[114:117], v[142:145], v[216:219], v[114:117]
	v_mfma_f32_16x16x32_bf16 v[106:109], v[168:171], v[216:219], v[106:109]
	v_mfma_f32_16x16x32_bf16 v[98:101], v[142:145], v[224:227], v[98:101]
	v_mfma_f32_16x16x32_bf16 v[90:93], v[168:171], v[224:227], v[90:93]
	v_mfma_f32_16x16x32_bf16 v[82:85], v[142:145], v[232:235], v[82:85]
	v_mfma_f32_16x16x32_bf16 v[74:77], v[168:171], v[232:235], v[74:77]
	v_mfma_f32_16x16x32_bf16 v[126:129], v[162:165], v[212:215], v[126:129]
	v_mfma_f32_16x16x32_bf16 v[122:125], v[172:175], v[212:215], v[122:125]
	v_mfma_f32_16x16x32_bf16 v[114:117], v[162:165], v[220:223], v[114:117]
	v_mfma_f32_16x16x32_bf16 v[106:109], v[172:175], v[220:223], v[106:109]
	v_mfma_f32_16x16x32_bf16 v[98:101], v[162:165], v[228:231], v[98:101]
	v_mfma_f32_16x16x32_bf16 v[90:93], v[172:175], v[228:231], v[90:93]
	v_mfma_f32_16x16x32_bf16 v[82:85], v[162:165], v[236:239], v[82:85]
	v_mfma_f32_16x16x32_bf16 v[74:77], v[172:175], v[236:239], v[74:77]
	s_setprio 0
	s_setprio 1
	v_mfma_f32_16x16x32_bf16 v[118:121], v[176:179], v[208:211], v[118:121]
	v_mfma_f32_16x16x32_bf16 v[110:113], v[184:187], v[208:211], v[110:113]
	v_mfma_f32_16x16x32_bf16 v[102:105], v[176:179], v[216:219], v[102:105]
	v_mfma_f32_16x16x32_bf16 v[94:97], v[184:187], v[216:219], v[94:97]
	v_mfma_f32_16x16x32_bf16 v[86:89], v[176:179], v[224:227], v[86:89]
	v_mfma_f32_16x16x32_bf16 v[78:81], v[184:187], v[224:227], v[78:81]
	v_mfma_f32_16x16x32_bf16 v[70:73], v[176:179], v[232:235], v[70:73]
	v_mfma_f32_16x16x32_bf16 v[66:69], v[184:187], v[232:235], v[66:69]
	v_mfma_f32_16x16x32_bf16 v[118:121], v[180:183], v[212:215], v[118:121]
	v_mfma_f32_16x16x32_bf16 v[110:113], v[188:191], v[212:215], v[110:113]
	v_mfma_f32_16x16x32_bf16 v[102:105], v[180:183], v[220:223], v[102:105]
	v_mfma_f32_16x16x32_bf16 v[94:97], v[188:191], v[220:223], v[94:97]
	v_mfma_f32_16x16x32_bf16 v[86:89], v[180:183], v[228:231], v[86:89]
	v_mfma_f32_16x16x32_bf16 v[78:81], v[188:191], v[228:231], v[78:81]
	v_mfma_f32_16x16x32_bf16 v[70:73], v[180:183], v[236:239], v[70:73]
	v_mfma_f32_16x16x32_bf16 v[66:69], v[188:191], v[236:239], v[66:69]
	s_setprio 0
	s_barrier
	s_add_i32 s46, s46, s26
	v_lshl_add_u64 v[192:193], s[18:19], 0, v[134:135]
	s_mov_b32 m0, s46
	ds_read_b128 v[208:211], v166 offset:16384
	ds_read_b128 v[212:215], v166 offset:17408
	ds_read_b128 v[216:219], v166 offset:18432
	ds_read_b128 v[220:223], v166 offset:19456
	ds_read_b128 v[224:227], v166 offset:20480
	ds_read_b128 v[228:231], v166 offset:21504
	ds_read_b128 v[232:235], v166 offset:22528
	ds_read_b128 v[236:239], v166 offset:23552
	global_load_lds_dwordx4 v[192:193], off
	s_add_i32 m0, s46, 0x2000
	s_add_u32 s46, s18, 0x80000
	v_lshl_add_u64 v[240:241], s[18:19], 0, v[130:131]
	s_addc_u32 s47, s19, 0
	s_add_i32 s48, s48, s26
	global_load_lds_dwordx4 v[240:241], off
	v_lshl_add_u64 v[242:243], s[46:47], 0, v[134:135]
	s_mov_b32 m0, s48
	v_lshl_add_u64 v[244:245], s[20:21], 0, v[132:133]
	global_load_lds_dwordx4 v[242:243], off
	v_lshl_add_u64 v[242:243], s[46:47], 0, v[130:131]
	s_add_i32 m0, s48, 0x2000
	s_nop 0
	global_load_lds_dwordx4 v[242:243], off
	v_lshl_add_u64 v[242:243], s[20:21], 0, v[136:137]
	s_mov_b32 m0, s27
	s_nop 0
	global_load_lds_dwordx4 v[242:243], off
	s_mov_b32 m0, s28
	s_nop 0
	global_load_lds_dwordx4 v[244:245], off
	s_nop 0
	s_nop 0
	s_nop 0
	s_waitcnt vmcnt(8)
	s_waitcnt lgkmcnt(0)
	s_barrier
; #define PG8_STAGE(bufoff, gbase, voff) do { _Pragma("unroll") for (int _i = 0; _i < 2; ++_i) \
;         __builtin_amdgcn_global_load_lds((const unsigned*)((const char*)(gbase) + (voff)[_i]), (LAS unsigned*)(lds + (bufoff) + ldsw + _i * 8192), 16, 0, 0); } while (0)
; #define PG8_LDA(dst, b, h) do { _Pragma("unroll") for (int m = 0; m < 4; ++m) _Pragma("unroll") for (int k = 0; k < 2; ++k) dst[m][k] = *(const LAS bf16x8*)(lds + PG8_SA(b, h) + aoff + m * 2048 + k * 1024); } while (0)
; #define PG8_LDB(dst, b, h) do { _Pragma("unroll") for (int n = 0; n < 2; ++n) _Pragma("unroll") for (int k = 0; k < 2; ++k) dst[n][k] = *(const LAS bf16x8*)(lds + PG8_SB(b, h) + boff + n * 2048 + k * 1024); } while (0)
; #define PG8_MMA(ai, bj, At, Bt) do { __builtin_amdgcn_s_setprio(1); _Pragma("unroll") for (int m = 0; m < 4; ++m) _Pragma("unroll") for (int n = 0; n < 2; ++n) _Pragma("unroll") for (int k = 0; k < 2; ++k) \
;         acc[ai][bj][m][n] = __builtin_amdgcn_mfma_f32_16x16x32_bf16(Bt[n][k], At[m][k], acc[ai][bj][m][n], 0, 0, 0); __builtin_amdgcn_s_setprio(0); } while (0)
; #define PG8_WAIT_V(n) asm volatile("s_waitcnt vmcnt(" #n ")" ::: "memory")
; #define PG8_WAIT_L(n) asm volatile("s_waitcnt lgkmcnt(" #n ")" ::: "memory")
; #define PG8_BAR __builtin_amdgcn_s_barrier()
; #define PG8_SCHED __builtin_amdgcn_sched_barrier(0)
; template <class Epi, class Sched>
; __device__ __forceinline__ void gemm_phase(LAS unsigned char* lds, const Gemm g, const Sched& S, const Epi& E) {
;     ...
;             PG8_WAIT_V(8); PG8_WAIT_L(0); PG8_BAR; PG8_MMA(1, 0, At, B0); PG8_MMA(1, 1, At, B1); PG8_BAR; PG8_SCHED;
;             PG8_LDB(B0, 1, 0); PG8_LDB(B1, 1, 1); PG8_SCHED; PG8_LDA(At, 1, 0); PG8_STAGE(PG8_SA(0, 1), a2 + hstepA, voffA);
;             PG8_WAIT_V(8); PG8_WAIT_L(0); PG8_BAR; PG8_MMA(0, 0, At, B0); PG8_MMA(0, 1, At, B1); PG8_BAR; PG8_SCHED;
	s_setprio 1
	s_waitcnt lgkmcnt(0)
	v_mfma_f32_16x16x32_bf16 v[62:65], v[142:145], v[208:211], v[62:65]
	v_mfma_f32_16x16x32_bf16 v[58:61], v[168:171], v[208:211], v[58:61]
	v_mfma_f32_16x16x32_bf16 v[50:53], v[142:145], v[216:219], v[50:53]
	v_mfma_f32_16x16x32_bf16 v[42:45], v[168:171], v[216:219], v[42:45]
	v_mfma_f32_16x16x32_bf16 v[34:37], v[142:145], v[224:227], v[34:37]
	v_mfma_f32_16x16x32_bf16 v[26:29], v[168:171], v[224:227], v[26:29]
	v_mfma_f32_16x16x32_bf16 v[18:21], v[142:145], v[232:235], v[18:21]
	v_mfma_f32_16x16x32_bf16 v[10:13], v[168:171], v[232:235], v[10:13]
	v_mfma_f32_16x16x32_bf16 v[62:65], v[162:165], v[212:215], v[62:65]
	v_mfma_f32_16x16x32_bf16 v[58:61], v[172:175], v[212:215], v[58:61]
	v_mfma_f32_16x16x32_bf16 v[50:53], v[162:165], v[220:223], v[50:53]
	v_mfma_f32_16x16x32_bf16 v[42:45], v[172:175], v[220:223], v[42:45]
	v_mfma_f32_16x16x32_bf16 v[34:37], v[162:165], v[228:231], v[34:37]
	v_mfma_f32_16x16x32_bf16 v[26:29], v[172:175], v[228:231], v[26:29]
	v_mfma_f32_16x16x32_bf16 v[18:21], v[162:165], v[236:239], v[18:21]
	v_mfma_f32_16x16x32_bf16 v[10:13], v[172:175], v[236:239], v[10:13]
	s_setprio 0
	s_setprio 1
	v_mfma_f32_16x16x32_bf16 v[54:57], v[176:179], v[208:211], v[54:57]
	v_mfma_f32_16x16x32_bf16 v[46:49], v[184:187], v[208:211], v[46:49]
	v_mfma_f32_16x16x32_bf16 v[38:41], v[176:179], v[216:219], v[38:41]
	v_mfma_f32_16x16x32_bf16 v[30:33], v[184:187], v[216:219], v[30:33]
	v_mfma_f32_16x16x32_bf16 v[22:25], v[176:179], v[224:227], v[22:25]
	v_mfma_f32_16x16x32_bf16 v[14:17], v[184:187], v[224:227], v[14:17]
	v_mfma_f32_16x16x32_bf16 v[6:9], v[176:179], v[232:235], v[6:9]
	v_mfma_f32_16x16x32_bf16 v[2:5], v[184:187], v[232:235], v[2:5]
	v_mfma_f32_16x16x32_bf16 v[54:57], v[180:183], v[212:215], v[54:57]
	v_mfma_f32_16x16x32_bf16 v[46:49], v[188:191], v[212:215], v[46:49]
	v_mfma_f32_16x16x32_bf16 v[38:41], v[180:183], v[220:223], v[38:41]
	v_mfma_f32_16x16x32_bf16 v[30:33], v[188:191], v[220:223], v[30:33]
	v_mfma_f32_16x16x32_bf16 v[22:25], v[180:183], v[228:231], v[22:25]
	v_mfma_f32_16x16x32_bf16 v[14:17], v[188:191], v[228:231], v[14:17]
	v_mfma_f32_16x16x32_bf16 v[6:9], v[180:183], v[236:239], v[6:9]
	v_mfma_f32_16x16x32_bf16 v[2:5], v[188:191], v[236:239], v[2:5]
	s_setprio 0
	s_barrier
	s_add_i32 s46, 0, 0x18000
	v_add_u32_e32 v167, s46, v1
	s_add_i32 s47, 0, 0x1c000
	ds_read_b128 v[142:145], v167
	ds_read_b128 v[162:165], v167 offset:1024
	ds_read_b128 v[168:171], v167 offset:2048
	ds_read_b128 v[172:175], v167 offset:3072
	v_add_u32_e32 v167, s47, v1
	ds_read_b128 v[176:179], v167
	ds_read_b128 v[180:183], v167 offset:1024
	ds_read_b128 v[184:187], v167 offset:2048
	ds_read_b128 v[188:191], v167 offset:3072
	s_add_u32 s20, s20, 0x80000
	s_addc_u32 s21, s21, 0
	s_mov_b32 m0, s29
	v_lshl_add_u64 v[246:247], s[20:21], 0, v[136:137]
	ds_read_b128 v[208:211], v166 offset:32768
	ds_read_b128 v[212:215], v166 offset:33792
	ds_read_b128 v[216:219], v166 offset:34816
	ds_read_b128 v[220:223], v166 offset:35840
	ds_read_b128 v[224:227], v166 offset:36864
	ds_read_b128 v[228:231], v166 offset:37888
	ds_read_b128 v[232:235], v166 offset:38912
	ds_read_b128 v[236:239], v166 offset:39936
	global_load_lds_dwordx4 v[246:247], off
	v_lshl_add_u64 v[246:247], s[20:21], 0, v[132:133]
	s_mov_b32 m0, s30
	s_nop 0
	global_load_lds_dwordx4 v[246:247], off
	s_nop 0
	s_nop 0
	s_nop 0
	s_waitcnt vmcnt(8)
	s_waitcnt lgkmcnt(0)
	s_barrier
	s_setprio 1
	s_waitcnt lgkmcnt(0)
	v_mfma_f32_16x16x32_bf16 v[126:129], v[142:145], v[208:211], v[126:129]
	v_mfma_f32_16x16x32_bf16 v[122:125], v[168:171], v[208:211], v[122:125]
	v_mfma_f32_16x16x32_bf16 v[114:117], v[142:145], v[216:219], v[114:117]
	v_mfma_f32_16x16x32_bf16 v[106:109], v[168:171], v[216:219], v[106:109]
	v_mfma_f32_16x16x32_bf16 v[98:101], v[142:145], v[224:227], v[98:101]
	v_mfma_f32_16x16x32_bf16 v[90:93], v[168:171], v[224:227], v[90:93]
	v_mfma_f32_16x16x32_bf16 v[82:85], v[142:145], v[232:235], v[82:85]
	v_mfma_f32_16x16x32_bf16 v[74:77], v[168:171], v[232:235], v[74:77]
	v_mfma_f32_16x16x32_bf16 v[126:129], v[162:165], v[212:215], v[126:129]
	v_mfma_f32_16x16x32_bf16 v[122:125], v[172:175], v[212:215], v[122:125]
	v_mfma_f32_16x16x32_bf16 v[114:117], v[162:165], v[220:223], v[114:117]
	v_mfma_f32_16x16x32_bf16 v[106:109], v[172:175], v[220:223], v[106:109]
	v_mfma_f32_16x16x32_bf16 v[98:101], v[162:165], v[228:231], v[98:101]
	v_mfma_f32_16x16x32_bf16 v[90:93], v[172:175], v[228:231], v[90:93]
	v_mfma_f32_16x16x32_bf16 v[82:85], v[162:165], v[236:239], v[82:85]
	v_mfma_f32_16x16x32_bf16 v[74:77], v[172:175], v[236:239], v[74:77]
	s_setprio 0
	s_setprio 1
	v_mfma_f32_16x16x32_bf16 v[118:121], v[176:179], v[208:211], v[118:121]
	v_mfma_f32_16x16x32_bf16 v[110:113], v[184:187], v[208:211], v[110:113]
	v_mfma_f32_16x16x32_bf16 v[102:105], v[176:179], v[216:219], v[102:105]
	v_mfma_f32_16x16x32_bf16 v[94:97], v[184:187], v[216:219], v[94:97]
	v_mfma_f32_16x16x32_bf16 v[86:89], v[176:179], v[224:227], v[86:89]
	v_mfma_f32_16x16x32_bf16 v[78:81], v[184:187], v[224:227], v[78:81]
	v_mfma_f32_16x16x32_bf16 v[70:73], v[176:179], v[232:235], v[70:73]
	v_mfma_f32_16x16x32_bf16 v[66:69], v[184:187], v[232:235], v[66:69]
	v_mfma_f32_16x16x32_bf16 v[118:121], v[180:183], v[212:215], v[118:121]
	v_mfma_f32_16x16x32_bf16 v[110:113], v[188:191], v[212:215], v[110:113]
	v_mfma_f32_16x16x32_bf16 v[102:105], v[180:183], v[220:223], v[102:105]
	v_mfma_f32_16x16x32_bf16 v[94:97], v[188:191], v[220:223], v[94:97]
	v_mfma_f32_16x16x32_bf16 v[86:89], v[180:183], v[228:231], v[86:89]
	v_mfma_f32_16x16x32_bf16 v[78:81], v[188:191], v[228:231], v[78:81]
	v_mfma_f32_16x16x32_bf16 v[70:73], v[180:183], v[236:239], v[70:73]
	v_mfma_f32_16x16x32_bf16 v[66:69], v[188:191], v[236:239], v[66:69]
	s_setprio 0
	s_barrier
; #define PG8_STAGE(bufoff, gbase, voff) do { _Pragma("unroll") for (int _i = 0; _i < 2; ++_i) \
;         __builtin_amdgcn_global_load_lds((const unsigned*)((const char*)(gbase) + (voff)[_i]), (LAS unsigned*)(lds + (bufoff) + ldsw + _i * 8192), 16, 0, 0); } while (0)
; #define PG8_LDA(dst, b, h) do { _Pragma("unroll") for (int m = 0; m < 4; ++m) _Pragma("unroll") for (int k = 0; k < 2; ++k) dst[m][k] = *(const LAS bf16x8*)(lds + PG8_SA(b, h) + aoff + m * 2048 + k * 1024); } while (0)
; #define PG8_MMA(ai, bj, At, Bt) do { __builtin_amdgcn_s_setprio(1); _Pragma("unroll") for (int m = 0; m < 4; ++m) _Pragma("unroll") for (int n = 0; n < 2; ++n) _Pragma("unroll") for (int k = 0; k < 2; ++k) \
;         acc[ai][bj][m][n] = __builtin_amdgcn_mfma_f32_16x16x32_bf16(Bt[n][k], At[m][k], acc[ai][bj][m][n], 0, 0, 0); __builtin_amdgcn_s_setprio(0); } while (0)
; #define PG8_WAIT_V(n) asm volatile("s_waitcnt vmcnt(" #n ")" ::: "memory")
; #define PG8_WAIT_L(n) asm volatile("s_waitcnt lgkmcnt(" #n ")" ::: "memory")
; #define PG8_BAR __builtin_amdgcn_s_barrier()
; #define PG8_SCHED __builtin_amdgcn_sched_barrier(0)
; template <class Epi, class Sched>
; __device__ __forceinline__ void gemm_phase(LAS unsigned char* lds, const Gemm g, const Sched& S, const Epi& E) {
;     ...
;             PG8_LDA(At, 1, 1); PG8_STAGE(PG8_SB(1, 0), b3, voffB); PG8_STAGE(PG8_SB(1, 1), b3 + hstepB, voffB); PG8_STAGE(PG8_SA(1, 0), a3, voffA);
;             PG8_WAIT_V(8); PG8_WAIT_L(0); PG8_BAR; PG8_MMA(1, 0, At, B0); PG8_MMA(1, 1, At, B1); PG8_BAR; PG8_SCHED;
;         }
;         if (wr == 0) PG8_BAR;
	s_add_i32 s20, s46, s26
	v_lshl_add_u64 v[192:193], v[192:193], 0, s[56:57]
	s_mov_b32 m0, s20
	ds_read_b128 v[208:211], v166 offset:49152
	ds_read_b128 v[212:215], v166 offset:50176
	ds_read_b128 v[216:219], v166 offset:51200
	ds_read_b128 v[220:223], v166 offset:52224
	ds_read_b128 v[224:227], v166 offset:53248
	ds_read_b128 v[228:231], v166 offset:54272
	ds_read_b128 v[232:235], v166 offset:55296
	ds_read_b128 v[236:239], v166 offset:56320
	global_load_lds_dwordx4 v[192:193], off
	s_add_i32 m0, s20, 0x2000
	s_add_u32 s18, s18, 0x80080
	v_lshl_add_u64 v[192:193], v[240:241], 0, s[56:57]
	s_addc_u32 s19, s19, 0
	s_add_i32 s20, s47, s26
	global_load_lds_dwordx4 v[192:193], off
	v_lshl_add_u64 v[192:193], s[18:19], 0, v[134:135]
	s_mov_b32 m0, s20
	s_nop 0
	global_load_lds_dwordx4 v[192:193], off
	v_lshl_add_u64 v[192:193], s[18:19], 0, v[130:131]
	s_add_i32 m0, s20, 0x2000
	s_nop 0
	global_load_lds_dwordx4 v[192:193], off
	v_lshl_add_u64 v[192:193], v[242:243], 0, s[56:57]
	s_mov_b32 m0, s34
	s_nop 0
	global_load_lds_dwordx4 v[192:193], off
	v_lshl_add_u64 v[192:193], v[244:245], 0, s[56:57]
	s_mov_b32 m0, s35
	s_nop 0
	global_load_lds_dwordx4 v[192:193], off
	s_nop 0
	s_nop 0
	s_waitcnt vmcnt(8)
	s_waitcnt lgkmcnt(0)
	s_barrier
	s_setprio 1
	s_waitcnt lgkmcnt(0)
	v_mfma_f32_16x16x32_bf16 v[62:65], v[142:145], v[208:211], v[62:65]
	v_mfma_f32_16x16x32_bf16 v[58:61], v[168:171], v[208:211], v[58:61]
	v_mfma_f32_16x16x32_bf16 v[50:53], v[142:145], v[216:219], v[50:53]
	v_mfma_f32_16x16x32_bf16 v[42:45], v[168:171], v[216:219], v[42:45]
	v_mfma_f32_16x16x32_bf16 v[34:37], v[142:145], v[224:227], v[34:37]
	v_mfma_f32_16x16x32_bf16 v[26:29], v[168:171], v[224:227], v[26:29]
	v_mfma_f32_16x16x32_bf16 v[18:21], v[142:145], v[232:235], v[18:21]
	v_mfma_f32_16x16x32_bf16 v[10:13], v[168:171], v[232:235], v[10:13]
	v_mfma_f32_16x16x32_bf16 v[62:65], v[162:165], v[212:215], v[62:65]
	v_mfma_f32_16x16x32_bf16 v[58:61], v[172:175], v[212:215], v[58:61]
	v_mfma_f32_16x16x32_bf16 v[50:53], v[162:165], v[220:223], v[50:53]
	v_mfma_f32_16x16x32_bf16 v[42:45], v[172:175], v[220:223], v[42:45]
	v_mfma_f32_16x16x32_bf16 v[34:37], v[162:165], v[228:231], v[34:37]
	v_mfma_f32_16x16x32_bf16 v[26:29], v[172:175], v[228:231], v[26:29]
	v_mfma_f32_16x16x32_bf16 v[18:21], v[162:165], v[236:239], v[18:21]
	v_mfma_f32_16x16x32_bf16 v[10:13], v[172:175], v[236:239], v[10:13]
	s_setprio 0
	s_setprio 1
	v_mfma_f32_16x16x32_bf16 v[54:57], v[176:179], v[208:211], v[54:57]
	v_mfma_f32_16x16x32_bf16 v[46:49], v[184:187], v[208:211], v[46:49]
	v_mfma_f32_16x16x32_bf16 v[38:41], v[176:179], v[216:219], v[38:41]
	v_mfma_f32_16x16x32_bf16 v[30:33], v[184:187], v[216:219], v[30:33]
	v_mfma_f32_16x16x32_bf16 v[22:25], v[176:179], v[224:227], v[22:25]
	v_mfma_f32_16x16x32_bf16 v[14:17], v[184:187], v[224:227], v[14:17]
	v_mfma_f32_16x16x32_bf16 v[6:9], v[176:179], v[232:235], v[6:9]
	v_mfma_f32_16x16x32_bf16 v[2:5], v[184:187], v[232:235], v[2:5]
	v_mfma_f32_16x16x32_bf16 v[54:57], v[180:183], v[212:215], v[54:57]
	v_mfma_f32_16x16x32_bf16 v[46:49], v[188:191], v[212:215], v[46:49]
	v_mfma_f32_16x16x32_bf16 v[38:41], v[180:183], v[220:223], v[38:41]
	v_mfma_f32_16x16x32_bf16 v[30:33], v[188:191], v[220:223], v[30:33]
	v_mfma_f32_16x16x32_bf16 v[22:25], v[180:183], v[228:231], v[22:25]
	v_mfma_f32_16x16x32_bf16 v[14:17], v[188:191], v[228:231], v[14:17]
	v_mfma_f32_16x16x32_bf16 v[6:9], v[180:183], v[236:239], v[6:9]
	v_mfma_f32_16x16x32_bf16 v[2:5], v[188:191], v[236:239], v[2:5]
	s_setprio 0
	s_barrier
	s_add_i32 s45, s45, 2
	s_add_u32 s16, s16, 0x100
	s_addc_u32 s17, s17, 0
	s_add_u32 s43, s43, 0x100
	s_addc_u32 s44, s44, 0
	s_cmp_gt_u32 s45, 29
	s_cbranch_scc0 .LBB0_3449
	s_and_b64 vcc, exec, s[6:7]
	s_cbranch_vccz .LBB0_3452
	s_barrier

; #define PG8_STAGE(bufoff, gbase, voff) do { _Pragma("unroll") for (int _i = 0; _i < 2; ++_i) \
;         __builtin_amdgcn_global_load_lds((const unsigned*)((const char*)(gbase) + (voff)[_i]), (LAS unsigned*)(lds + (bufoff) + ldsw + _i * 8192), 16, 0, 0); } while (0)
; #define PG8_LDA(dst, b, h) do { _Pragma("unroll") for (int m = 0; m < 4; ++m) _Pragma("unroll") for (int k = 0; k < 2; ++k) dst[m][k] = *(const LAS bf16x8*)(lds + PG8_SA(b, h) + aoff + m * 2048 + k * 1024); } while (0)
; #define PG8_LDB(dst, b, h) do { _Pragma("unroll") for (int n = 0; n < 2; ++n) _Pragma("unroll") for (int k = 0; k < 2; ++k) dst[n][k] = *(const LAS bf16x8*)(lds + PG8_SB(b, h) + boff + n * 2048 + k * 1024); } while (0)
; #define PG8_MMA(ai, bj, At, Bt) do { __builtin_amdgcn_s_setprio(1); _Pragma("unroll") for (int m = 0; m < 4; ++m) _Pragma("unroll") for (int n = 0; n < 2; ++n) _Pragma("unroll") for (int k = 0; k < 2; ++k) \
;         acc[ai][bj][m][n] = __builtin_amdgcn_mfma_f32_16x16x32_bf16(Bt[n][k], At[m][k], acc[ai][bj][m][n], 0, 0, 0); __builtin_amdgcn_s_setprio(0); } while (0)
; #define PG8_WAIT_V(n) asm volatile("s_waitcnt vmcnt(" #n ")" ::: "memory")
; #define PG8_WAIT_L(n) asm volatile("s_waitcnt lgkmcnt(" #n ")" ::: "memory")
; template <class Epi, class Sched>
; __device__ __forceinline__ void gemm_phase(LAS unsigned char* lds, const Gemm g, const Sched& S, const Epi& E) {
;     ...
;         const bool has_next = S.next(ui + 1, nxt);
;         const char* nA = has_next ? (const char*)g.A + (size_t)nxt.pm * tstepA : cA; const char* nB = has_next ? (const char*)g.Bt + (size_t)nxt.pn * tstepB : cB;
;         for (int t = 0; t < nt; t += 2) {
;             const bool last = (t == nt - 2);
;             const char* a1 = cA + (size_t)(t + 1) * kstep;
;             const char* a2 = last ? nA : cA + (size_t)(t + 2) * kstep; const char* b2 = last ? nB : cB + (size_t)(t + 2) * kstep;
;             const char* a3 = a2 + kstep; const char* b3 = b2 + kstep;
;             PG8_LDB(B0, 0, 0); PG8_LDB(B1, 0, 1); PG8_SCHED; PG8_LDA(At, 0, 0); PG8_STAGE(PG8_SA(1, 1), a1 + hstepA, voffA);
;             PG8_WAIT_V(8); PG8_WAIT_L(0); PG8_BAR; PG8_MMA(0, 0, At, B0); PG8_MMA(0, 1, At, B1); PG8_BAR; PG8_SCHED;
;             PG8_LDA(At, 0, 1); PG8_STAGE(PG8_SB(0, 0), b2, voffB); PG8_STAGE(PG8_SB(0, 1), b2 + hstepB, voffB); PG8_STAGE(PG8_SA(0, 0), a2, voffA);
.LBB0_3538:
	s_add_u32 s23, s16, s22
	s_addc_u32 s28, s17, 0
	s_add_u32 s26, s23, 0x100
	s_addc_u32 s27, s28, 0
	s_and_b64 s[24:25], s[20:21], exec
	s_cselect_b32 s25, s7, s27
	s_cselect_b32 s24, s49, s26
	s_add_u32 s22, s14, s22
	s_addc_u32 s26, s15, 0
	s_add_u32 s22, s22, 0x100
	s_addc_u32 s26, s26, 0
	s_add_i32 s59, 0, 0x10000
	s_and_b64 s[20:21], s[20:21], exec
	s_cselect_b32 s27, s9, s26
	s_cselect_b32 s26, s50, s22
	s_add_i32 s21, 0, 0x14000
	s_add_u32 s30, s23, 0x10080
	s_addc_u32 s31, s28, 0
	s_add_i32 s58, s59, s38
	s_add_i32 m0, s39, 0xc000
	s_add_i32 s61, s39, 0xe000
	s_add_i32 s55, s58, 0x2000
	v_add_u32_e32 v138, s59, v1
	s_add_u32 s28, s26, 0x10000
	s_waitcnt lgkmcnt(0)
	ds_read_b128 v[142:145], v138
	ds_read_b128 v[162:165], v138 offset:1024
	ds_read_b128 v[166:169], v138 offset:2048
	ds_read_b128 v[170:173], v138 offset:3072
	v_add_u32_e32 v138, s21, v1
	s_addc_u32 s29, s27, 0
	s_add_i32 s57, s21, s38
	ds_read_b128 v[174:177], v138
	ds_read_b128 v[178:181], v138 offset:1024
	ds_read_b128 v[182:185], v138 offset:2048
	ds_read_b128 v[186:189], v138 offset:3072
	s_add_i32 s56, s57, 0x2000
	s_add_i32 s54, 0, 0x18000
	s_add_i32 s53, 0, 0x1c000
	s_add_u32 s22, s24, 0x10000
	s_addc_u32 s23, s25, 0
	s_add_i32 s52, s54, s38
	s_add_i32 s51, s52, 0x2000
	s_add_u32 s20, s26, 0x10080
	s_addc_u32 s21, s27, 0
	s_add_i32 s60, s53, s38
	s_add_i32 s59, s60, 0x2000
	v_lshl_add_u64 v[138:139], s[30:31], 0, v[136:137]
	ds_read_b128 v[190:193], v140
	ds_read_b128 v[208:211], v140 offset:1024
	ds_read_b128 v[212:215], v140 offset:2048
	ds_read_b128 v[216:219], v140 offset:3072
	ds_read_b128 v[220:223], v140 offset:4096
	ds_read_b128 v[224:227], v140 offset:5120
	ds_read_b128 v[228:231], v140 offset:6144
	ds_read_b128 v[232:235], v140 offset:7168
	global_load_lds_dwordx4 v[138:139], off
	v_lshl_add_u64 v[138:139], s[30:31], 0, v[132:133]
	s_mov_b32 m0, s61
	s_nop 0
	global_load_lds_dwordx4 v[138:139], off
	s_nop 0
	s_nop 0
	s_nop 0
	s_waitcnt vmcnt(8)
	s_waitcnt lgkmcnt(0)
	s_barrier
	s_setprio 1
	s_waitcnt lgkmcnt(0)
	v_mfma_f32_16x16x32_bf16 v[126:129], v[142:145], v[190:193], v[126:129]
	v_mfma_f32_16x16x32_bf16 v[122:125], v[166:169], v[190:193], v[122:125]
	v_mfma_f32_16x16x32_bf16 v[114:117], v[142:145], v[212:215], v[114:117]
	v_mfma_f32_16x16x32_bf16 v[106:109], v[166:169], v[212:215], v[106:109]
	v_mfma_f32_16x16x32_bf16 v[98:101], v[142:145], v[220:223], v[98:101]
	v_mfma_f32_16x16x32_bf16 v[90:93], v[166:169], v[220:223], v[90:93]
	v_mfma_f32_16x16x32_bf16 v[78:81], v[142:145], v[228:231], v[78:81]
	v_mfma_f32_16x16x32_bf16 v[74:77], v[166:169], v[228:231], v[74:77]
	v_mfma_f32_16x16x32_bf16 v[126:129], v[162:165], v[208:211], v[126:129]
	v_mfma_f32_16x16x32_bf16 v[122:125], v[170:173], v[208:211], v[122:125]
	v_mfma_f32_16x16x32_bf16 v[114:117], v[162:165], v[216:219], v[114:117]
	v_mfma_f32_16x16x32_bf16 v[106:109], v[170:173], v[216:219], v[106:109]
	v_mfma_f32_16x16x32_bf16 v[98:101], v[162:165], v[224:227], v[98:101]
	v_mfma_f32_16x16x32_bf16 v[90:93], v[170:173], v[224:227], v[90:93]
	v_mfma_f32_16x16x32_bf16 v[78:81], v[162:165], v[232:235], v[78:81]
	v_mfma_f32_16x16x32_bf16 v[74:77], v[170:173], v[232:235], v[74:77]
	s_setprio 0
	s_setprio 1
	v_mfma_f32_16x16x32_bf16 v[118:121], v[174:177], v[190:193], v[118:121]
	v_mfma_f32_16x16x32_bf16 v[110:113], v[182:185], v[190:193], v[110:113]
	v_mfma_f32_16x16x32_bf16 v[102:105], v[174:177], v[212:215], v[102:105]
	v_mfma_f32_16x16x32_bf16 v[94:97], v[182:185], v[212:215], v[94:97]
	v_mfma_f32_16x16x32_bf16 v[86:89], v[174:177], v[220:223], v[86:89]
	v_mfma_f32_16x16x32_bf16 v[82:85], v[182:185], v[220:223], v[82:85]
	v_mfma_f32_16x16x32_bf16 v[70:73], v[174:177], v[228:231], v[70:73]
	v_mfma_f32_16x16x32_bf16 v[66:69], v[182:185], v[228:231], v[66:69]
	v_mfma_f32_16x16x32_bf16 v[118:121], v[178:181], v[208:211], v[118:121]
	v_mfma_f32_16x16x32_bf16 v[110:113], v[186:189], v[208:211], v[110:113]
	v_mfma_f32_16x16x32_bf16 v[102:105], v[178:181], v[216:219], v[102:105]
	v_mfma_f32_16x16x32_bf16 v[94:97], v[186:189], v[216:219], v[94:97]
	v_mfma_f32_16x16x32_bf16 v[86:89], v[178:181], v[224:227], v[86:89]
	v_mfma_f32_16x16x32_bf16 v[82:85], v[186:189], v[224:227], v[82:85]
	v_mfma_f32_16x16x32_bf16 v[70:73], v[178:181], v[232:235], v[70:73]
	v_mfma_f32_16x16x32_bf16 v[66:69], v[186:189], v[232:235], v[66:69]
	s_setprio 0
	s_barrier
	s_mov_b32 m0, s58
	v_lshl_add_u64 v[138:139], s[26:27], 0, v[134:135]
	ds_read_b128 v[190:193], v140 offset:16384
	ds_read_b128 v[208:211], v140 offset:17408
	ds_read_b128 v[212:215], v140 offset:18432
	ds_read_b128 v[216:219], v140 offset:19456
	ds_read_b128 v[220:223], v140 offset:20480
	ds_read_b128 v[224:227], v140 offset:21504
	ds_read_b128 v[228:231], v140 offset:22528
	ds_read_b128 v[232:235], v140 offset:23552
	global_load_lds_dwordx4 v[138:139], off
	v_lshl_add_u64 v[236:237], s[26:27], 0, v[130:131]
	s_mov_b32 m0, s55
	v_lshl_add_u64 v[238:239], s[28:29], 0, v[134:135]
	global_load_lds_dwordx4 v[236:237], off
	s_mov_b32 m0, s57
	v_lshl_add_u64 v[240:241], s[24:25], 0, v[132:133]
	global_load_lds_dwordx4 v[238:239], off
	v_lshl_add_u64 v[238:239], s[28:29], 0, v[130:131]
	s_mov_b32 m0, s56
	s_nop 0
	global_load_lds_dwordx4 v[238:239], off
	v_lshl_add_u64 v[238:239], s[24:25], 0, v[136:137]
	s_mov_b32 m0, s39
	s_nop 0
	global_load_lds_dwordx4 v[238:239], off
	s_mov_b32 m0, s40
	s_nop 0
	global_load_lds_dwordx4 v[240:241], off
	s_nop 0
	s_nop 0
	s_waitcnt vmcnt(8)
	s_waitcnt lgkmcnt(0)
	s_barrier
; #define PG8_STAGE(bufoff, gbase, voff) do { _Pragma("unroll") for (int _i = 0; _i < 2; ++_i) \
;         __builtin_amdgcn_global_load_lds((const unsigned*)((const char*)(gbase) + (voff)[_i]), (LAS unsigned*)(lds + (bufoff) + ldsw + _i * 8192), 16, 0, 0); } while (0)
; #define PG8_LDA(dst, b, h) do { _Pragma("unroll") for (int m = 0; m < 4; ++m) _Pragma("unroll") for (int k = 0; k < 2; ++k) dst[m][k] = *(const LAS bf16x8*)(lds + PG8_SA(b, h) + aoff + m * 2048 + k * 1024); } while (0)
; #define PG8_LDB(dst, b, h) do { _Pragma("unroll") for (int n = 0; n < 2; ++n) _Pragma("unroll") for (int k = 0; k < 2; ++k) dst[n][k] = *(const LAS bf16x8*)(lds + PG8_SB(b, h) + boff + n * 2048 + k * 1024); } while (0)
; #define PG8_MMA(ai, bj, At, Bt) do { __builtin_amdgcn_s_setprio(1); _Pragma("unroll") for (int m = 0; m < 4; ++m) _Pragma("unroll") for (int n = 0; n < 2; ++n) _Pragma("unroll") for (int k = 0; k < 2; ++k) \
;         acc[ai][bj][m][n] = __builtin_amdgcn_mfma_f32_16x16x32_bf16(Bt[n][k], At[m][k], acc[ai][bj][m][n], 0, 0, 0); __builtin_amdgcn_s_setprio(0); } while (0)
; #define PG8_WAIT_V(n) asm volatile("s_waitcnt vmcnt(" #n ")" ::: "memory")
; #define PG8_WAIT_L(n) asm volatile("s_waitcnt lgkmcnt(" #n ")" ::: "memory")
; #define PG8_BAR __builtin_amdgcn_s_barrier()
; #define PG8_SCHED __builtin_amdgcn_sched_barrier(0)
; template <class Epi, class Sched>
; __device__ __forceinline__ void gemm_phase(LAS unsigned char* lds, const Gemm g, const Sched& S, const Epi& E) {
;     ...
;             PG8_WAIT_V(8); PG8_WAIT_L(0); PG8_BAR; PG8_MMA(1, 0, At, B0); PG8_MMA(1, 1, At, B1); PG8_BAR; PG8_SCHED;
;             PG8_LDB(B0, 1, 0); PG8_LDB(B1, 1, 1); PG8_SCHED; PG8_LDA(At, 1, 0); PG8_STAGE(PG8_SA(0, 1), a2 + hstepA, voffA);
;             PG8_WAIT_V(8); PG8_WAIT_L(0); PG8_BAR; PG8_MMA(0, 0, At, B0); PG8_MMA(0, 1, At, B1); PG8_BAR; PG8_SCHED;
	s_setprio 1
	s_waitcnt lgkmcnt(0)
	v_mfma_f32_16x16x32_bf16 v[62:65], v[142:145], v[190:193], v[62:65]
	v_mfma_f32_16x16x32_bf16 v[58:61], v[166:169], v[190:193], v[58:61]
	v_mfma_f32_16x16x32_bf16 v[50:53], v[142:145], v[212:215], v[50:53]
	v_mfma_f32_16x16x32_bf16 v[42:45], v[166:169], v[212:215], v[42:45]
	v_mfma_f32_16x16x32_bf16 v[34:37], v[142:145], v[220:223], v[34:37]
	v_mfma_f32_16x16x32_bf16 v[26:29], v[166:169], v[220:223], v[26:29]
	v_mfma_f32_16x16x32_bf16 v[18:21], v[142:145], v[228:231], v[18:21]
	v_mfma_f32_16x16x32_bf16 v[10:13], v[166:169], v[228:231], v[10:13]
	v_mfma_f32_16x16x32_bf16 v[62:65], v[162:165], v[208:211], v[62:65]
	v_mfma_f32_16x16x32_bf16 v[58:61], v[170:173], v[208:211], v[58:61]
	v_mfma_f32_16x16x32_bf16 v[50:53], v[162:165], v[216:219], v[50:53]
	v_mfma_f32_16x16x32_bf16 v[42:45], v[170:173], v[216:219], v[42:45]
	v_mfma_f32_16x16x32_bf16 v[34:37], v[162:165], v[224:227], v[34:37]
	v_mfma_f32_16x16x32_bf16 v[26:29], v[170:173], v[224:227], v[26:29]
	v_mfma_f32_16x16x32_bf16 v[18:21], v[162:165], v[232:235], v[18:21]
	v_mfma_f32_16x16x32_bf16 v[10:13], v[170:173], v[232:235], v[10:13]
	s_setprio 0
	s_setprio 1
	v_mfma_f32_16x16x32_bf16 v[54:57], v[174:177], v[190:193], v[54:57]
	v_mfma_f32_16x16x32_bf16 v[46:49], v[182:185], v[190:193], v[46:49]
	v_mfma_f32_16x16x32_bf16 v[38:41], v[174:177], v[212:215], v[38:41]
	v_mfma_f32_16x16x32_bf16 v[30:33], v[182:185], v[212:215], v[30:33]
	v_mfma_f32_16x16x32_bf16 v[22:25], v[174:177], v[220:223], v[22:25]
	v_mfma_f32_16x16x32_bf16 v[14:17], v[182:185], v[220:223], v[14:17]
	v_mfma_f32_16x16x32_bf16 v[6:9], v[174:177], v[228:231], v[6:9]
	v_mfma_f32_16x16x32_bf16 v[2:5], v[182:185], v[228:231], v[2:5]
	v_mfma_f32_16x16x32_bf16 v[54:57], v[178:181], v[208:211], v[54:57]
	v_mfma_f32_16x16x32_bf16 v[46:49], v[186:189], v[208:211], v[46:49]
	v_mfma_f32_16x16x32_bf16 v[38:41], v[178:181], v[216:219], v[38:41]
	v_mfma_f32_16x16x32_bf16 v[30:33], v[186:189], v[216:219], v[30:33]
	v_mfma_f32_16x16x32_bf16 v[22:25], v[178:181], v[224:227], v[22:25]
	v_mfma_f32_16x16x32_bf16 v[14:17], v[186:189], v[224:227], v[14:17]
	v_mfma_f32_16x16x32_bf16 v[6:9], v[178:181], v[232:235], v[6:9]
	v_mfma_f32_16x16x32_bf16 v[2:5], v[186:189], v[232:235], v[2:5]
	s_setprio 0
	s_barrier
	v_add_u32_e32 v141, s54, v1
	ds_read_b128 v[142:145], v141
	ds_read_b128 v[162:165], v141 offset:1024
	ds_read_b128 v[166:169], v141 offset:2048
	ds_read_b128 v[170:173], v141 offset:3072
	v_add_u32_e32 v141, s53, v1
	ds_read_b128 v[174:177], v141
	ds_read_b128 v[178:181], v141 offset:1024
	ds_read_b128 v[182:185], v141 offset:2048
	ds_read_b128 v[186:189], v141 offset:3072
	s_mov_b32 m0, s41
	v_lshl_add_u64 v[242:243], s[22:23], 0, v[136:137]
	ds_read_b128 v[190:193], v140 offset:32768
	ds_read_b128 v[208:211], v140 offset:33792
	ds_read_b128 v[212:215], v140 offset:34816
	ds_read_b128 v[216:219], v140 offset:35840
	ds_read_b128 v[220:223], v140 offset:36864
	ds_read_b128 v[224:227], v140 offset:37888
	ds_read_b128 v[228:231], v140 offset:38912
	ds_read_b128 v[232:235], v140 offset:39936
	global_load_lds_dwordx4 v[242:243], off
	v_lshl_add_u64 v[242:243], s[22:23], 0, v[132:133]
	s_mov_b32 m0, s42
	s_nop 0
	global_load_lds_dwordx4 v[242:243], off
	s_nop 0
	s_nop 0
	s_waitcnt vmcnt(8)
	s_waitcnt lgkmcnt(0)
	s_barrier
	s_setprio 1
	s_waitcnt lgkmcnt(0)
	v_mfma_f32_16x16x32_bf16 v[126:129], v[142:145], v[190:193], v[126:129]
	v_mfma_f32_16x16x32_bf16 v[122:125], v[166:169], v[190:193], v[122:125]
	v_mfma_f32_16x16x32_bf16 v[114:117], v[142:145], v[212:215], v[114:117]
	v_mfma_f32_16x16x32_bf16 v[106:109], v[166:169], v[212:215], v[106:109]
	v_mfma_f32_16x16x32_bf16 v[98:101], v[142:145], v[220:223], v[98:101]
	v_mfma_f32_16x16x32_bf16 v[90:93], v[166:169], v[220:223], v[90:93]
	v_mfma_f32_16x16x32_bf16 v[78:81], v[142:145], v[228:231], v[78:81]
	v_mfma_f32_16x16x32_bf16 v[74:77], v[166:169], v[228:231], v[74:77]
	v_mfma_f32_16x16x32_bf16 v[126:129], v[162:165], v[208:211], v[126:129]
	v_mfma_f32_16x16x32_bf16 v[122:125], v[170:173], v[208:211], v[122:125]
	v_mfma_f32_16x16x32_bf16 v[114:117], v[162:165], v[216:219], v[114:117]
	v_mfma_f32_16x16x32_bf16 v[106:109], v[170:173], v[216:219], v[106:109]
	v_mfma_f32_16x16x32_bf16 v[98:101], v[162:165], v[224:227], v[98:101]
	v_mfma_f32_16x16x32_bf16 v[90:93], v[170:173], v[224:227], v[90:93]
	v_mfma_f32_16x16x32_bf16 v[78:81], v[162:165], v[232:235], v[78:81]
	v_mfma_f32_16x16x32_bf16 v[74:77], v[170:173], v[232:235], v[74:77]
	s_setprio 0
	s_setprio 1
	v_mfma_f32_16x16x32_bf16 v[118:121], v[174:177], v[190:193], v[118:121]
	v_mfma_f32_16x16x32_bf16 v[110:113], v[182:185], v[190:193], v[110:113]
	v_mfma_f32_16x16x32_bf16 v[102:105], v[174:177], v[212:215], v[102:105]
	v_mfma_f32_16x16x32_bf16 v[94:97], v[182:185], v[212:215], v[94:97]
	v_mfma_f32_16x16x32_bf16 v[86:89], v[174:177], v[220:223], v[86:89]
	v_mfma_f32_16x16x32_bf16 v[82:85], v[182:185], v[220:223], v[82:85]
	v_mfma_f32_16x16x32_bf16 v[70:73], v[174:177], v[228:231], v[70:73]
	v_mfma_f32_16x16x32_bf16 v[66:69], v[182:185], v[228:231], v[66:69]
	v_mfma_f32_16x16x32_bf16 v[118:121], v[178:181], v[208:211], v[118:121]
	v_mfma_f32_16x16x32_bf16 v[110:113], v[186:189], v[208:211], v[110:113]
	v_mfma_f32_16x16x32_bf16 v[102:105], v[178:181], v[216:219], v[102:105]
	v_mfma_f32_16x16x32_bf16 v[94:97], v[186:189], v[216:219], v[94:97]
	v_mfma_f32_16x16x32_bf16 v[86:89], v[178:181], v[224:227], v[86:89]
	v_mfma_f32_16x16x32_bf16 v[82:85], v[186:189], v[224:227], v[82:85]
	v_mfma_f32_16x16x32_bf16 v[70:73], v[178:181], v[232:235], v[70:73]
	v_mfma_f32_16x16x32_bf16 v[66:69], v[186:189], v[232:235], v[66:69]
	s_setprio 0
	s_barrier
; #define PG8_STAGE(bufoff, gbase, voff) do { _Pragma("unroll") for (int _i = 0; _i < 2; ++_i) \
;         __builtin_amdgcn_global_load_lds((const unsigned*)((const char*)(gbase) + (voff)[_i]), (LAS unsigned*)(lds + (bufoff) + ldsw + _i * 8192), 16, 0, 0); } while (0)
; #define PG8_LDA(dst, b, h) do { _Pragma("unroll") for (int m = 0; m < 4; ++m) _Pragma("unroll") for (int k = 0; k < 2; ++k) dst[m][k] = *(const LAS bf16x8*)(lds + PG8_SA(b, h) + aoff + m * 2048 + k * 1024); } while (0)
; #define PG8_MMA(ai, bj, At, Bt) do { __builtin_amdgcn_s_setprio(1); _Pragma("unroll") for (int m = 0; m < 4; ++m) _Pragma("unroll") for (int n = 0; n < 2; ++n) _Pragma("unroll") for (int k = 0; k < 2; ++k) \
;         acc[ai][bj][m][n] = __builtin_amdgcn_mfma_f32_16x16x32_bf16(Bt[n][k], At[m][k], acc[ai][bj][m][n], 0, 0, 0); __builtin_amdgcn_s_setprio(0); } while (0)
; #define PG8_WAIT_V(n) asm volatile("s_waitcnt vmcnt(" #n ")" ::: "memory")
; #define PG8_WAIT_L(n) asm volatile("s_waitcnt lgkmcnt(" #n ")" ::: "memory")
; #define PG8_BAR __builtin_amdgcn_s_barrier()
; #define PG8_SCHED __builtin_amdgcn_sched_barrier(0)
; template <class Epi, class Sched>
; __device__ __forceinline__ void gemm_phase(LAS unsigned char* lds, const Gemm g, const Sched& S, const Epi& E) {
;     ...
;             PG8_LDA(At, 1, 1); PG8_STAGE(PG8_SB(1, 0), b3, voffB); PG8_STAGE(PG8_SB(1, 1), b3 + hstepB, voffB); PG8_STAGE(PG8_SA(1, 0), a3, voffA);
;             PG8_WAIT_V(8); PG8_WAIT_L(0); PG8_BAR; PG8_MMA(1, 0, At, B0); PG8_MMA(1, 1, At, B1); PG8_BAR; PG8_SCHED;
;         }
;         if (wr == 0) PG8_BAR;
	s_mov_b32 m0, s52
	v_lshl_add_u64 v[138:139], v[138:139], 0, s[64:65]
	ds_read_b128 v[190:193], v140 offset:49152
	ds_read_b128 v[208:211], v140 offset:50176
	ds_read_b128 v[212:215], v140 offset:51200
	ds_read_b128 v[216:219], v140 offset:52224
	ds_read_b128 v[220:223], v140 offset:53248
	ds_read_b128 v[224:227], v140 offset:54272
	ds_read_b128 v[228:231], v140 offset:55296
	ds_read_b128 v[232:235], v140 offset:56320
	global_load_lds_dwordx4 v[138:139], off
	v_lshl_add_u64 v[138:139], v[236:237], 0, s[64:65]
	s_mov_b32 m0, s51
	s_nop 0
	global_load_lds_dwordx4 v[138:139], off
	v_lshl_add_u64 v[138:139], s[20:21], 0, v[134:135]
	s_mov_b32 m0, s60
	s_nop 0
	global_load_lds_dwordx4 v[138:139], off
	v_lshl_add_u64 v[138:139], s[20:21], 0, v[130:131]
	s_mov_b32 m0, s59
	s_nop 0
	global_load_lds_dwordx4 v[138:139], off
	v_lshl_add_u64 v[138:139], v[238:239], 0, s[64:65]
	s_mov_b32 m0, s45
	s_nop 0
	global_load_lds_dwordx4 v[138:139], off
	v_lshl_add_u64 v[138:139], v[240:241], 0, s[64:65]
	s_mov_b32 m0, s46
	s_nop 0
	global_load_lds_dwordx4 v[138:139], off
	s_waitcnt vmcnt(8)
	s_waitcnt lgkmcnt(0)
	s_barrier
	s_setprio 1
	s_waitcnt lgkmcnt(0)
	v_mfma_f32_16x16x32_bf16 v[62:65], v[142:145], v[190:193], v[62:65]
	v_mfma_f32_16x16x32_bf16 v[58:61], v[166:169], v[190:193], v[58:61]
	v_mfma_f32_16x16x32_bf16 v[50:53], v[142:145], v[212:215], v[50:53]
	v_mfma_f32_16x16x32_bf16 v[42:45], v[166:169], v[212:215], v[42:45]
	v_mfma_f32_16x16x32_bf16 v[34:37], v[142:145], v[220:223], v[34:37]
	v_mfma_f32_16x16x32_bf16 v[26:29], v[166:169], v[220:223], v[26:29]
	v_mfma_f32_16x16x32_bf16 v[18:21], v[142:145], v[228:231], v[18:21]
	v_mfma_f32_16x16x32_bf16 v[10:13], v[166:169], v[228:231], v[10:13]
	v_mfma_f32_16x16x32_bf16 v[62:65], v[162:165], v[208:211], v[62:65]
	v_mfma_f32_16x16x32_bf16 v[58:61], v[170:173], v[208:211], v[58:61]
	v_mfma_f32_16x16x32_bf16 v[50:53], v[162:165], v[216:219], v[50:53]
	v_mfma_f32_16x16x32_bf16 v[42:45], v[170:173], v[216:219], v[42:45]
	v_mfma_f32_16x16x32_bf16 v[34:37], v[162:165], v[224:227], v[34:37]
	v_mfma_f32_16x16x32_bf16 v[26:29], v[170:173], v[224:227], v[26:29]
	v_mfma_f32_16x16x32_bf16 v[18:21], v[162:165], v[232:235], v[18:21]
	v_mfma_f32_16x16x32_bf16 v[10:13], v[170:173], v[232:235], v[10:13]
	s_setprio 0
	s_setprio 1
	v_mfma_f32_16x16x32_bf16 v[54:57], v[174:177], v[190:193], v[54:57]
	v_mfma_f32_16x16x32_bf16 v[46:49], v[182:185], v[190:193], v[46:49]
	v_mfma_f32_16x16x32_bf16 v[38:41], v[174:177], v[212:215], v[38:41]
	v_mfma_f32_16x16x32_bf16 v[30:33], v[182:185], v[212:215], v[30:33]
	v_mfma_f32_16x16x32_bf16 v[22:25], v[174:177], v[220:223], v[22:25]
	v_mfma_f32_16x16x32_bf16 v[14:17], v[182:185], v[220:223], v[14:17]
	v_mfma_f32_16x16x32_bf16 v[6:9], v[174:177], v[228:231], v[6:9]
	v_mfma_f32_16x16x32_bf16 v[2:5], v[182:185], v[228:231], v[2:5]
	v_mfma_f32_16x16x32_bf16 v[54:57], v[178:181], v[208:211], v[54:57]
	v_mfma_f32_16x16x32_bf16 v[46:49], v[186:189], v[208:211], v[46:49]
	v_mfma_f32_16x16x32_bf16 v[38:41], v[178:181], v[216:219], v[38:41]
	v_mfma_f32_16x16x32_bf16 v[30:33], v[186:189], v[216:219], v[30:33]
	v_mfma_f32_16x16x32_bf16 v[22:25], v[178:181], v[224:227], v[22:25]
	v_mfma_f32_16x16x32_bf16 v[14:17], v[186:189], v[224:227], v[14:17]
	v_mfma_f32_16x16x32_bf16 v[6:9], v[178:181], v[232:235], v[6:9]
	v_mfma_f32_16x16x32_bf16 v[2:5], v[186:189], v[232:235], v[2:5]
	s_setprio 0
	s_barrier
	s_movk_i32 s22, 0x100
	s_andn2_b64 vcc, exec, s[18:19]
	s_mov_b64 s[20:21], -1
	s_mov_b64 s[18:19], 0
	s_cbranch_vccz .LBB0_3538
	s_and_b64 vcc, exec, s[4:5]
	s_cbranch_vccz .LBB0_3541
	s_barrier

; #define PG8_STAGE(bufoff, gbase, voff) do { _Pragma("unroll") for (int _i = 0; _i < 2; ++_i) \
;         __builtin_amdgcn_global_load_lds((const unsigned*)((const char*)(gbase) + (voff)[_i]), (LAS unsigned*)(lds + (bufoff) + ldsw + _i * 8192), 16, 0, 0); } while (0)
; #define PG8_LDA(dst, b, h) do { _Pragma("unroll") for (int m = 0; m < 4; ++m) _Pragma("unroll") for (int k = 0; k < 2; ++k) dst[m][k] = *(const LAS bf16x8*)(lds + PG8_SA(b, h) + aoff + m * 2048 + k * 1024); } while (0)
; #define PG8_LDB(dst, b, h) do { _Pragma("unroll") for (int n = 0; n < 2; ++n) _Pragma("unroll") for (int k = 0; k < 2; ++k) dst[n][k] = *(const LAS bf16x8*)(lds + PG8_SB(b, h) + boff + n * 2048 + k * 1024); } while (0)
; #define PG8_MMA(ai, bj, At, Bt) do { __builtin_amdgcn_s_setprio(1); _Pragma("unroll") for (int m = 0; m < 4; ++m) _Pragma("unroll") for (int n = 0; n < 2; ++n) _Pragma("unroll") for (int k = 0; k < 2; ++k) \
;         acc[ai][bj][m][n] = __builtin_amdgcn_mfma_f32_16x16x32_bf16(Bt[n][k], At[m][k], acc[ai][bj][m][n], 0, 0, 0); __builtin_amdgcn_s_setprio(0); } while (0)
; #define PG8_WAIT_V(n) asm volatile("s_waitcnt vmcnt(" #n ")" ::: "memory")
; #define PG8_WAIT_L(n) asm volatile("s_waitcnt lgkmcnt(" #n ")" ::: "memory")
; #define PG8_BAR __builtin_amdgcn_s_barrier()
; #define PG8_SCHED __builtin_amdgcn_sched_barrier(0)
; template <class Epi, class Sched>
; __device__ __forceinline__ void gemm_phase(LAS unsigned char* lds, const Gemm g, const Sched& S, const Epi& E) {
;     ...
;         for (int t = 0; t < nt; t += 2) {
;             const bool last = (t == nt - 2);
;             const char* a1 = cA + (size_t)(t + 1) * kstep;
;             const char* a2 = last ? nA : cA + (size_t)(t + 2) * kstep; const char* b2 = last ? nB : cB + (size_t)(t + 2) * kstep;
;             const char* a3 = a2 + kstep; const char* b3 = b2 + kstep;
;             PG8_LDB(B0, 0, 0); PG8_LDB(B1, 0, 1); PG8_SCHED; PG8_LDA(At, 0, 0); PG8_STAGE(PG8_SA(1, 1), a1 + hstepA, voffA);
;             PG8_WAIT_V(8); PG8_WAIT_L(0); PG8_BAR; PG8_MMA(0, 0, At, B0); PG8_MMA(0, 1, At, B1); PG8_BAR; PG8_SCHED;
;             PG8_LDA(At, 0, 1); PG8_STAGE(PG8_SB(0, 0), b2, voffB); PG8_STAGE(PG8_SB(0, 1), b2 + hstepB, voffB); PG8_STAGE(PG8_SA(0, 0), a2, voffA);
;             PG8_WAIT_V(8); PG8_WAIT_L(0); PG8_BAR; PG8_MMA(1, 0, At, B0); PG8_MMA(1, 1, At, B1); PG8_BAR; PG8_SCHED;
.LBB0_3562:
	s_add_u32 s20, s18, 0xfff80080
	s_addc_u32 s21, s19, -1
	s_add_i32 s49, 0, 0x10000
	v_add_u32_e32 v83, s49, v1
	ds_read_b128 v[78:81], v83
	ds_read_b128 v[84:87], v83 offset:1024
	ds_read_b128 v[88:91], v83 offset:2048
	ds_read_b128 v[92:95], v83 offset:3072
	s_cmp_eq_u32 s48, 28
	s_cselect_b32 s23, s13, s21
	s_cselect_b32 s22, s44, s20
	s_cselect_b32 s21, s11, s47
	s_cselect_b32 s20, s45, s46
	v_lshl_add_u64 v[128:129], s[18:19], 0, v[74:75]
	s_add_i32 m0, s26, 0xc000
	ds_read_b128 v[96:99], v82
	ds_read_b128 v[100:103], v82 offset:1024
	ds_read_b128 v[104:107], v82 offset:2048
	ds_read_b128 v[108:111], v82 offset:3072
	ds_read_b128 v[112:115], v82 offset:4096
	ds_read_b128 v[116:119], v82 offset:5120
	ds_read_b128 v[120:123], v82 offset:6144
	ds_read_b128 v[124:127], v82 offset:7168
	global_load_lds_dwordx4 v[128:129], off
	v_lshl_add_u64 v[128:129], s[18:19], 0, v[76:77]
	s_add_i32 m0, s26, 0xe000
	s_nop 0
	global_load_lds_dwordx4 v[128:129], off
	s_nop 0
	s_nop 0
	s_waitcnt vmcnt(8)
	s_waitcnt lgkmcnt(0)
	s_barrier
	s_setprio 1
	s_waitcnt lgkmcnt(0)
	v_mfma_f32_16x16x32_bf16 v[62:65], v[78:81], v[96:99], v[62:65]
	v_mfma_f32_16x16x32_bf16 v[58:61], v[88:91], v[96:99], v[58:61]
	v_mfma_f32_16x16x32_bf16 v[54:57], v[78:81], v[104:107], v[54:57]
	v_mfma_f32_16x16x32_bf16 v[50:53], v[88:91], v[104:107], v[50:53]
	v_mfma_f32_16x16x32_bf16 v[46:49], v[78:81], v[112:115], v[46:49]
	v_mfma_f32_16x16x32_bf16 v[42:45], v[88:91], v[112:115], v[42:45]
	v_mfma_f32_16x16x32_bf16 v[38:41], v[78:81], v[120:123], v[38:41]
	v_mfma_f32_16x16x32_bf16 v[34:37], v[88:91], v[120:123], v[34:37]
	v_mfma_f32_16x16x32_bf16 v[62:65], v[84:87], v[100:103], v[62:65]
	v_mfma_f32_16x16x32_bf16 v[58:61], v[92:95], v[100:103], v[58:61]
	v_mfma_f32_16x16x32_bf16 v[54:57], v[84:87], v[108:111], v[54:57]
	v_mfma_f32_16x16x32_bf16 v[50:53], v[92:95], v[108:111], v[50:53]
	v_mfma_f32_16x16x32_bf16 v[46:49], v[84:87], v[116:119], v[46:49]
	v_mfma_f32_16x16x32_bf16 v[42:45], v[92:95], v[116:119], v[42:45]
	v_mfma_f32_16x16x32_bf16 v[38:41], v[84:87], v[124:127], v[38:41]
	v_mfma_f32_16x16x32_bf16 v[34:37], v[92:95], v[124:127], v[34:37]
	s_setprio 0
	s_setprio 1
	s_setprio 0
	s_barrier
	s_add_i32 s49, s49, s25
	v_lshl_add_u64 v[128:129], s[20:21], 0, v[70:71]
	s_mov_b32 m0, s49
	ds_read_b128 v[96:99], v82 offset:16384
	ds_read_b128 v[100:103], v82 offset:17408
	ds_read_b128 v[104:107], v82 offset:18432
	ds_read_b128 v[108:111], v82 offset:19456
	ds_read_b128 v[112:115], v82 offset:20480
	ds_read_b128 v[116:119], v82 offset:21504
	ds_read_b128 v[120:123], v82 offset:22528
	ds_read_b128 v[124:127], v82 offset:23552
	global_load_lds_dwordx4 v[128:129], off
	s_add_i32 m0, s49, 0x2000
	s_add_u32 s50, s20, 0x80000
	v_lshl_add_u64 v[130:131], s[20:21], 0, v[66:67]
	s_addc_u32 s51, s21, 0
	global_load_lds_dwordx4 v[130:131], off
	v_lshl_add_u64 v[132:133], s[50:51], 0, v[70:71]
	s_mov_b32 m0, s27
	v_lshl_add_u64 v[134:135], s[22:23], 0, v[68:69]
	global_load_lds_dwordx4 v[132:133], off
	v_lshl_add_u64 v[132:133], s[50:51], 0, v[66:67]
	s_mov_b32 m0, s28
	s_nop 0
	global_load_lds_dwordx4 v[132:133], off
	v_lshl_add_u64 v[132:133], s[22:23], 0, v[72:73]
	s_mov_b32 m0, s26
	s_nop 0
	global_load_lds_dwordx4 v[132:133], off
	s_mov_b32 m0, s29
	s_nop 0
	global_load_lds_dwordx4 v[134:135], off
	s_nop 0
	s_waitcnt vmcnt(8)
	s_waitcnt lgkmcnt(0)
	s_barrier
	s_setprio 1
	s_waitcnt lgkmcnt(0)
	v_mfma_f32_16x16x32_bf16 v[30:33], v[78:81], v[96:99], v[30:33]
	v_mfma_f32_16x16x32_bf16 v[26:29], v[88:91], v[96:99], v[26:29]
	v_mfma_f32_16x16x32_bf16 v[22:25], v[78:81], v[104:107], v[22:25]
	v_mfma_f32_16x16x32_bf16 v[18:21], v[88:91], v[104:107], v[18:21]
	v_mfma_f32_16x16x32_bf16 v[14:17], v[78:81], v[112:115], v[14:17]
	v_mfma_f32_16x16x32_bf16 v[10:13], v[88:91], v[112:115], v[10:13]
	v_mfma_f32_16x16x32_bf16 v[6:9], v[78:81], v[120:123], v[6:9]
	v_mfma_f32_16x16x32_bf16 v[2:5], v[88:91], v[120:123], v[2:5]
	v_mfma_f32_16x16x32_bf16 v[30:33], v[84:87], v[100:103], v[30:33]
	v_mfma_f32_16x16x32_bf16 v[26:29], v[92:95], v[100:103], v[26:29]
	v_mfma_f32_16x16x32_bf16 v[22:25], v[84:87], v[108:111], v[22:25]
	v_mfma_f32_16x16x32_bf16 v[18:21], v[92:95], v[108:111], v[18:21]
	v_mfma_f32_16x16x32_bf16 v[14:17], v[84:87], v[116:119], v[14:17]
	v_mfma_f32_16x16x32_bf16 v[10:13], v[92:95], v[116:119], v[10:13]
	v_mfma_f32_16x16x32_bf16 v[6:9], v[84:87], v[124:127], v[6:9]
	v_mfma_f32_16x16x32_bf16 v[2:5], v[92:95], v[124:127], v[2:5]
	s_setprio 0
	s_setprio 1
	s_setprio 0
	s_barrier
; #define PG8_STAGE(bufoff, gbase, voff) do { _Pragma("unroll") for (int _i = 0; _i < 2; ++_i) \
;         __builtin_amdgcn_global_load_lds((const unsigned*)((const char*)(gbase) + (voff)[_i]), (LAS unsigned*)(lds + (bufoff) + ldsw + _i * 8192), 16, 0, 0); } while (0)
; #define PG8_LDA(dst, b, h) do { _Pragma("unroll") for (int m = 0; m < 4; ++m) _Pragma("unroll") for (int k = 0; k < 2; ++k) dst[m][k] = *(const LAS bf16x8*)(lds + PG8_SA(b, h) + aoff + m * 2048 + k * 1024); } while (0)
; #define PG8_LDB(dst, b, h) do { _Pragma("unroll") for (int n = 0; n < 2; ++n) _Pragma("unroll") for (int k = 0; k < 2; ++k) dst[n][k] = *(const LAS bf16x8*)(lds + PG8_SB(b, h) + boff + n * 2048 + k * 1024); } while (0)
; #define PG8_MMA(ai, bj, At, Bt) do { __builtin_amdgcn_s_setprio(1); _Pragma("unroll") for (int m = 0; m < 4; ++m) _Pragma("unroll") for (int n = 0; n < 2; ++n) _Pragma("unroll") for (int k = 0; k < 2; ++k) \
;         acc[ai][bj][m][n] = __builtin_amdgcn_mfma_f32_16x16x32_bf16(Bt[n][k], At[m][k], acc[ai][bj][m][n], 0, 0, 0); __builtin_amdgcn_s_setprio(0); } while (0)
; #define PG8_WAIT_V(n) asm volatile("s_waitcnt vmcnt(" #n ")" ::: "memory")
; #define PG8_WAIT_L(n) asm volatile("s_waitcnt lgkmcnt(" #n ")" ::: "memory")
; #define PG8_BAR __builtin_amdgcn_s_barrier()
; #define PG8_SCHED __builtin_amdgcn_sched_barrier(0)
; template <class Epi, class Sched>
; __device__ __forceinline__ void gemm_phase(LAS unsigned char* lds, const Gemm g, const Sched& S, const Epi& E) {
;     ...
;             PG8_LDB(B0, 1, 0); PG8_LDB(B1, 1, 1); PG8_SCHED; PG8_LDA(At, 1, 0); PG8_STAGE(PG8_SA(0, 1), a2 + hstepA, voffA);
;             PG8_WAIT_V(8); PG8_WAIT_L(0); PG8_BAR; PG8_MMA(0, 0, At, B0); PG8_MMA(0, 1, At, B1); PG8_BAR; PG8_SCHED;
;             PG8_LDA(At, 1, 1); PG8_STAGE(PG8_SB(1, 0), b3, voffB); PG8_STAGE(PG8_SB(1, 1), b3 + hstepB, voffB); PG8_STAGE(PG8_SA(1, 0), a3, voffA);
;             PG8_WAIT_V(8); PG8_WAIT_L(0); PG8_BAR; PG8_MMA(1, 0, At, B0); PG8_MMA(1, 1, At, B1); PG8_BAR; PG8_SCHED;
;         }
;         if (wr == 0) PG8_BAR;
	s_add_i32 s49, 0, 0x18000
	v_add_u32_e32 v83, s49, v1
	ds_read_b128 v[78:81], v83
	ds_read_b128 v[84:87], v83 offset:1024
	ds_read_b128 v[88:91], v83 offset:2048
	ds_read_b128 v[92:95], v83 offset:3072
	s_add_u32 s22, s22, 0x80000
	s_addc_u32 s23, s23, 0
	s_mov_b32 m0, s30
	v_lshl_add_u64 v[136:137], s[22:23], 0, v[72:73]
	ds_read_b128 v[96:99], v82 offset:32768
	ds_read_b128 v[100:103], v82 offset:33792
	ds_read_b128 v[104:107], v82 offset:34816
	ds_read_b128 v[108:111], v82 offset:35840
	ds_read_b128 v[112:115], v82 offset:36864
	ds_read_b128 v[116:119], v82 offset:37888
	ds_read_b128 v[120:123], v82 offset:38912
	ds_read_b128 v[124:127], v82 offset:39936
	global_load_lds_dwordx4 v[136:137], off
	v_lshl_add_u64 v[136:137], s[22:23], 0, v[68:69]
	s_mov_b32 m0, s31
	s_nop 0
	global_load_lds_dwordx4 v[136:137], off
	s_nop 0
	s_nop 0
	s_waitcnt vmcnt(8)
	s_waitcnt lgkmcnt(0)
	s_barrier
	s_setprio 1
	s_waitcnt lgkmcnt(0)
	v_mfma_f32_16x16x32_bf16 v[62:65], v[78:81], v[96:99], v[62:65]
	v_mfma_f32_16x16x32_bf16 v[58:61], v[88:91], v[96:99], v[58:61]
	v_mfma_f32_16x16x32_bf16 v[54:57], v[78:81], v[104:107], v[54:57]
	v_mfma_f32_16x16x32_bf16 v[50:53], v[88:91], v[104:107], v[50:53]
	v_mfma_f32_16x16x32_bf16 v[46:49], v[78:81], v[112:115], v[46:49]
	v_mfma_f32_16x16x32_bf16 v[42:45], v[88:91], v[112:115], v[42:45]
	v_mfma_f32_16x16x32_bf16 v[38:41], v[78:81], v[120:123], v[38:41]
	v_mfma_f32_16x16x32_bf16 v[34:37], v[88:91], v[120:123], v[34:37]
	v_mfma_f32_16x16x32_bf16 v[62:65], v[84:87], v[100:103], v[62:65]
	v_mfma_f32_16x16x32_bf16 v[58:61], v[92:95], v[100:103], v[58:61]
	v_mfma_f32_16x16x32_bf16 v[54:57], v[84:87], v[108:111], v[54:57]
	v_mfma_f32_16x16x32_bf16 v[50:53], v[92:95], v[108:111], v[50:53]
	v_mfma_f32_16x16x32_bf16 v[46:49], v[84:87], v[116:119], v[46:49]
	v_mfma_f32_16x16x32_bf16 v[42:45], v[92:95], v[116:119], v[42:45]
	v_mfma_f32_16x16x32_bf16 v[38:41], v[84:87], v[124:127], v[38:41]
	v_mfma_f32_16x16x32_bf16 v[34:37], v[92:95], v[124:127], v[34:37]
	s_setprio 0
	s_setprio 1
	s_setprio 0
	s_barrier
	s_add_i32 s22, s49, s25
	v_lshl_add_u64 v[128:129], v[128:129], 0, s[56:57]
	s_mov_b32 m0, s22
	ds_read_b128 v[96:99], v82 offset:49152
	ds_read_b128 v[100:103], v82 offset:50176
	ds_read_b128 v[104:107], v82 offset:51200
	ds_read_b128 v[108:111], v82 offset:52224
	ds_read_b128 v[112:115], v82 offset:53248
	ds_read_b128 v[116:119], v82 offset:54272
	ds_read_b128 v[120:123], v82 offset:55296
	ds_read_b128 v[124:127], v82 offset:56320
	global_load_lds_dwordx4 v[128:129], off
	s_add_i32 m0, s22, 0x2000
	s_add_u32 s20, s20, 0x80080
	v_lshl_add_u64 v[128:129], v[130:131], 0, s[56:57]
	s_addc_u32 s21, s21, 0
	global_load_lds_dwordx4 v[128:129], off
	v_lshl_add_u64 v[128:129], s[20:21], 0, v[70:71]
	s_mov_b32 m0, s38
	s_nop 0
	global_load_lds_dwordx4 v[128:129], off
	v_lshl_add_u64 v[128:129], s[20:21], 0, v[66:67]
	s_mov_b32 m0, s39
	s_nop 0
	global_load_lds_dwordx4 v[128:129], off
	v_lshl_add_u64 v[128:129], v[132:133], 0, s[56:57]
	s_mov_b32 m0, s36
	s_nop 0
	global_load_lds_dwordx4 v[128:129], off
	v_lshl_add_u64 v[128:129], v[134:135], 0, s[56:57]
	s_mov_b32 m0, s37
	s_nop 0
	global_load_lds_dwordx4 v[128:129], off
	s_waitcnt vmcnt(8)
	s_waitcnt lgkmcnt(0)
	s_barrier
	s_setprio 1
	s_waitcnt lgkmcnt(0)
	v_mfma_f32_16x16x32_bf16 v[30:33], v[78:81], v[96:99], v[30:33]
	v_mfma_f32_16x16x32_bf16 v[26:29], v[88:91], v[96:99], v[26:29]
	v_mfma_f32_16x16x32_bf16 v[22:25], v[78:81], v[104:107], v[22:25]
	v_mfma_f32_16x16x32_bf16 v[18:21], v[88:91], v[104:107], v[18:21]
	v_mfma_f32_16x16x32_bf16 v[14:17], v[78:81], v[112:115], v[14:17]
	v_mfma_f32_16x16x32_bf16 v[10:13], v[88:91], v[112:115], v[10:13]
	v_mfma_f32_16x16x32_bf16 v[6:9], v[78:81], v[120:123], v[6:9]
	v_mfma_f32_16x16x32_bf16 v[2:5], v[88:91], v[120:123], v[2:5]
	v_mfma_f32_16x16x32_bf16 v[30:33], v[84:87], v[100:103], v[30:33]
	v_mfma_f32_16x16x32_bf16 v[26:29], v[92:95], v[100:103], v[26:29]
	v_mfma_f32_16x16x32_bf16 v[22:25], v[84:87], v[108:111], v[22:25]
	v_mfma_f32_16x16x32_bf16 v[18:21], v[92:95], v[108:111], v[18:21]
	v_mfma_f32_16x16x32_bf16 v[14:17], v[84:87], v[116:119], v[14:17]
	v_mfma_f32_16x16x32_bf16 v[10:13], v[92:95], v[116:119], v[10:13]
	v_mfma_f32_16x16x32_bf16 v[6:9], v[84:87], v[124:127], v[6:9]
	v_mfma_f32_16x16x32_bf16 v[2:5], v[92:95], v[124:127], v[2:5]
	s_setprio 0
	s_setprio 1
	s_setprio 0
	s_barrier
	s_add_i32 s48, s48, 2
	s_add_u32 s18, s18, 0x100
	s_addc_u32 s19, s19, 0
	s_add_u32 s46, s46, 0x100
	s_addc_u32 s47, s47, 0
	s_cmp_gt_u32 s48, 29
	s_cbranch_scc0 .LBB0_3562
	s_and_b64 vcc, exec, s[6:7]
	s_cbranch_vccz .LBB0_3565
	s_barrier

; #define PG8_STAGE(bufoff, gbase, voff) do { _Pragma("unroll") for (int _i = 0; _i < 2; ++_i) \
;         __builtin_amdgcn_global_load_lds((const unsigned*)((const char*)(gbase) + (voff)[_i]), (LAS unsigned*)(lds + (bufoff) + ldsw + _i * 8192), 16, 0, 0); } while (0)
; #define PG8_LDA(dst, b, h) do { _Pragma("unroll") for (int m = 0; m < 4; ++m) _Pragma("unroll") for (int k = 0; k < 2; ++k) dst[m][k] = *(const LAS bf16x8*)(lds + PG8_SA(b, h) + aoff + m * 2048 + k * 1024); } while (0)
; #define PG8_LDB(dst, b, h) do { _Pragma("unroll") for (int n = 0; n < 2; ++n) _Pragma("unroll") for (int k = 0; k < 2; ++k) dst[n][k] = *(const LAS bf16x8*)(lds + PG8_SB(b, h) + boff + n * 2048 + k * 1024); } while (0)
; #define PG8_MMA(ai, bj, At, Bt) do { __builtin_amdgcn_s_setprio(1); _Pragma("unroll") for (int m = 0; m < 4; ++m) _Pragma("unroll") for (int n = 0; n < 2; ++n) _Pragma("unroll") for (int k = 0; k < 2; ++k) \
;         acc[ai][bj][m][n] = __builtin_amdgcn_mfma_f32_16x16x32_bf16(Bt[n][k], At[m][k], acc[ai][bj][m][n], 0, 0, 0); __builtin_amdgcn_s_setprio(0); } while (0)
; #define PG8_WAIT_V(n) asm volatile("s_waitcnt vmcnt(" #n ")" ::: "memory")
; #define PG8_WAIT_L(n) asm volatile("s_waitcnt lgkmcnt(" #n ")" ::: "memory")
; #define PG8_BAR __builtin_amdgcn_s_barrier()
; #define PG8_SCHED __builtin_amdgcn_sched_barrier(0)
; template <class Epi, class Sched>
; __device__ __forceinline__ void gemm_phase(LAS unsigned char* lds, const Gemm g, const Sched& S, const Epi& E) {
;     ...
;         for (int t = 0; t < nt; t += 2) {
;             const bool last = (t == nt - 2);
;             const char* a1 = cA + (size_t)(t + 1) * kstep;
;             const char* a2 = last ? nA : cA + (size_t)(t + 2) * kstep; const char* b2 = last ? nB : cB + (size_t)(t + 2) * kstep;
;             const char* a3 = a2 + kstep; const char* b3 = b2 + kstep;
;             PG8_LDB(B0, 0, 0); PG8_LDB(B1, 0, 1); PG8_SCHED; PG8_LDA(At, 0, 0); PG8_STAGE(PG8_SA(1, 1), a1 + hstepA, voffA);
;             PG8_WAIT_V(8); PG8_WAIT_L(0); PG8_BAR; PG8_MMA(0, 0, At, B0); PG8_MMA(0, 1, At, B1); PG8_BAR; PG8_SCHED;
;             PG8_LDA(At, 0, 1); PG8_STAGE(PG8_SB(0, 0), b2, voffB); PG8_STAGE(PG8_SB(0, 1), b2 + hstepB, voffB); PG8_STAGE(PG8_SA(0, 0), a2, voffA);
.LBB0_3585:
	s_add_u32 s20, s18, 0xfff80080
	s_addc_u32 s21, s19, -1
	s_add_i32 s49, 0, 0x10000
	s_cmp_eq_u32 s48, 60
	s_cselect_b32 s23, s13, s21
	s_cselect_b32 s22, s44, s20
	s_cselect_b32 s21, s11, s47
	s_cselect_b32 s20, s45, s46
	s_add_i32 s52, 0, 0x14000
	v_add_u32_e32 v46, s49, v1
	v_add_u32_e32 v178, s52, v1
	ds_read_b128 v[26:29], v46
	ds_read_b128 v[30:33], v46 offset:1024
	ds_read_b128 v[42:45], v46 offset:2048
	ds_read_b128 v[46:49], v46 offset:3072
	ds_read_b128 v[174:177], v178
	ds_read_b128 v[182:185], v178 offset:1024
	ds_read_b128 v[186:189], v178 offset:2048
	ds_read_b128 v[190:193], v178 offset:3072
	v_lshl_add_u64 v[178:179], s[18:19], 0, v[170:171]
	s_add_i32 m0, s31, 0xc000
	ds_read_b128 v[208:211], v180
	ds_read_b128 v[212:215], v180 offset:1024
	ds_read_b128 v[216:219], v180 offset:2048
	ds_read_b128 v[220:223], v180 offset:3072
	ds_read_b128 v[224:227], v180 offset:4096
	ds_read_b128 v[228:231], v180 offset:5120
	ds_read_b128 v[232:235], v180 offset:6144
	ds_read_b128 v[236:239], v180 offset:7168
	global_load_lds_dwordx4 v[178:179], off
	v_lshl_add_u64 v[178:179], s[18:19], 0, v[172:173]
	s_add_i32 m0, s31, 0xe000
	s_nop 0
	global_load_lds_dwordx4 v[178:179], off
	s_nop 0
	s_nop 0
	s_nop 0
	s_waitcnt vmcnt(8)
	s_waitcnt lgkmcnt(0)
	s_barrier
	s_setprio 1
	s_waitcnt lgkmcnt(0)
	v_mfma_f32_16x16x32_bf16 v[142:145], v[26:29], v[208:211], v[142:145]
	v_mfma_f32_16x16x32_bf16 v[138:141], v[42:45], v[208:211], v[138:141]
	v_mfma_f32_16x16x32_bf16 v[126:129], v[26:29], v[216:219], v[126:129]
	v_mfma_f32_16x16x32_bf16 v[122:125], v[42:45], v[216:219], v[122:125]
	v_mfma_f32_16x16x32_bf16 v[110:113], v[26:29], v[224:227], v[110:113]
	v_mfma_f32_16x16x32_bf16 v[106:109], v[42:45], v[224:227], v[106:109]
	v_mfma_f32_16x16x32_bf16 v[94:97], v[26:29], v[232:235], v[94:97]
	v_mfma_f32_16x16x32_bf16 v[90:93], v[42:45], v[232:235], v[90:93]
	v_mfma_f32_16x16x32_bf16 v[142:145], v[30:33], v[212:215], v[142:145]
	v_mfma_f32_16x16x32_bf16 v[138:141], v[46:49], v[212:215], v[138:141]
	v_mfma_f32_16x16x32_bf16 v[126:129], v[30:33], v[220:223], v[126:129]
	v_mfma_f32_16x16x32_bf16 v[122:125], v[46:49], v[220:223], v[122:125]
	v_mfma_f32_16x16x32_bf16 v[110:113], v[30:33], v[228:231], v[110:113]
	v_mfma_f32_16x16x32_bf16 v[106:109], v[46:49], v[228:231], v[106:109]
	v_mfma_f32_16x16x32_bf16 v[94:97], v[30:33], v[236:239], v[94:97]
	v_mfma_f32_16x16x32_bf16 v[90:93], v[46:49], v[236:239], v[90:93]
	s_setprio 0
	s_setprio 1
	v_mfma_f32_16x16x32_bf16 v[134:137], v[174:177], v[208:211], v[134:137]
	v_mfma_f32_16x16x32_bf16 v[130:133], v[186:189], v[208:211], v[130:133]
	v_mfma_f32_16x16x32_bf16 v[118:121], v[174:177], v[216:219], v[118:121]
	v_mfma_f32_16x16x32_bf16 v[114:117], v[186:189], v[216:219], v[114:117]
	v_mfma_f32_16x16x32_bf16 v[102:105], v[174:177], v[224:227], v[102:105]
	v_mfma_f32_16x16x32_bf16 v[98:101], v[186:189], v[224:227], v[98:101]
	v_mfma_f32_16x16x32_bf16 v[86:89], v[174:177], v[232:235], v[86:89]
	v_mfma_f32_16x16x32_bf16 v[82:85], v[186:189], v[232:235], v[82:85]
	v_mfma_f32_16x16x32_bf16 v[134:137], v[182:185], v[212:215], v[134:137]
	v_mfma_f32_16x16x32_bf16 v[130:133], v[190:193], v[212:215], v[130:133]
	v_mfma_f32_16x16x32_bf16 v[118:121], v[182:185], v[220:223], v[118:121]
	v_mfma_f32_16x16x32_bf16 v[114:117], v[190:193], v[220:223], v[114:117]
	v_mfma_f32_16x16x32_bf16 v[102:105], v[182:185], v[228:231], v[102:105]
	v_mfma_f32_16x16x32_bf16 v[98:101], v[190:193], v[228:231], v[98:101]
	v_mfma_f32_16x16x32_bf16 v[86:89], v[182:185], v[236:239], v[86:89]
	v_mfma_f32_16x16x32_bf16 v[82:85], v[190:193], v[236:239], v[82:85]
	s_setprio 0
	s_barrier
	s_add_i32 s49, s49, s30
	v_lshl_add_u64 v[178:179], s[20:21], 0, v[164:165]
	s_mov_b32 m0, s49
	ds_read_b128 v[208:211], v180 offset:16384
	ds_read_b128 v[212:215], v180 offset:17408
	ds_read_b128 v[216:219], v180 offset:18432
	ds_read_b128 v[220:223], v180 offset:19456
	ds_read_b128 v[224:227], v180 offset:20480
	ds_read_b128 v[228:231], v180 offset:21504
	ds_read_b128 v[232:235], v180 offset:22528
	ds_read_b128 v[236:239], v180 offset:23552
	global_load_lds_dwordx4 v[178:179], off
	s_add_i32 m0, s49, 0x2000
	s_add_u32 s50, s20, 0x100000
	v_lshl_add_u64 v[240:241], s[20:21], 0, v[168:169]
	s_addc_u32 s51, s21, 0
	s_add_i32 s49, s52, s30
	global_load_lds_dwordx4 v[240:241], off
	v_lshl_add_u64 v[242:243], s[50:51], 0, v[164:165]
	s_mov_b32 m0, s49
	v_lshl_add_u64 v[244:245], s[22:23], 0, v[166:167]
	global_load_lds_dwordx4 v[242:243], off
	v_lshl_add_u64 v[242:243], s[50:51], 0, v[168:169]
	s_add_i32 m0, s49, 0x2000
	s_nop 0
	global_load_lds_dwordx4 v[242:243], off
	v_lshl_add_u64 v[242:243], s[22:23], 0, v[162:163]
	s_mov_b32 m0, s31
	s_nop 0
	global_load_lds_dwordx4 v[242:243], off
	s_mov_b32 m0, s34
	s_nop 0
	global_load_lds_dwordx4 v[244:245], off
	s_nop 0
	s_nop 0
	s_nop 0
	s_waitcnt vmcnt(8)
	s_waitcnt lgkmcnt(0)
	s_barrier
; #define PG8_STAGE(bufoff, gbase, voff) do { _Pragma("unroll") for (int _i = 0; _i < 2; ++_i) \
;         __builtin_amdgcn_global_load_lds((const unsigned*)((const char*)(gbase) + (voff)[_i]), (LAS unsigned*)(lds + (bufoff) + ldsw + _i * 8192), 16, 0, 0); } while (0)
; #define PG8_LDA(dst, b, h) do { _Pragma("unroll") for (int m = 0; m < 4; ++m) _Pragma("unroll") for (int k = 0; k < 2; ++k) dst[m][k] = *(const LAS bf16x8*)(lds + PG8_SA(b, h) + aoff + m * 2048 + k * 1024); } while (0)
; #define PG8_LDB(dst, b, h) do { _Pragma("unroll") for (int n = 0; n < 2; ++n) _Pragma("unroll") for (int k = 0; k < 2; ++k) dst[n][k] = *(const LAS bf16x8*)(lds + PG8_SB(b, h) + boff + n * 2048 + k * 1024); } while (0)
; #define PG8_MMA(ai, bj, At, Bt) do { __builtin_amdgcn_s_setprio(1); _Pragma("unroll") for (int m = 0; m < 4; ++m) _Pragma("unroll") for (int n = 0; n < 2; ++n) _Pragma("unroll") for (int k = 0; k < 2; ++k) \
;         acc[ai][bj][m][n] = __builtin_amdgcn_mfma_f32_16x16x32_bf16(Bt[n][k], At[m][k], acc[ai][bj][m][n], 0, 0, 0); __builtin_amdgcn_s_setprio(0); } while (0)
; #define PG8_WAIT_V(n) asm volatile("s_waitcnt vmcnt(" #n ")" ::: "memory")
; #define PG8_WAIT_L(n) asm volatile("s_waitcnt lgkmcnt(" #n ")" ::: "memory")
; #define PG8_BAR __builtin_amdgcn_s_barrier()
; #define PG8_SCHED __builtin_amdgcn_sched_barrier(0)
; template <class Epi, class Sched>
; __device__ __forceinline__ void gemm_phase(LAS unsigned char* lds, const Gemm g, const Sched& S, const Epi& E) {
;     ...
;             PG8_WAIT_V(8); PG8_WAIT_L(0); PG8_BAR; PG8_MMA(1, 0, At, B0); PG8_MMA(1, 1, At, B1); PG8_BAR; PG8_SCHED;
;             PG8_LDB(B0, 1, 0); PG8_LDB(B1, 1, 1); PG8_SCHED; PG8_LDA(At, 1, 0); PG8_STAGE(PG8_SA(0, 1), a2 + hstepA, voffA);
;             PG8_WAIT_V(8); PG8_WAIT_L(0); PG8_BAR; PG8_MMA(0, 0, At, B0); PG8_MMA(0, 1, At, B1); PG8_BAR; PG8_SCHED;
	s_setprio 1
	s_waitcnt lgkmcnt(0)
	v_mfma_f32_16x16x32_bf16 v[78:81], v[26:29], v[208:211], v[78:81]
	v_mfma_f32_16x16x32_bf16 v[74:77], v[42:45], v[208:211], v[74:77]
	v_mfma_f32_16x16x32_bf16 v[62:65], v[26:29], v[216:219], v[62:65]
	v_mfma_f32_16x16x32_bf16 v[58:61], v[42:45], v[216:219], v[58:61]
	v_mfma_f32_16x16x32_bf16 v[38:41], v[26:29], v[224:227], v[38:41]
	v_mfma_f32_16x16x32_bf16 v[34:37], v[42:45], v[224:227], v[34:37]
	v_mfma_f32_16x16x32_bf16 v[14:17], v[26:29], v[232:235], v[14:17]
	v_mfma_f32_16x16x32_bf16 v[10:13], v[42:45], v[232:235], v[10:13]
	v_mfma_f32_16x16x32_bf16 v[78:81], v[30:33], v[212:215], v[78:81]
	v_mfma_f32_16x16x32_bf16 v[74:77], v[46:49], v[212:215], v[74:77]
	v_mfma_f32_16x16x32_bf16 v[62:65], v[30:33], v[220:223], v[62:65]
	v_mfma_f32_16x16x32_bf16 v[58:61], v[46:49], v[220:223], v[58:61]
	v_mfma_f32_16x16x32_bf16 v[38:41], v[30:33], v[228:231], v[38:41]
	v_mfma_f32_16x16x32_bf16 v[34:37], v[46:49], v[228:231], v[34:37]
	v_mfma_f32_16x16x32_bf16 v[14:17], v[30:33], v[236:239], v[14:17]
	v_mfma_f32_16x16x32_bf16 v[10:13], v[46:49], v[236:239], v[10:13]
	s_setprio 0
	s_setprio 1
	v_mfma_f32_16x16x32_bf16 v[22:25], v[174:177], v[224:227], v[22:25]
	v_mfma_f32_16x16x32_bf16 v[18:21], v[186:189], v[224:227], v[18:21]
	v_mfma_f32_16x16x32_bf16 v[6:9], v[174:177], v[232:235], v[6:9]
	v_mfma_f32_16x16x32_bf16 v[2:5], v[186:189], v[232:235], v[2:5]
	v_mfma_f32_16x16x32_bf16 v[26:29], v[174:177], v[208:211], v[70:73]
	v_mfma_f32_16x16x32_bf16 v[30:33], v[186:189], v[208:211], v[66:69]
	v_mfma_f32_16x16x32_bf16 v[42:45], v[174:177], v[216:219], v[54:57]
	v_mfma_f32_16x16x32_bf16 v[46:49], v[186:189], v[216:219], v[50:53]
	v_mfma_f32_16x16x32_bf16 v[22:25], v[182:185], v[228:231], v[22:25]
	v_mfma_f32_16x16x32_bf16 v[18:21], v[190:193], v[228:231], v[18:21]
	v_mfma_f32_16x16x32_bf16 v[6:9], v[182:185], v[236:239], v[6:9]
	v_mfma_f32_16x16x32_bf16 v[2:5], v[190:193], v[236:239], v[2:5]
	v_mfma_f32_16x16x32_bf16 v[26:29], v[182:185], v[212:215], v[26:29]
	v_mfma_f32_16x16x32_bf16 v[30:33], v[190:193], v[212:215], v[30:33]
	v_mfma_f32_16x16x32_bf16 v[42:45], v[182:185], v[220:223], v[42:45]
	v_mfma_f32_16x16x32_bf16 v[46:49], v[190:193], v[220:223], v[46:49]
	s_setprio 0
	s_barrier
	s_add_i32 s49, 0, 0x18000
	s_add_i32 s50, 0, 0x1c000
	v_add_u32_e32 v70, s49, v1
	v_add_u32_e32 v181, s50, v1
	ds_read_b128 v[50:53], v70
	ds_read_b128 v[54:57], v70 offset:1024
	ds_read_b128 v[66:69], v70 offset:2048
	ds_read_b128 v[70:73], v70 offset:3072
	ds_read_b128 v[174:177], v181
	ds_read_b128 v[182:185], v181 offset:1024
	ds_read_b128 v[186:189], v181 offset:2048
	ds_read_b128 v[190:193], v181 offset:3072
	s_add_u32 s22, s22, 0x80000
	s_addc_u32 s23, s23, 0
	s_mov_b32 m0, s35
	v_lshl_add_u64 v[246:247], s[22:23], 0, v[162:163]
	ds_read_b128 v[208:211], v180 offset:32768
	ds_read_b128 v[212:215], v180 offset:33792
	ds_read_b128 v[216:219], v180 offset:34816
	ds_read_b128 v[220:223], v180 offset:35840
	ds_read_b128 v[224:227], v180 offset:36864
	ds_read_b128 v[228:231], v180 offset:37888
	ds_read_b128 v[232:235], v180 offset:38912
	ds_read_b128 v[236:239], v180 offset:39936
	global_load_lds_dwordx4 v[246:247], off
	v_lshl_add_u64 v[246:247], s[22:23], 0, v[166:167]
	s_mov_b32 m0, s36
	s_nop 0
	global_load_lds_dwordx4 v[246:247], off
	s_nop 0
	s_nop 0
	s_nop 0
	s_waitcnt vmcnt(8)
	s_waitcnt lgkmcnt(0)
	s_barrier
	s_setprio 1
	s_waitcnt lgkmcnt(0)
	v_mfma_f32_16x16x32_bf16 v[142:145], v[50:53], v[208:211], v[142:145]
	v_mfma_f32_16x16x32_bf16 v[138:141], v[66:69], v[208:211], v[138:141]
	v_mfma_f32_16x16x32_bf16 v[126:129], v[50:53], v[216:219], v[126:129]
	v_mfma_f32_16x16x32_bf16 v[122:125], v[66:69], v[216:219], v[122:125]
	v_mfma_f32_16x16x32_bf16 v[110:113], v[50:53], v[224:227], v[110:113]
	v_mfma_f32_16x16x32_bf16 v[106:109], v[66:69], v[224:227], v[106:109]
	v_mfma_f32_16x16x32_bf16 v[94:97], v[50:53], v[232:235], v[94:97]
	v_mfma_f32_16x16x32_bf16 v[90:93], v[66:69], v[232:235], v[90:93]
	v_mfma_f32_16x16x32_bf16 v[142:145], v[54:57], v[212:215], v[142:145]
	v_mfma_f32_16x16x32_bf16 v[138:141], v[70:73], v[212:215], v[138:141]
	v_mfma_f32_16x16x32_bf16 v[126:129], v[54:57], v[220:223], v[126:129]
	v_mfma_f32_16x16x32_bf16 v[122:125], v[70:73], v[220:223], v[122:125]
	v_mfma_f32_16x16x32_bf16 v[110:113], v[54:57], v[228:231], v[110:113]
	v_mfma_f32_16x16x32_bf16 v[106:109], v[70:73], v[228:231], v[106:109]
	v_mfma_f32_16x16x32_bf16 v[94:97], v[54:57], v[236:239], v[94:97]
	v_mfma_f32_16x16x32_bf16 v[90:93], v[70:73], v[236:239], v[90:93]
	s_setprio 0
	s_setprio 1
	v_mfma_f32_16x16x32_bf16 v[134:137], v[174:177], v[208:211], v[134:137]
	v_mfma_f32_16x16x32_bf16 v[130:133], v[186:189], v[208:211], v[130:133]
	v_mfma_f32_16x16x32_bf16 v[118:121], v[174:177], v[216:219], v[118:121]
	v_mfma_f32_16x16x32_bf16 v[114:117], v[186:189], v[216:219], v[114:117]
	v_mfma_f32_16x16x32_bf16 v[102:105], v[174:177], v[224:227], v[102:105]
	v_mfma_f32_16x16x32_bf16 v[98:101], v[186:189], v[224:227], v[98:101]
	v_mfma_f32_16x16x32_bf16 v[86:89], v[174:177], v[232:235], v[86:89]
	v_mfma_f32_16x16x32_bf16 v[82:85], v[186:189], v[232:235], v[82:85]
	v_mfma_f32_16x16x32_bf16 v[134:137], v[182:185], v[212:215], v[134:137]
	v_mfma_f32_16x16x32_bf16 v[130:133], v[190:193], v[212:215], v[130:133]
	v_mfma_f32_16x16x32_bf16 v[118:121], v[182:185], v[220:223], v[118:121]
	v_mfma_f32_16x16x32_bf16 v[114:117], v[190:193], v[220:223], v[114:117]
	v_mfma_f32_16x16x32_bf16 v[102:105], v[182:185], v[228:231], v[102:105]
	v_mfma_f32_16x16x32_bf16 v[98:101], v[190:193], v[228:231], v[98:101]
	v_mfma_f32_16x16x32_bf16 v[86:89], v[182:185], v[236:239], v[86:89]
	v_mfma_f32_16x16x32_bf16 v[82:85], v[190:193], v[236:239], v[82:85]
	s_setprio 0
	s_barrier
; #define PG8_STAGE(bufoff, gbase, voff) do { _Pragma("unroll") for (int _i = 0; _i < 2; ++_i) \
;         __builtin_amdgcn_global_load_lds((const unsigned*)((const char*)(gbase) + (voff)[_i]), (LAS unsigned*)(lds + (bufoff) + ldsw + _i * 8192), 16, 0, 0); } while (0)
; #define PG8_LDA(dst, b, h) do { _Pragma("unroll") for (int m = 0; m < 4; ++m) _Pragma("unroll") for (int k = 0; k < 2; ++k) dst[m][k] = *(const LAS bf16x8*)(lds + PG8_SA(b, h) + aoff + m * 2048 + k * 1024); } while (0)
; #define PG8_MMA(ai, bj, At, Bt) do { __builtin_amdgcn_s_setprio(1); _Pragma("unroll") for (int m = 0; m < 4; ++m) _Pragma("unroll") for (int n = 0; n < 2; ++n) _Pragma("unroll") for (int k = 0; k < 2; ++k) \
;         acc[ai][bj][m][n] = __builtin_amdgcn_mfma_f32_16x16x32_bf16(Bt[n][k], At[m][k], acc[ai][bj][m][n], 0, 0, 0); __builtin_amdgcn_s_setprio(0); } while (0)
; #define PG8_WAIT_V(n) asm volatile("s_waitcnt vmcnt(" #n ")" ::: "memory")
; #define PG8_WAIT_L(n) asm volatile("s_waitcnt lgkmcnt(" #n ")" ::: "memory")
; #define PG8_BAR __builtin_amdgcn_s_barrier()
; #define PG8_SCHED __builtin_amdgcn_sched_barrier(0)
; template <class Epi, class Sched>
; __device__ __forceinline__ void gemm_phase(LAS unsigned char* lds, const Gemm g, const Sched& S, const Epi& E) {
;     ...
;             PG8_LDA(At, 1, 1); PG8_STAGE(PG8_SB(1, 0), b3, voffB); PG8_STAGE(PG8_SB(1, 1), b3 + hstepB, voffB); PG8_STAGE(PG8_SA(1, 0), a3, voffA);
;             PG8_WAIT_V(8); PG8_WAIT_L(0); PG8_BAR; PG8_MMA(1, 0, At, B0); PG8_MMA(1, 1, At, B1); PG8_BAR; PG8_SCHED;
;         }
;         if (wr == 0) PG8_BAR;
	s_add_i32 s22, s49, s30
	v_lshl_add_u64 v[178:179], v[178:179], 0, s[56:57]
	s_mov_b32 m0, s22
	ds_read_b128 v[208:211], v180 offset:49152
	ds_read_b128 v[212:215], v180 offset:50176
	ds_read_b128 v[216:219], v180 offset:51200
	ds_read_b128 v[220:223], v180 offset:52224
	ds_read_b128 v[224:227], v180 offset:53248
	ds_read_b128 v[228:231], v180 offset:54272
	ds_read_b128 v[232:235], v180 offset:55296
	ds_read_b128 v[236:239], v180 offset:56320
	global_load_lds_dwordx4 v[178:179], off
	s_add_i32 m0, s22, 0x2000
	s_add_u32 s20, s20, 0x100080
	v_lshl_add_u64 v[178:179], v[240:241], 0, s[56:57]
	s_addc_u32 s21, s21, 0
	s_add_i32 s22, s50, s30
	global_load_lds_dwordx4 v[178:179], off
	v_lshl_add_u64 v[178:179], s[20:21], 0, v[164:165]
	s_mov_b32 m0, s22
	s_nop 0
	global_load_lds_dwordx4 v[178:179], off
	v_lshl_add_u64 v[178:179], s[20:21], 0, v[168:169]
	s_add_i32 m0, s22, 0x2000
	s_nop 0
	global_load_lds_dwordx4 v[178:179], off
	v_lshl_add_u64 v[178:179], v[242:243], 0, s[56:57]
	s_mov_b32 m0, s39
	s_nop 0
	global_load_lds_dwordx4 v[178:179], off
	v_lshl_add_u64 v[178:179], v[244:245], 0, s[56:57]
	s_mov_b32 m0, s40
	s_nop 0
	global_load_lds_dwordx4 v[178:179], off
	s_nop 0
	s_nop 0
	s_waitcnt vmcnt(8)
	s_waitcnt lgkmcnt(0)
	s_barrier
	s_setprio 1
	s_waitcnt lgkmcnt(0)
	v_mfma_f32_16x16x32_bf16 v[78:81], v[50:53], v[208:211], v[78:81]
	v_mfma_f32_16x16x32_bf16 v[74:77], v[66:69], v[208:211], v[74:77]
	v_mfma_f32_16x16x32_bf16 v[62:65], v[50:53], v[216:219], v[62:65]
	v_mfma_f32_16x16x32_bf16 v[58:61], v[66:69], v[216:219], v[58:61]
	v_mfma_f32_16x16x32_bf16 v[38:41], v[50:53], v[224:227], v[38:41]
	v_mfma_f32_16x16x32_bf16 v[34:37], v[66:69], v[224:227], v[34:37]
	v_mfma_f32_16x16x32_bf16 v[14:17], v[50:53], v[232:235], v[14:17]
	v_mfma_f32_16x16x32_bf16 v[10:13], v[66:69], v[232:235], v[10:13]
	v_mfma_f32_16x16x32_bf16 v[78:81], v[54:57], v[212:215], v[78:81]
	v_mfma_f32_16x16x32_bf16 v[74:77], v[70:73], v[212:215], v[74:77]
	v_mfma_f32_16x16x32_bf16 v[62:65], v[54:57], v[220:223], v[62:65]
	v_mfma_f32_16x16x32_bf16 v[58:61], v[70:73], v[220:223], v[58:61]
	v_mfma_f32_16x16x32_bf16 v[38:41], v[54:57], v[228:231], v[38:41]
	v_mfma_f32_16x16x32_bf16 v[34:37], v[70:73], v[228:231], v[34:37]
	v_mfma_f32_16x16x32_bf16 v[14:17], v[54:57], v[236:239], v[14:17]
	v_mfma_f32_16x16x32_bf16 v[10:13], v[70:73], v[236:239], v[10:13]
	s_setprio 0
	s_setprio 1
	v_mfma_f32_16x16x32_bf16 v[26:29], v[174:177], v[208:211], v[26:29]
	v_mfma_f32_16x16x32_bf16 v[70:73], v[182:185], v[212:215], v[26:29]
	v_mfma_f32_16x16x32_bf16 v[26:29], v[186:189], v[208:211], v[30:33]
	v_mfma_f32_16x16x32_bf16 v[66:69], v[190:193], v[212:215], v[26:29]
	v_mfma_f32_16x16x32_bf16 v[26:29], v[174:177], v[216:219], v[42:45]
	v_mfma_f32_16x16x32_bf16 v[54:57], v[182:185], v[220:223], v[26:29]
	v_mfma_f32_16x16x32_bf16 v[26:29], v[186:189], v[216:219], v[46:49]
	v_mfma_f32_16x16x32_bf16 v[22:25], v[174:177], v[224:227], v[22:25]
	v_mfma_f32_16x16x32_bf16 v[18:21], v[186:189], v[224:227], v[18:21]
	v_mfma_f32_16x16x32_bf16 v[6:9], v[174:177], v[232:235], v[6:9]
	v_mfma_f32_16x16x32_bf16 v[2:5], v[186:189], v[232:235], v[2:5]
	v_mfma_f32_16x16x32_bf16 v[50:53], v[190:193], v[220:223], v[26:29]
	v_mfma_f32_16x16x32_bf16 v[22:25], v[182:185], v[228:231], v[22:25]
	v_mfma_f32_16x16x32_bf16 v[18:21], v[190:193], v[228:231], v[18:21]
	v_mfma_f32_16x16x32_bf16 v[6:9], v[182:185], v[236:239], v[6:9]
	v_mfma_f32_16x16x32_bf16 v[2:5], v[190:193], v[236:239], v[2:5]
	s_setprio 0
	s_barrier
	s_add_i32 s48, s48, 2
	s_add_u32 s18, s18, 0x100
	s_addc_u32 s19, s19, 0
	s_add_u32 s46, s46, 0x100
	s_addc_u32 s47, s47, 0
	s_cmp_gt_u32 s48, 61
	s_cbranch_scc0 .LBB0_3585
	s_and_b64 vcc, exec, s[6:7]
	s_cbranch_vccz .LBB0_3588
	s_barrier

; #define PG8_STAGE(bufoff, gbase, voff) do { _Pragma("unroll") for (int _i = 0; _i < 2; ++_i) \
;         __builtin_amdgcn_global_load_lds((const unsigned*)((const char*)(gbase) + (voff)[_i]), (LAS unsigned*)(lds + (bufoff) + ldsw + _i * 8192), 16, 0, 0); } while (0)
; #define PG8_LDA(dst, b, h) do { _Pragma("unroll") for (int m = 0; m < 4; ++m) _Pragma("unroll") for (int k = 0; k < 2; ++k) dst[m][k] = *(const LAS bf16x8*)(lds + PG8_SA(b, h) + aoff + m * 2048 + k * 1024); } while (0)
; #define PG8_LDB(dst, b, h) do { _Pragma("unroll") for (int n = 0; n < 2; ++n) _Pragma("unroll") for (int k = 0; k < 2; ++k) dst[n][k] = *(const LAS bf16x8*)(lds + PG8_SB(b, h) + boff + n * 2048 + k * 1024); } while (0)
; #define PG8_MMA(ai, bj, At, Bt) do { __builtin_amdgcn_s_setprio(1); _Pragma("unroll") for (int m = 0; m < 4; ++m) _Pragma("unroll") for (int n = 0; n < 2; ++n) _Pragma("unroll") for (int k = 0; k < 2; ++k) \
;         acc[ai][bj][m][n] = __builtin_amdgcn_mfma_f32_16x16x32_bf16(Bt[n][k], At[m][k], acc[ai][bj][m][n], 0, 0, 0); __builtin_amdgcn_s_setprio(0); } while (0)
; #define PG8_WAIT_V(n) asm volatile("s_waitcnt vmcnt(" #n ")" ::: "memory")
; #define PG8_WAIT_L(n) asm volatile("s_waitcnt lgkmcnt(" #n ")" ::: "memory")
; #define PG8_BAR __builtin_amdgcn_s_barrier()
; #define PG8_SCHED __builtin_amdgcn_sched_barrier(0)
; template <class Epi, class Sched>
; __device__ __forceinline__ void gemm_phase(LAS unsigned char* lds, const Gemm g, const Sched& S, const Epi& E) {
;     ...
;         for (int t = 0; t < nt; t += 2) {
;             const bool last = (t == nt - 2);
;             const char* a1 = cA + (size_t)(t + 1) * kstep;
;             const char* a2 = last ? nA : cA + (size_t)(t + 2) * kstep; const char* b2 = last ? nB : cB + (size_t)(t + 2) * kstep;
;             const char* a3 = a2 + kstep; const char* b3 = b2 + kstep;
;             PG8_LDB(B0, 0, 0); PG8_LDB(B1, 0, 1); PG8_SCHED; PG8_LDA(At, 0, 0); PG8_STAGE(PG8_SA(1, 1), a1 + hstepA, voffA);
;             PG8_WAIT_V(8); PG8_WAIT_L(0); PG8_BAR; PG8_MMA(0, 0, At, B0); PG8_MMA(0, 1, At, B1); PG8_BAR; PG8_SCHED;
;             PG8_LDA(At, 0, 1); PG8_STAGE(PG8_SB(0, 0), b2, voffB); PG8_STAGE(PG8_SB(0, 1), b2 + hstepB, voffB); PG8_STAGE(PG8_SA(0, 0), a2, voffA);
;             PG8_WAIT_V(8); PG8_WAIT_L(0); PG8_BAR; PG8_MMA(1, 0, At, B0); PG8_MMA(1, 1, At, B1); PG8_BAR; PG8_SCHED;
.LBB0_3676:
	s_add_u32 s20, s18, 0xfffe0080
	s_addc_u32 s21, s19, -1
	s_add_i32 s50, 0, 0x10000
	v_add_u32_e32 v79, s50, v1
	ds_read_b128 v[80:83], v79
	ds_read_b128 v[84:87], v79 offset:1024
	ds_read_b128 v[88:91], v79 offset:2048
	ds_read_b128 v[92:95], v79 offset:3072
	s_cmp_eq_u32 s49, 4
	s_cselect_b32 s23, s13, s21
	s_cselect_b32 s22, s45, s20
	s_cselect_b32 s21, s11, s48
	s_cselect_b32 s20, s46, s47
	v_lshl_add_u64 v[128:129], s[18:19], 0, v[74:75]
	s_add_i32 m0, s29, 0xc000
	ds_read_b128 v[96:99], v78
	ds_read_b128 v[100:103], v78 offset:1024
	ds_read_b128 v[104:107], v78 offset:2048
	ds_read_b128 v[108:111], v78 offset:3072
	ds_read_b128 v[112:115], v78 offset:4096
	ds_read_b128 v[116:119], v78 offset:5120
	ds_read_b128 v[120:123], v78 offset:6144
	ds_read_b128 v[124:127], v78 offset:7168
	global_load_lds_dwordx4 v[128:129], off
	v_lshl_add_u64 v[128:129], s[18:19], 0, v[76:77]
	s_add_i32 m0, s29, 0xe000
	s_nop 0
	global_load_lds_dwordx4 v[128:129], off
	s_nop 0
	s_nop 0
	s_waitcnt vmcnt(8)
	s_waitcnt lgkmcnt(0)
	s_barrier
	s_setprio 1
	s_waitcnt lgkmcnt(0)
	v_mfma_f32_16x16x32_bf16 v[62:65], v[80:83], v[96:99], v[62:65]
	v_mfma_f32_16x16x32_bf16 v[58:61], v[88:91], v[96:99], v[58:61]
	v_mfma_f32_16x16x32_bf16 v[54:57], v[80:83], v[104:107], v[54:57]
	v_mfma_f32_16x16x32_bf16 v[50:53], v[88:91], v[104:107], v[50:53]
	v_mfma_f32_16x16x32_bf16 v[46:49], v[80:83], v[112:115], v[46:49]
	v_mfma_f32_16x16x32_bf16 v[42:45], v[88:91], v[112:115], v[42:45]
	v_mfma_f32_16x16x32_bf16 v[38:41], v[80:83], v[120:123], v[38:41]
	v_mfma_f32_16x16x32_bf16 v[34:37], v[88:91], v[120:123], v[34:37]
	v_mfma_f32_16x16x32_bf16 v[62:65], v[84:87], v[100:103], v[62:65]
	v_mfma_f32_16x16x32_bf16 v[58:61], v[92:95], v[100:103], v[58:61]
	v_mfma_f32_16x16x32_bf16 v[54:57], v[84:87], v[108:111], v[54:57]
	v_mfma_f32_16x16x32_bf16 v[50:53], v[92:95], v[108:111], v[50:53]
	v_mfma_f32_16x16x32_bf16 v[46:49], v[84:87], v[116:119], v[46:49]
	v_mfma_f32_16x16x32_bf16 v[42:45], v[92:95], v[116:119], v[42:45]
	v_mfma_f32_16x16x32_bf16 v[38:41], v[84:87], v[124:127], v[38:41]
	v_mfma_f32_16x16x32_bf16 v[34:37], v[92:95], v[124:127], v[34:37]
	s_setprio 0
	s_setprio 1
	s_setprio 0
	s_barrier
	s_add_i32 s50, s50, s28
	v_lshl_add_u64 v[128:129], s[20:21], 0, v[70:71]
	s_mov_b32 m0, s50
	ds_read_b128 v[96:99], v78 offset:16384
	ds_read_b128 v[100:103], v78 offset:17408
	ds_read_b128 v[104:107], v78 offset:18432
	ds_read_b128 v[108:111], v78 offset:19456
	ds_read_b128 v[112:115], v78 offset:20480
	ds_read_b128 v[116:119], v78 offset:21504
	ds_read_b128 v[120:123], v78 offset:22528
	ds_read_b128 v[124:127], v78 offset:23552
	global_load_lds_dwordx4 v[128:129], off
	s_add_i32 m0, s50, 0x2000
	s_add_u32 s50, s20, 0x20000
	v_lshl_add_u64 v[130:131], s[20:21], 0, v[66:67]
	s_addc_u32 s51, s21, 0
	global_load_lds_dwordx4 v[130:131], off
	v_lshl_add_u64 v[132:133], s[50:51], 0, v[70:71]
	s_mov_b32 m0, s30
	v_lshl_add_u64 v[134:135], s[22:23], 0, v[68:69]
	global_load_lds_dwordx4 v[132:133], off
	v_lshl_add_u64 v[132:133], s[50:51], 0, v[66:67]
	s_mov_b32 m0, s31
	s_nop 0
	global_load_lds_dwordx4 v[132:133], off
	v_lshl_add_u64 v[132:133], s[22:23], 0, v[72:73]
	s_mov_b32 m0, s29
	s_nop 0
	global_load_lds_dwordx4 v[132:133], off
	s_mov_b32 m0, s33
	s_nop 0
	global_load_lds_dwordx4 v[134:135], off
	s_nop 0
	s_waitcnt vmcnt(8)
	s_waitcnt lgkmcnt(0)
	s_barrier
	s_setprio 1
	s_waitcnt lgkmcnt(0)
	v_mfma_f32_16x16x32_bf16 v[30:33], v[80:83], v[96:99], v[30:33]
	v_mfma_f32_16x16x32_bf16 v[26:29], v[88:91], v[96:99], v[26:29]
	v_mfma_f32_16x16x32_bf16 v[22:25], v[80:83], v[104:107], v[22:25]
	v_mfma_f32_16x16x32_bf16 v[18:21], v[88:91], v[104:107], v[18:21]
	v_mfma_f32_16x16x32_bf16 v[14:17], v[80:83], v[112:115], v[14:17]
	v_mfma_f32_16x16x32_bf16 v[10:13], v[88:91], v[112:115], v[10:13]
	v_mfma_f32_16x16x32_bf16 v[6:9], v[80:83], v[120:123], v[6:9]
	v_mfma_f32_16x16x32_bf16 v[2:5], v[88:91], v[120:123], v[2:5]
	v_mfma_f32_16x16x32_bf16 v[30:33], v[84:87], v[100:103], v[30:33]
	v_mfma_f32_16x16x32_bf16 v[26:29], v[92:95], v[100:103], v[26:29]
	v_mfma_f32_16x16x32_bf16 v[22:25], v[84:87], v[108:111], v[22:25]
	v_mfma_f32_16x16x32_bf16 v[18:21], v[92:95], v[108:111], v[18:21]
	v_mfma_f32_16x16x32_bf16 v[14:17], v[84:87], v[116:119], v[14:17]
	v_mfma_f32_16x16x32_bf16 v[10:13], v[92:95], v[116:119], v[10:13]
	v_mfma_f32_16x16x32_bf16 v[6:9], v[84:87], v[124:127], v[6:9]
	v_mfma_f32_16x16x32_bf16 v[2:5], v[92:95], v[124:127], v[2:5]
	s_setprio 0
	s_setprio 1
	s_setprio 0
	s_barrier
; #define PG8_STAGE(bufoff, gbase, voff) do { _Pragma("unroll") for (int _i = 0; _i < 2; ++_i) \
;         __builtin_amdgcn_global_load_lds((const unsigned*)((const char*)(gbase) + (voff)[_i]), (LAS unsigned*)(lds + (bufoff) + ldsw + _i * 8192), 16, 0, 0); } while (0)
; #define PG8_LDA(dst, b, h) do { _Pragma("unroll") for (int m = 0; m < 4; ++m) _Pragma("unroll") for (int k = 0; k < 2; ++k) dst[m][k] = *(const LAS bf16x8*)(lds + PG8_SA(b, h) + aoff + m * 2048 + k * 1024); } while (0)
; #define PG8_LDB(dst, b, h) do { _Pragma("unroll") for (int n = 0; n < 2; ++n) _Pragma("unroll") for (int k = 0; k < 2; ++k) dst[n][k] = *(const LAS bf16x8*)(lds + PG8_SB(b, h) + boff + n * 2048 + k * 1024); } while (0)
; #define PG8_MMA(ai, bj, At, Bt) do { __builtin_amdgcn_s_setprio(1); _Pragma("unroll") for (int m = 0; m < 4; ++m) _Pragma("unroll") for (int n = 0; n < 2; ++n) _Pragma("unroll") for (int k = 0; k < 2; ++k) \
;         acc[ai][bj][m][n] = __builtin_amdgcn_mfma_f32_16x16x32_bf16(Bt[n][k], At[m][k], acc[ai][bj][m][n], 0, 0, 0); __builtin_amdgcn_s_setprio(0); } while (0)
; #define PG8_WAIT_V(n) asm volatile("s_waitcnt vmcnt(" #n ")" ::: "memory")
; #define PG8_WAIT_L(n) asm volatile("s_waitcnt lgkmcnt(" #n ")" ::: "memory")
; #define PG8_BAR __builtin_amdgcn_s_barrier()
; #define PG8_SCHED __builtin_amdgcn_sched_barrier(0)
; template <class Epi, class Sched>
; __device__ __forceinline__ void gemm_phase(LAS unsigned char* lds, const Gemm g, const Sched& S, const Epi& E) {
;     ...
;             PG8_LDB(B0, 1, 0); PG8_LDB(B1, 1, 1); PG8_SCHED; PG8_LDA(At, 1, 0); PG8_STAGE(PG8_SA(0, 1), a2 + hstepA, voffA);
;             PG8_WAIT_V(8); PG8_WAIT_L(0); PG8_BAR; PG8_MMA(0, 0, At, B0); PG8_MMA(0, 1, At, B1); PG8_BAR; PG8_SCHED;
;             PG8_LDA(At, 1, 1); PG8_STAGE(PG8_SB(1, 0), b3, voffB); PG8_STAGE(PG8_SB(1, 1), b3 + hstepB, voffB); PG8_STAGE(PG8_SA(1, 0), a3, voffA);
;             PG8_WAIT_V(8); PG8_WAIT_L(0); PG8_BAR; PG8_MMA(1, 0, At, B0); PG8_MMA(1, 1, At, B1); PG8_BAR; PG8_SCHED;
;         }
;         if (wr == 0) PG8_BAR;
	s_add_i32 s50, 0, 0x18000
	v_add_u32_e32 v79, s50, v1
	ds_read_b128 v[80:83], v79
	ds_read_b128 v[84:87], v79 offset:1024
	ds_read_b128 v[88:91], v79 offset:2048
	ds_read_b128 v[92:95], v79 offset:3072
	s_add_u32 s22, s22, 0x20000
	s_addc_u32 s23, s23, 0
	s_mov_b32 m0, s34
	v_lshl_add_u64 v[136:137], s[22:23], 0, v[72:73]
	ds_read_b128 v[96:99], v78 offset:32768
	ds_read_b128 v[100:103], v78 offset:33792
	ds_read_b128 v[104:107], v78 offset:34816
	ds_read_b128 v[108:111], v78 offset:35840
	ds_read_b128 v[112:115], v78 offset:36864
	ds_read_b128 v[116:119], v78 offset:37888
	ds_read_b128 v[120:123], v78 offset:38912
	ds_read_b128 v[124:127], v78 offset:39936
	global_load_lds_dwordx4 v[136:137], off
	v_lshl_add_u64 v[136:137], s[22:23], 0, v[68:69]
	s_mov_b32 m0, s35
	s_nop 0
	global_load_lds_dwordx4 v[136:137], off
	s_nop 0
	s_nop 0
	s_waitcnt vmcnt(8)
	s_waitcnt lgkmcnt(0)
	s_barrier
	s_setprio 1
	s_waitcnt lgkmcnt(0)
	v_mfma_f32_16x16x32_bf16 v[62:65], v[80:83], v[96:99], v[62:65]
	v_mfma_f32_16x16x32_bf16 v[58:61], v[88:91], v[96:99], v[58:61]
	v_mfma_f32_16x16x32_bf16 v[54:57], v[80:83], v[104:107], v[54:57]
	v_mfma_f32_16x16x32_bf16 v[50:53], v[88:91], v[104:107], v[50:53]
	v_mfma_f32_16x16x32_bf16 v[46:49], v[80:83], v[112:115], v[46:49]
	v_mfma_f32_16x16x32_bf16 v[42:45], v[88:91], v[112:115], v[42:45]
	v_mfma_f32_16x16x32_bf16 v[38:41], v[80:83], v[120:123], v[38:41]
	v_mfma_f32_16x16x32_bf16 v[34:37], v[88:91], v[120:123], v[34:37]
	v_mfma_f32_16x16x32_bf16 v[62:65], v[84:87], v[100:103], v[62:65]
	v_mfma_f32_16x16x32_bf16 v[58:61], v[92:95], v[100:103], v[58:61]
	v_mfma_f32_16x16x32_bf16 v[54:57], v[84:87], v[108:111], v[54:57]
	v_mfma_f32_16x16x32_bf16 v[50:53], v[92:95], v[108:111], v[50:53]
	v_mfma_f32_16x16x32_bf16 v[46:49], v[84:87], v[116:119], v[46:49]
	v_mfma_f32_16x16x32_bf16 v[42:45], v[92:95], v[116:119], v[42:45]
	v_mfma_f32_16x16x32_bf16 v[38:41], v[84:87], v[124:127], v[38:41]
	v_mfma_f32_16x16x32_bf16 v[34:37], v[92:95], v[124:127], v[34:37]
	s_setprio 0
	s_setprio 1
	s_setprio 0
	s_barrier
	s_add_i32 s22, s50, s28
	v_lshl_add_u64 v[128:129], v[128:129], 0, s[56:57]
	s_mov_b32 m0, s22
	ds_read_b128 v[96:99], v78 offset:49152
	ds_read_b128 v[100:103], v78 offset:50176
	ds_read_b128 v[104:107], v78 offset:51200
	ds_read_b128 v[108:111], v78 offset:52224
	ds_read_b128 v[112:115], v78 offset:53248
	ds_read_b128 v[116:119], v78 offset:54272
	ds_read_b128 v[120:123], v78 offset:55296
	ds_read_b128 v[124:127], v78 offset:56320
	global_load_lds_dwordx4 v[128:129], off
	s_add_i32 m0, s22, 0x2000
	s_add_u32 s20, s20, 0x20080
	v_lshl_add_u64 v[128:129], v[130:131], 0, s[56:57]
	s_addc_u32 s21, s21, 0
	global_load_lds_dwordx4 v[128:129], off
	v_lshl_add_u64 v[128:129], s[20:21], 0, v[70:71]
	s_mov_b32 m0, s40
	s_nop 0
	global_load_lds_dwordx4 v[128:129], off
	v_lshl_add_u64 v[128:129], s[20:21], 0, v[66:67]
	s_mov_b32 m0, s41
	s_nop 0
	global_load_lds_dwordx4 v[128:129], off
	v_lshl_add_u64 v[128:129], v[132:133], 0, s[56:57]
	s_mov_b32 m0, s38
	s_nop 0
	global_load_lds_dwordx4 v[128:129], off
	v_lshl_add_u64 v[128:129], v[134:135], 0, s[56:57]
	s_mov_b32 m0, s39
	s_nop 0
	global_load_lds_dwordx4 v[128:129], off
	s_waitcnt vmcnt(8)
	s_waitcnt lgkmcnt(0)
	s_barrier
	s_setprio 1
	s_waitcnt lgkmcnt(0)
	v_mfma_f32_16x16x32_bf16 v[30:33], v[80:83], v[96:99], v[30:33]
	v_mfma_f32_16x16x32_bf16 v[26:29], v[88:91], v[96:99], v[26:29]
	v_mfma_f32_16x16x32_bf16 v[22:25], v[80:83], v[104:107], v[22:25]
	v_mfma_f32_16x16x32_bf16 v[18:21], v[88:91], v[104:107], v[18:21]
	v_mfma_f32_16x16x32_bf16 v[14:17], v[80:83], v[112:115], v[14:17]
	v_mfma_f32_16x16x32_bf16 v[10:13], v[88:91], v[112:115], v[10:13]
	v_mfma_f32_16x16x32_bf16 v[6:9], v[80:83], v[120:123], v[6:9]
	v_mfma_f32_16x16x32_bf16 v[2:5], v[88:91], v[120:123], v[2:5]
	v_mfma_f32_16x16x32_bf16 v[30:33], v[84:87], v[100:103], v[30:33]
	v_mfma_f32_16x16x32_bf16 v[26:29], v[92:95], v[100:103], v[26:29]
	v_mfma_f32_16x16x32_bf16 v[22:25], v[84:87], v[108:111], v[22:25]
	v_mfma_f32_16x16x32_bf16 v[18:21], v[92:95], v[108:111], v[18:21]
	v_mfma_f32_16x16x32_bf16 v[14:17], v[84:87], v[116:119], v[14:17]
	v_mfma_f32_16x16x32_bf16 v[10:13], v[92:95], v[116:119], v[10:13]
	v_mfma_f32_16x16x32_bf16 v[6:9], v[84:87], v[124:127], v[6:9]
	v_mfma_f32_16x16x32_bf16 v[2:5], v[92:95], v[124:127], v[2:5]
	s_setprio 0
	s_setprio 1
	s_setprio 0
	s_barrier
	s_add_i32 s49, s49, 2
	s_add_u32 s18, s18, 0x100
	s_addc_u32 s19, s19, 0
	s_add_u32 s47, s47, 0x100
	s_addc_u32 s48, s48, 0
	s_cmp_gt_u32 s49, 5
	s_cbranch_scc0 .LBB0_3676
	s_and_b64 vcc, exec, s[6:7]
	s_cbranch_vccz .LBB0_3679
	s_barrier

; #define PG8_STAGE(bufoff, gbase, voff) do { _Pragma("unroll") for (int _i = 0; _i < 2; ++_i) \
;         __builtin_amdgcn_global_load_lds((const unsigned*)((const char*)(gbase) + (voff)[_i]), (LAS unsigned*)(lds + (bufoff) + ldsw + _i * 8192), 16, 0, 0); } while (0)
; #define PG8_LDA(dst, b, h) do { _Pragma("unroll") for (int m = 0; m < 4; ++m) _Pragma("unroll") for (int k = 0; k < 2; ++k) dst[m][k] = *(const LAS bf16x8*)(lds + PG8_SA(b, h) + aoff + m * 2048 + k * 1024); } while (0)
; #define PG8_LDB(dst, b, h) do { _Pragma("unroll") for (int n = 0; n < 2; ++n) _Pragma("unroll") for (int k = 0; k < 2; ++k) dst[n][k] = *(const LAS bf16x8*)(lds + PG8_SB(b, h) + boff + n * 2048 + k * 1024); } while (0)
; #define PG8_MMA(ai, bj, At, Bt) do { __builtin_amdgcn_s_setprio(1); _Pragma("unroll") for (int m = 0; m < 4; ++m) _Pragma("unroll") for (int n = 0; n < 2; ++n) _Pragma("unroll") for (int k = 0; k < 2; ++k) \
;         acc[ai][bj][m][n] = __builtin_amdgcn_mfma_f32_16x16x32_bf16(Bt[n][k], At[m][k], acc[ai][bj][m][n], 0, 0, 0); __builtin_amdgcn_s_setprio(0); } while (0)
; #define PG8_WAIT_V(n) asm volatile("s_waitcnt vmcnt(" #n ")" ::: "memory")
; #define PG8_WAIT_L(n) asm volatile("s_waitcnt lgkmcnt(" #n ")" ::: "memory")
; #define PG8_BAR __builtin_amdgcn_s_barrier()
; #define PG8_SCHED __builtin_amdgcn_sched_barrier(0)
; template <class Epi, class Sched>
; __device__ __forceinline__ void gemm_phase(LAS unsigned char* lds, const Gemm g, const Sched& S, const Epi& E) {
;     ...
;             const bool last = (t == nt - 2);
;             const char* a1 = cA + (size_t)(t + 1) * kstep;
;             const char* a2 = last ? nA : cA + (size_t)(t + 2) * kstep; const char* b2 = last ? nB : cB + (size_t)(t + 2) * kstep;
;             const char* a3 = a2 + kstep; const char* b3 = b2 + kstep;
;             PG8_LDB(B0, 0, 0); PG8_LDB(B1, 0, 1); PG8_SCHED; PG8_LDA(At, 0, 0); PG8_STAGE(PG8_SA(1, 1), a1 + hstepA, voffA);
;             PG8_WAIT_V(8); PG8_WAIT_L(0); PG8_BAR; PG8_MMA(0, 0, At, B0); PG8_MMA(0, 1, At, B1); PG8_BAR; PG8_SCHED;
;             PG8_LDA(At, 0, 1); PG8_STAGE(PG8_SB(0, 0), b2, voffB); PG8_STAGE(PG8_SB(0, 1), b2 + hstepB, voffB); PG8_STAGE(PG8_SA(0, 0), a2, voffA);
;             PG8_WAIT_V(8); PG8_WAIT_L(0); PG8_BAR; PG8_MMA(1, 0, At, B0); PG8_MMA(1, 1, At, B1); PG8_BAR; PG8_SCHED;
.LBB0_3698:
	s_add_u32 s20, s18, 0xfffe0080
	s_addc_u32 s21, s19, -1
	s_add_i32 s50, 0, 0x10000
	v_add_u32_e32 v79, s50, v1
	ds_read_b128 v[80:83], v79
	ds_read_b128 v[84:87], v79 offset:1024
	ds_read_b128 v[88:91], v79 offset:2048
	ds_read_b128 v[92:95], v79 offset:3072
	s_cmp_eq_u32 s49, 4
	s_cselect_b32 s23, s13, s21
	s_cselect_b32 s22, s45, s20
	s_cselect_b32 s21, s11, s48
	s_cselect_b32 s20, s46, s47
	v_lshl_add_u64 v[128:129], s[18:19], 0, v[74:75]
	s_add_i32 m0, s29, 0xc000
	ds_read_b128 v[96:99], v78
	ds_read_b128 v[100:103], v78 offset:1024
	ds_read_b128 v[104:107], v78 offset:2048
	ds_read_b128 v[108:111], v78 offset:3072
	ds_read_b128 v[112:115], v78 offset:4096
	ds_read_b128 v[116:119], v78 offset:5120
	ds_read_b128 v[120:123], v78 offset:6144
	ds_read_b128 v[124:127], v78 offset:7168
	global_load_lds_dwordx4 v[128:129], off
	v_lshl_add_u64 v[128:129], s[18:19], 0, v[76:77]
	s_add_i32 m0, s29, 0xe000
	s_nop 0
	global_load_lds_dwordx4 v[128:129], off
	s_nop 0
	s_nop 0
	s_nop 0
	s_waitcnt vmcnt(8)
	s_waitcnt lgkmcnt(0)
	s_barrier
	s_setprio 1
	s_waitcnt lgkmcnt(0)
	v_mfma_f32_16x16x32_bf16 v[62:65], v[80:83], v[96:99], v[62:65]
	v_mfma_f32_16x16x32_bf16 v[58:61], v[88:91], v[96:99], v[58:61]
	v_mfma_f32_16x16x32_bf16 v[54:57], v[80:83], v[104:107], v[54:57]
	v_mfma_f32_16x16x32_bf16 v[50:53], v[88:91], v[104:107], v[50:53]
	v_mfma_f32_16x16x32_bf16 v[46:49], v[80:83], v[112:115], v[46:49]
	v_mfma_f32_16x16x32_bf16 v[42:45], v[88:91], v[112:115], v[42:45]
	v_mfma_f32_16x16x32_bf16 v[38:41], v[80:83], v[120:123], v[38:41]
	v_mfma_f32_16x16x32_bf16 v[34:37], v[88:91], v[120:123], v[34:37]
	v_mfma_f32_16x16x32_bf16 v[62:65], v[84:87], v[100:103], v[62:65]
	v_mfma_f32_16x16x32_bf16 v[58:61], v[92:95], v[100:103], v[58:61]
	v_mfma_f32_16x16x32_bf16 v[54:57], v[84:87], v[108:111], v[54:57]
	v_mfma_f32_16x16x32_bf16 v[50:53], v[92:95], v[108:111], v[50:53]
	v_mfma_f32_16x16x32_bf16 v[46:49], v[84:87], v[116:119], v[46:49]
	v_mfma_f32_16x16x32_bf16 v[42:45], v[92:95], v[116:119], v[42:45]
	v_mfma_f32_16x16x32_bf16 v[38:41], v[84:87], v[124:127], v[38:41]
	v_mfma_f32_16x16x32_bf16 v[34:37], v[92:95], v[124:127], v[34:37]
	s_setprio 0
	s_setprio 1
	s_setprio 0
	s_barrier
	s_add_i32 s50, s50, s28
	v_lshl_add_u64 v[128:129], s[20:21], 0, v[70:71]
	s_mov_b32 m0, s50
	ds_read_b128 v[96:99], v78 offset:16384
	ds_read_b128 v[100:103], v78 offset:17408
	ds_read_b128 v[104:107], v78 offset:18432
	ds_read_b128 v[108:111], v78 offset:19456
	ds_read_b128 v[112:115], v78 offset:20480
	ds_read_b128 v[116:119], v78 offset:21504
	ds_read_b128 v[120:123], v78 offset:22528
	ds_read_b128 v[124:127], v78 offset:23552
	global_load_lds_dwordx4 v[128:129], off
	s_add_i32 m0, s50, 0x2000
	s_add_u32 s50, s20, 0x20000
	v_lshl_add_u64 v[130:131], s[20:21], 0, v[66:67]
	s_addc_u32 s51, s21, 0
	global_load_lds_dwordx4 v[130:131], off
	v_lshl_add_u64 v[132:133], s[50:51], 0, v[70:71]
	s_mov_b32 m0, s30
	v_lshl_add_u64 v[134:135], s[22:23], 0, v[68:69]
	global_load_lds_dwordx4 v[132:133], off
	v_lshl_add_u64 v[132:133], s[50:51], 0, v[66:67]
	s_mov_b32 m0, s31
	s_nop 0
	global_load_lds_dwordx4 v[132:133], off
	v_lshl_add_u64 v[132:133], s[22:23], 0, v[72:73]
	s_mov_b32 m0, s29
	s_nop 0
	global_load_lds_dwordx4 v[132:133], off
	s_mov_b32 m0, s33
	s_nop 0
	global_load_lds_dwordx4 v[134:135], off
	s_nop 0
	s_waitcnt vmcnt(8)
	s_waitcnt lgkmcnt(0)
	s_barrier
	s_setprio 1
	s_waitcnt lgkmcnt(0)
	v_mfma_f32_16x16x32_bf16 v[30:33], v[80:83], v[96:99], v[30:33]
	v_mfma_f32_16x16x32_bf16 v[26:29], v[88:91], v[96:99], v[26:29]
	v_mfma_f32_16x16x32_bf16 v[22:25], v[80:83], v[104:107], v[22:25]
	v_mfma_f32_16x16x32_bf16 v[18:21], v[88:91], v[104:107], v[18:21]
	v_mfma_f32_16x16x32_bf16 v[14:17], v[80:83], v[112:115], v[14:17]
	v_mfma_f32_16x16x32_bf16 v[10:13], v[88:91], v[112:115], v[10:13]
	v_mfma_f32_16x16x32_bf16 v[6:9], v[80:83], v[120:123], v[6:9]
	v_mfma_f32_16x16x32_bf16 v[2:5], v[88:91], v[120:123], v[2:5]
	v_mfma_f32_16x16x32_bf16 v[30:33], v[84:87], v[100:103], v[30:33]
	v_mfma_f32_16x16x32_bf16 v[26:29], v[92:95], v[100:103], v[26:29]
	v_mfma_f32_16x16x32_bf16 v[22:25], v[84:87], v[108:111], v[22:25]
	v_mfma_f32_16x16x32_bf16 v[18:21], v[92:95], v[108:111], v[18:21]
	v_mfma_f32_16x16x32_bf16 v[14:17], v[84:87], v[116:119], v[14:17]
	v_mfma_f32_16x16x32_bf16 v[10:13], v[92:95], v[116:119], v[10:13]
	v_mfma_f32_16x16x32_bf16 v[6:9], v[84:87], v[124:127], v[6:9]
	v_mfma_f32_16x16x32_bf16 v[2:5], v[92:95], v[124:127], v[2:5]
	s_setprio 0
	s_setprio 1
	s_setprio 0
	s_barrier
; #define PG8_STAGE(bufoff, gbase, voff) do { _Pragma("unroll") for (int _i = 0; _i < 2; ++_i) \
;         __builtin_amdgcn_global_load_lds((const unsigned*)((const char*)(gbase) + (voff)[_i]), (LAS unsigned*)(lds + (bufoff) + ldsw + _i * 8192), 16, 0, 0); } while (0)
; #define PG8_LDA(dst, b, h) do { _Pragma("unroll") for (int m = 0; m < 4; ++m) _Pragma("unroll") for (int k = 0; k < 2; ++k) dst[m][k] = *(const LAS bf16x8*)(lds + PG8_SA(b, h) + aoff + m * 2048 + k * 1024); } while (0)
; #define PG8_LDB(dst, b, h) do { _Pragma("unroll") for (int n = 0; n < 2; ++n) _Pragma("unroll") for (int k = 0; k < 2; ++k) dst[n][k] = *(const LAS bf16x8*)(lds + PG8_SB(b, h) + boff + n * 2048 + k * 1024); } while (0)
; #define PG8_MMA(ai, bj, At, Bt) do { __builtin_amdgcn_s_setprio(1); _Pragma("unroll") for (int m = 0; m < 4; ++m) _Pragma("unroll") for (int n = 0; n < 2; ++n) _Pragma("unroll") for (int k = 0; k < 2; ++k) \
;         acc[ai][bj][m][n] = __builtin_amdgcn_mfma_f32_16x16x32_bf16(Bt[n][k], At[m][k], acc[ai][bj][m][n], 0, 0, 0); __builtin_amdgcn_s_setprio(0); } while (0)
; #define PG8_WAIT_V(n) asm volatile("s_waitcnt vmcnt(" #n ")" ::: "memory")
; #define PG8_WAIT_L(n) asm volatile("s_waitcnt lgkmcnt(" #n ")" ::: "memory")
; #define PG8_BAR __builtin_amdgcn_s_barrier()
; #define PG8_SCHED __builtin_amdgcn_sched_barrier(0)
; template <class Epi, class Sched>
; __device__ __forceinline__ void gemm_phase(LAS unsigned char* lds, const Gemm g, const Sched& S, const Epi& E) {
;     ...
;             PG8_LDB(B0, 1, 0); PG8_LDB(B1, 1, 1); PG8_SCHED; PG8_LDA(At, 1, 0); PG8_STAGE(PG8_SA(0, 1), a2 + hstepA, voffA);
;             PG8_WAIT_V(8); PG8_WAIT_L(0); PG8_BAR; PG8_MMA(0, 0, At, B0); PG8_MMA(0, 1, At, B1); PG8_BAR; PG8_SCHED;
;             PG8_LDA(At, 1, 1); PG8_STAGE(PG8_SB(1, 0), b3, voffB); PG8_STAGE(PG8_SB(1, 1), b3 + hstepB, voffB); PG8_STAGE(PG8_SA(1, 0), a3, voffA);
;             PG8_WAIT_V(8); PG8_WAIT_L(0); PG8_BAR; PG8_MMA(1, 0, At, B0); PG8_MMA(1, 1, At, B1); PG8_BAR; PG8_SCHED;
;         }
;         if (wr == 0) PG8_BAR;
	s_add_i32 s50, 0, 0x18000
	v_add_u32_e32 v79, s50, v1
	ds_read_b128 v[80:83], v79
	ds_read_b128 v[84:87], v79 offset:1024
	ds_read_b128 v[88:91], v79 offset:2048
	ds_read_b128 v[92:95], v79 offset:3072
	s_add_u32 s22, s22, 0x20000
	s_addc_u32 s23, s23, 0
	s_mov_b32 m0, s34
	v_lshl_add_u64 v[136:137], s[22:23], 0, v[72:73]
	ds_read_b128 v[96:99], v78 offset:32768
	ds_read_b128 v[100:103], v78 offset:33792
	ds_read_b128 v[104:107], v78 offset:34816
	ds_read_b128 v[108:111], v78 offset:35840
	ds_read_b128 v[112:115], v78 offset:36864
	ds_read_b128 v[116:119], v78 offset:37888
	ds_read_b128 v[120:123], v78 offset:38912
	ds_read_b128 v[124:127], v78 offset:39936
	global_load_lds_dwordx4 v[136:137], off
	v_lshl_add_u64 v[136:137], s[22:23], 0, v[68:69]
	s_mov_b32 m0, s35
	s_nop 0
	global_load_lds_dwordx4 v[136:137], off
	s_nop 0
	s_nop 0
	s_waitcnt vmcnt(8)
	s_waitcnt lgkmcnt(0)
	s_barrier
	s_setprio 1
	s_waitcnt lgkmcnt(0)
	v_mfma_f32_16x16x32_bf16 v[62:65], v[80:83], v[96:99], v[62:65]
	v_mfma_f32_16x16x32_bf16 v[58:61], v[88:91], v[96:99], v[58:61]
	v_mfma_f32_16x16x32_bf16 v[54:57], v[80:83], v[104:107], v[54:57]
	v_mfma_f32_16x16x32_bf16 v[50:53], v[88:91], v[104:107], v[50:53]
	v_mfma_f32_16x16x32_bf16 v[46:49], v[80:83], v[112:115], v[46:49]
	v_mfma_f32_16x16x32_bf16 v[42:45], v[88:91], v[112:115], v[42:45]
	v_mfma_f32_16x16x32_bf16 v[38:41], v[80:83], v[120:123], v[38:41]
	v_mfma_f32_16x16x32_bf16 v[34:37], v[88:91], v[120:123], v[34:37]
	v_mfma_f32_16x16x32_bf16 v[62:65], v[84:87], v[100:103], v[62:65]
	v_mfma_f32_16x16x32_bf16 v[58:61], v[92:95], v[100:103], v[58:61]
	v_mfma_f32_16x16x32_bf16 v[54:57], v[84:87], v[108:111], v[54:57]
	v_mfma_f32_16x16x32_bf16 v[50:53], v[92:95], v[108:111], v[50:53]
	v_mfma_f32_16x16x32_bf16 v[46:49], v[84:87], v[116:119], v[46:49]
	v_mfma_f32_16x16x32_bf16 v[42:45], v[92:95], v[116:119], v[42:45]
	v_mfma_f32_16x16x32_bf16 v[38:41], v[84:87], v[124:127], v[38:41]
	v_mfma_f32_16x16x32_bf16 v[34:37], v[92:95], v[124:127], v[34:37]
	s_setprio 0
	s_setprio 1
	s_setprio 0
	s_barrier
	s_add_i32 s22, s50, s28
	v_lshl_add_u64 v[128:129], v[128:129], 0, s[56:57]
	s_mov_b32 m0, s22
	ds_read_b128 v[96:99], v78 offset:49152
	ds_read_b128 v[100:103], v78 offset:50176
	ds_read_b128 v[104:107], v78 offset:51200
	ds_read_b128 v[108:111], v78 offset:52224
	ds_read_b128 v[112:115], v78 offset:53248
	ds_read_b128 v[116:119], v78 offset:54272
	ds_read_b128 v[120:123], v78 offset:55296
	ds_read_b128 v[124:127], v78 offset:56320
	global_load_lds_dwordx4 v[128:129], off
	s_add_i32 m0, s22, 0x2000
	s_add_u32 s20, s20, 0x20080
	v_lshl_add_u64 v[128:129], v[130:131], 0, s[56:57]
	s_addc_u32 s21, s21, 0
	global_load_lds_dwordx4 v[128:129], off
	v_lshl_add_u64 v[128:129], s[20:21], 0, v[70:71]
	s_mov_b32 m0, s40
	s_nop 0
	global_load_lds_dwordx4 v[128:129], off
	v_lshl_add_u64 v[128:129], s[20:21], 0, v[66:67]
	s_mov_b32 m0, s41
	s_nop 0
	global_load_lds_dwordx4 v[128:129], off
	v_lshl_add_u64 v[128:129], v[132:133], 0, s[56:57]
	s_mov_b32 m0, s38
	s_nop 0
	global_load_lds_dwordx4 v[128:129], off
	v_lshl_add_u64 v[128:129], v[134:135], 0, s[56:57]
	s_mov_b32 m0, s39
	s_nop 0
	global_load_lds_dwordx4 v[128:129], off
	s_waitcnt vmcnt(8)
	s_waitcnt lgkmcnt(0)
	s_barrier
	s_setprio 1
	s_waitcnt lgkmcnt(0)
	v_mfma_f32_16x16x32_bf16 v[30:33], v[80:83], v[96:99], v[30:33]
	v_mfma_f32_16x16x32_bf16 v[26:29], v[88:91], v[96:99], v[26:29]
	v_mfma_f32_16x16x32_bf16 v[22:25], v[80:83], v[104:107], v[22:25]
	v_mfma_f32_16x16x32_bf16 v[18:21], v[88:91], v[104:107], v[18:21]
	v_mfma_f32_16x16x32_bf16 v[14:17], v[80:83], v[112:115], v[14:17]
	v_mfma_f32_16x16x32_bf16 v[10:13], v[88:91], v[112:115], v[10:13]
	v_mfma_f32_16x16x32_bf16 v[6:9], v[80:83], v[120:123], v[6:9]
	v_mfma_f32_16x16x32_bf16 v[2:5], v[88:91], v[120:123], v[2:5]
	v_mfma_f32_16x16x32_bf16 v[30:33], v[84:87], v[100:103], v[30:33]
	v_mfma_f32_16x16x32_bf16 v[26:29], v[92:95], v[100:103], v[26:29]
	v_mfma_f32_16x16x32_bf16 v[22:25], v[84:87], v[108:111], v[22:25]
	v_mfma_f32_16x16x32_bf16 v[18:21], v[92:95], v[108:111], v[18:21]
	v_mfma_f32_16x16x32_bf16 v[14:17], v[84:87], v[116:119], v[14:17]
	v_mfma_f32_16x16x32_bf16 v[10:13], v[92:95], v[116:119], v[10:13]
	v_mfma_f32_16x16x32_bf16 v[6:9], v[84:87], v[124:127], v[6:9]
	v_mfma_f32_16x16x32_bf16 v[2:5], v[92:95], v[124:127], v[2:5]
	s_setprio 0
	s_setprio 1
	s_setprio 0
	s_barrier
	s_add_i32 s49, s49, 2
	s_add_u32 s18, s18, 0x100
	s_addc_u32 s19, s19, 0
	s_add_u32 s47, s47, 0x100
	s_addc_u32 s48, s48, 0
	s_cmp_gt_u32 s49, 5
	s_cbranch_scc0 .LBB0_3698
	s_and_b64 vcc, exec, s[6:7]
	s_cbranch_vccz .LBB0_3701
	s_barrier

; #define PG8_STAGE(bufoff, gbase, voff) do { _Pragma("unroll") for (int _i = 0; _i < 2; ++_i) \
;         __builtin_amdgcn_global_load_lds((const unsigned*)((const char*)(gbase) + (voff)[_i]), (LAS unsigned*)(lds + (bufoff) + ldsw + _i * 8192), 16, 0, 0); } while (0)
; #define PG8_LDA(dst, b, h) do { _Pragma("unroll") for (int m = 0; m < 4; ++m) _Pragma("unroll") for (int k = 0; k < 2; ++k) dst[m][k] = *(const LAS bf16x8*)(lds + PG8_SA(b, h) + aoff + m * 2048 + k * 1024); } while (0)
; #define PG8_LDB(dst, b, h) do { _Pragma("unroll") for (int n = 0; n < 2; ++n) _Pragma("unroll") for (int k = 0; k < 2; ++k) dst[n][k] = *(const LAS bf16x8*)(lds + PG8_SB(b, h) + boff + n * 2048 + k * 1024); } while (0)
; #define PG8_MMA(ai, bj, At, Bt) do { __builtin_amdgcn_s_setprio(1); _Pragma("unroll") for (int m = 0; m < 4; ++m) _Pragma("unroll") for (int n = 0; n < 2; ++n) _Pragma("unroll") for (int k = 0; k < 2; ++k) \
;         acc[ai][bj][m][n] = __builtin_amdgcn_mfma_f32_16x16x32_bf16(Bt[n][k], At[m][k], acc[ai][bj][m][n], 0, 0, 0); __builtin_amdgcn_s_setprio(0); } while (0)
; #define PG8_WAIT_V(n) asm volatile("s_waitcnt vmcnt(" #n ")" ::: "memory")
; #define PG8_WAIT_L(n) asm volatile("s_waitcnt lgkmcnt(" #n ")" ::: "memory")
; #define PG8_BAR __builtin_amdgcn_s_barrier()
; #define PG8_SCHED __builtin_amdgcn_sched_barrier(0)
; template <class Epi, class Sched>
; __device__ __forceinline__ void gemm_phase(LAS unsigned char* lds, const Gemm g, const Sched& S, const Epi& E) {
;     ...
;             const bool last = (t == nt - 2);
;             const char* a1 = cA + (size_t)(t + 1) * kstep;
;             const char* a2 = last ? nA : cA + (size_t)(t + 2) * kstep; const char* b2 = last ? nB : cB + (size_t)(t + 2) * kstep;
;             const char* a3 = a2 + kstep; const char* b3 = b2 + kstep;
;             PG8_LDB(B0, 0, 0); PG8_LDB(B1, 0, 1); PG8_SCHED; PG8_LDA(At, 0, 0); PG8_STAGE(PG8_SA(1, 1), a1 + hstepA, voffA);
;             PG8_WAIT_V(8); PG8_WAIT_L(0); PG8_BAR; PG8_MMA(0, 0, At, B0); PG8_MMA(0, 1, At, B1); PG8_BAR; PG8_SCHED;
;             PG8_LDA(At, 0, 1); PG8_STAGE(PG8_SB(0, 0), b2, voffB); PG8_STAGE(PG8_SB(0, 1), b2 + hstepB, voffB); PG8_STAGE(PG8_SA(0, 0), a2, voffA);
.LBB0_4095:
	s_add_u32 s22, s20, 0xfff80080
	s_addc_u32 s23, s21, -1
	s_add_i32 s46, 0, 0x10000
	s_cmp_eq_u32 s45, 28
	s_cselect_b32 s25, s11, s23
	s_cselect_b32 s24, s17, s22
	s_cselect_b32 s23, s7, s44
	s_cselect_b32 s22, s19, s43
	s_add_i32 s49, 0, 0x14000
	v_add_u32_e32 v170, s46, v1
	v_add_u32_e32 v174, s49, v1
	ds_read_b128 v[130:133], v170
	ds_read_b128 v[134:137], v170 offset:1024
	ds_read_b128 v[166:169], v170 offset:2048
	ds_read_b128 v[170:173], v170 offset:3072
	ds_read_b128 v[178:181], v174
	ds_read_b128 v[182:185], v174 offset:1024
	ds_read_b128 v[186:189], v174 offset:2048
	ds_read_b128 v[190:193], v174 offset:3072
	v_lshl_add_u64 v[174:175], s[20:21], 0, v[162:163]
	s_add_i32 m0, s31, 0xc000
	ds_read_b128 v[208:211], v176
	ds_read_b128 v[212:215], v176 offset:1024
	ds_read_b128 v[216:219], v176 offset:2048
	ds_read_b128 v[220:223], v176 offset:3072
	ds_read_b128 v[224:227], v176 offset:4096
	ds_read_b128 v[228:231], v176 offset:5120
	ds_read_b128 v[232:235], v176 offset:6144
	ds_read_b128 v[236:239], v176 offset:7168
	global_load_lds_dwordx4 v[174:175], off
	v_lshl_add_u64 v[174:175], s[20:21], 0, v[164:165]
	s_add_i32 m0, s31, 0xe000
	s_nop 0
	global_load_lds_dwordx4 v[174:175], off
	s_nop 0
	s_nop 0
	s_waitcnt vmcnt(8)
	s_waitcnt lgkmcnt(0)
	s_barrier
	s_setprio 1
	s_waitcnt lgkmcnt(0)
	v_mfma_f32_16x16x32_bf16 v[126:129], v[130:133], v[208:211], v[126:129]
	v_mfma_f32_16x16x32_bf16 v[122:125], v[166:169], v[208:211], v[122:125]
	v_mfma_f32_16x16x32_bf16 v[110:113], v[130:133], v[216:219], v[110:113]
	v_mfma_f32_16x16x32_bf16 v[106:109], v[166:169], v[216:219], v[106:109]
	v_mfma_f32_16x16x32_bf16 v[94:97], v[130:133], v[224:227], v[94:97]
	v_mfma_f32_16x16x32_bf16 v[90:93], v[166:169], v[224:227], v[90:93]
	v_mfma_f32_16x16x32_bf16 v[78:81], v[130:133], v[232:235], v[78:81]
	v_mfma_f32_16x16x32_bf16 v[74:77], v[166:169], v[232:235], v[74:77]
	v_mfma_f32_16x16x32_bf16 v[126:129], v[134:137], v[212:215], v[126:129]
	v_mfma_f32_16x16x32_bf16 v[122:125], v[170:173], v[212:215], v[122:125]
	v_mfma_f32_16x16x32_bf16 v[110:113], v[134:137], v[220:223], v[110:113]
	v_mfma_f32_16x16x32_bf16 v[106:109], v[170:173], v[220:223], v[106:109]
	v_mfma_f32_16x16x32_bf16 v[94:97], v[134:137], v[228:231], v[94:97]
	v_mfma_f32_16x16x32_bf16 v[90:93], v[170:173], v[228:231], v[90:93]
	v_mfma_f32_16x16x32_bf16 v[78:81], v[134:137], v[236:239], v[78:81]
	v_mfma_f32_16x16x32_bf16 v[74:77], v[170:173], v[236:239], v[74:77]
	s_setprio 0
	s_setprio 1
	v_mfma_f32_16x16x32_bf16 v[118:121], v[178:181], v[208:211], v[118:121]
	v_mfma_f32_16x16x32_bf16 v[114:117], v[186:189], v[208:211], v[114:117]
	v_mfma_f32_16x16x32_bf16 v[102:105], v[178:181], v[216:219], v[102:105]
	v_mfma_f32_16x16x32_bf16 v[98:101], v[186:189], v[216:219], v[98:101]
	v_mfma_f32_16x16x32_bf16 v[86:89], v[178:181], v[224:227], v[86:89]
	v_mfma_f32_16x16x32_bf16 v[82:85], v[186:189], v[224:227], v[82:85]
	v_mfma_f32_16x16x32_bf16 v[70:73], v[178:181], v[232:235], v[70:73]
	v_mfma_f32_16x16x32_bf16 v[66:69], v[186:189], v[232:235], v[66:69]
	v_mfma_f32_16x16x32_bf16 v[118:121], v[182:185], v[212:215], v[118:121]
	v_mfma_f32_16x16x32_bf16 v[114:117], v[190:193], v[212:215], v[114:117]
	v_mfma_f32_16x16x32_bf16 v[102:105], v[182:185], v[220:223], v[102:105]
	v_mfma_f32_16x16x32_bf16 v[98:101], v[190:193], v[220:223], v[98:101]
	v_mfma_f32_16x16x32_bf16 v[86:89], v[182:185], v[228:231], v[86:89]
	v_mfma_f32_16x16x32_bf16 v[82:85], v[190:193], v[228:231], v[82:85]
	v_mfma_f32_16x16x32_bf16 v[70:73], v[182:185], v[236:239], v[70:73]
	v_mfma_f32_16x16x32_bf16 v[66:69], v[190:193], v[236:239], v[66:69]
	s_setprio 0
	s_barrier
	s_add_i32 s46, s46, s30
	v_lshl_add_u64 v[174:175], s[22:23], 0, v[140:141]
	s_mov_b32 m0, s46
	ds_read_b128 v[208:211], v176 offset:16384
	ds_read_b128 v[212:215], v176 offset:17408
	ds_read_b128 v[216:219], v176 offset:18432
	ds_read_b128 v[220:223], v176 offset:19456
	ds_read_b128 v[224:227], v176 offset:20480
	ds_read_b128 v[228:231], v176 offset:21504
	ds_read_b128 v[232:235], v176 offset:22528
	ds_read_b128 v[236:239], v176 offset:23552
	global_load_lds_dwordx4 v[174:175], off
	s_add_i32 m0, s46, 0x2000
	s_add_u32 s46, s22, 0x80000
	v_lshl_add_u64 v[240:241], s[22:23], 0, v[144:145]
	s_addc_u32 s47, s23, 0
	s_add_i32 s49, s49, s30
	global_load_lds_dwordx4 v[240:241], off
	v_lshl_add_u64 v[242:243], s[46:47], 0, v[140:141]
	s_mov_b32 m0, s49
	v_lshl_add_u64 v[244:245], s[24:25], 0, v[142:143]
	global_load_lds_dwordx4 v[242:243], off
	v_lshl_add_u64 v[242:243], s[46:47], 0, v[144:145]
	s_add_i32 m0, s49, 0x2000
	s_nop 0
	global_load_lds_dwordx4 v[242:243], off
	v_lshl_add_u64 v[242:243], s[24:25], 0, v[138:139]
	s_mov_b32 m0, s31
	s_nop 0
	global_load_lds_dwordx4 v[242:243], off
	s_mov_b32 m0, s33
	s_nop 0
	global_load_lds_dwordx4 v[244:245], off
	s_nop 0
	s_nop 0
	s_nop 0
	s_waitcnt vmcnt(8)
	s_waitcnt lgkmcnt(0)
	s_barrier
; #define PG8_STAGE(bufoff, gbase, voff) do { _Pragma("unroll") for (int _i = 0; _i < 2; ++_i) \
;         __builtin_amdgcn_global_load_lds((const unsigned*)((const char*)(gbase) + (voff)[_i]), (LAS unsigned*)(lds + (bufoff) + ldsw + _i * 8192), 16, 0, 0); } while (0)
; #define PG8_LDA(dst, b, h) do { _Pragma("unroll") for (int m = 0; m < 4; ++m) _Pragma("unroll") for (int k = 0; k < 2; ++k) dst[m][k] = *(const LAS bf16x8*)(lds + PG8_SA(b, h) + aoff + m * 2048 + k * 1024); } while (0)
; #define PG8_LDB(dst, b, h) do { _Pragma("unroll") for (int n = 0; n < 2; ++n) _Pragma("unroll") for (int k = 0; k < 2; ++k) dst[n][k] = *(const LAS bf16x8*)(lds + PG8_SB(b, h) + boff + n * 2048 + k * 1024); } while (0)
; #define PG8_MMA(ai, bj, At, Bt) do { __builtin_amdgcn_s_setprio(1); _Pragma("unroll") for (int m = 0; m < 4; ++m) _Pragma("unroll") for (int n = 0; n < 2; ++n) _Pragma("unroll") for (int k = 0; k < 2; ++k) \
;         acc[ai][bj][m][n] = __builtin_amdgcn_mfma_f32_16x16x32_bf16(Bt[n][k], At[m][k], acc[ai][bj][m][n], 0, 0, 0); __builtin_amdgcn_s_setprio(0); } while (0)
; #define PG8_WAIT_V(n) asm volatile("s_waitcnt vmcnt(" #n ")" ::: "memory")
; #define PG8_WAIT_L(n) asm volatile("s_waitcnt lgkmcnt(" #n ")" ::: "memory")
; #define PG8_BAR __builtin_amdgcn_s_barrier()
; #define PG8_SCHED __builtin_amdgcn_sched_barrier(0)
; template <class Epi, class Sched>
; __device__ __forceinline__ void gemm_phase(LAS unsigned char* lds, const Gemm g, const Sched& S, const Epi& E) {
;     ...
;             PG8_WAIT_V(8); PG8_WAIT_L(0); PG8_BAR; PG8_MMA(1, 0, At, B0); PG8_MMA(1, 1, At, B1); PG8_BAR; PG8_SCHED;
;             PG8_LDB(B0, 1, 0); PG8_LDB(B1, 1, 1); PG8_SCHED; PG8_LDA(At, 1, 0); PG8_STAGE(PG8_SA(0, 1), a2 + hstepA, voffA);
;             PG8_WAIT_V(8); PG8_WAIT_L(0); PG8_BAR; PG8_MMA(0, 0, At, B0); PG8_MMA(0, 1, At, B1); PG8_BAR; PG8_SCHED;
	s_setprio 1
	s_waitcnt lgkmcnt(0)
	v_mfma_f32_16x16x32_bf16 v[62:65], v[130:133], v[208:211], v[62:65]
	v_mfma_f32_16x16x32_bf16 v[58:61], v[166:169], v[208:211], v[58:61]
	v_mfma_f32_16x16x32_bf16 v[46:49], v[130:133], v[216:219], v[46:49]
	v_mfma_f32_16x16x32_bf16 v[42:45], v[166:169], v[216:219], v[42:45]
	v_mfma_f32_16x16x32_bf16 v[30:33], v[130:133], v[224:227], v[30:33]
	v_mfma_f32_16x16x32_bf16 v[26:29], v[166:169], v[224:227], v[26:29]
	v_mfma_f32_16x16x32_bf16 v[14:17], v[130:133], v[232:235], v[14:17]
	v_mfma_f32_16x16x32_bf16 v[10:13], v[166:169], v[232:235], v[10:13]
	v_mfma_f32_16x16x32_bf16 v[62:65], v[134:137], v[212:215], v[62:65]
	v_mfma_f32_16x16x32_bf16 v[58:61], v[170:173], v[212:215], v[58:61]
	v_mfma_f32_16x16x32_bf16 v[46:49], v[134:137], v[220:223], v[46:49]
	v_mfma_f32_16x16x32_bf16 v[42:45], v[170:173], v[220:223], v[42:45]
	v_mfma_f32_16x16x32_bf16 v[30:33], v[134:137], v[228:231], v[30:33]
	v_mfma_f32_16x16x32_bf16 v[26:29], v[170:173], v[228:231], v[26:29]
	v_mfma_f32_16x16x32_bf16 v[14:17], v[134:137], v[236:239], v[14:17]
	v_mfma_f32_16x16x32_bf16 v[10:13], v[170:173], v[236:239], v[10:13]
	s_setprio 0
	s_setprio 1
	v_mfma_f32_16x16x32_bf16 v[54:57], v[178:181], v[208:211], v[54:57]
	v_mfma_f32_16x16x32_bf16 v[50:53], v[186:189], v[208:211], v[50:53]
	v_mfma_f32_16x16x32_bf16 v[38:41], v[178:181], v[216:219], v[38:41]
	v_mfma_f32_16x16x32_bf16 v[34:37], v[186:189], v[216:219], v[34:37]
	v_mfma_f32_16x16x32_bf16 v[22:25], v[178:181], v[224:227], v[22:25]
	v_mfma_f32_16x16x32_bf16 v[18:21], v[186:189], v[224:227], v[18:21]
	v_mfma_f32_16x16x32_bf16 v[6:9], v[178:181], v[232:235], v[6:9]
	v_mfma_f32_16x16x32_bf16 v[2:5], v[186:189], v[232:235], v[2:5]
	v_mfma_f32_16x16x32_bf16 v[54:57], v[182:185], v[212:215], v[54:57]
	v_mfma_f32_16x16x32_bf16 v[50:53], v[190:193], v[212:215], v[50:53]
	v_mfma_f32_16x16x32_bf16 v[38:41], v[182:185], v[220:223], v[38:41]
	v_mfma_f32_16x16x32_bf16 v[34:37], v[190:193], v[220:223], v[34:37]
	v_mfma_f32_16x16x32_bf16 v[22:25], v[182:185], v[228:231], v[22:25]
	v_mfma_f32_16x16x32_bf16 v[18:21], v[190:193], v[228:231], v[18:21]
	v_mfma_f32_16x16x32_bf16 v[6:9], v[182:185], v[236:239], v[6:9]
	v_mfma_f32_16x16x32_bf16 v[2:5], v[190:193], v[236:239], v[2:5]
	s_setprio 0
	s_barrier
	s_add_i32 s46, 0, 0x18000
	s_add_i32 s47, 0, 0x1c000
	v_add_u32_e32 v170, s46, v1
	v_add_u32_e32 v177, s47, v1
	ds_read_b128 v[130:133], v170
	ds_read_b128 v[134:137], v170 offset:1024
	ds_read_b128 v[166:169], v170 offset:2048
	ds_read_b128 v[170:173], v170 offset:3072
	ds_read_b128 v[178:181], v177
	ds_read_b128 v[182:185], v177 offset:1024
	ds_read_b128 v[186:189], v177 offset:2048
	ds_read_b128 v[190:193], v177 offset:3072
	s_add_u32 s24, s24, 0x80000
	s_addc_u32 s25, s25, 0
	s_mov_b32 m0, s34
	v_lshl_add_u64 v[246:247], s[24:25], 0, v[138:139]
	ds_read_b128 v[208:211], v176 offset:32768
	ds_read_b128 v[212:215], v176 offset:33792
	ds_read_b128 v[216:219], v176 offset:34816
	ds_read_b128 v[220:223], v176 offset:35840
	ds_read_b128 v[224:227], v176 offset:36864
	ds_read_b128 v[228:231], v176 offset:37888
	ds_read_b128 v[232:235], v176 offset:38912
	ds_read_b128 v[236:239], v176 offset:39936
	global_load_lds_dwordx4 v[246:247], off
	v_lshl_add_u64 v[246:247], s[24:25], 0, v[142:143]
	s_mov_b32 m0, s35
	s_nop 0
	global_load_lds_dwordx4 v[246:247], off
	s_nop 0
	s_nop 0
	s_nop 0
	s_waitcnt vmcnt(8)
	s_waitcnt lgkmcnt(0)
	s_barrier
	s_setprio 1
	s_waitcnt lgkmcnt(0)
	v_mfma_f32_16x16x32_bf16 v[126:129], v[130:133], v[208:211], v[126:129]
	v_mfma_f32_16x16x32_bf16 v[122:125], v[166:169], v[208:211], v[122:125]
	v_mfma_f32_16x16x32_bf16 v[110:113], v[130:133], v[216:219], v[110:113]
	v_mfma_f32_16x16x32_bf16 v[106:109], v[166:169], v[216:219], v[106:109]
	v_mfma_f32_16x16x32_bf16 v[94:97], v[130:133], v[224:227], v[94:97]
	v_mfma_f32_16x16x32_bf16 v[90:93], v[166:169], v[224:227], v[90:93]
	v_mfma_f32_16x16x32_bf16 v[78:81], v[130:133], v[232:235], v[78:81]
	v_mfma_f32_16x16x32_bf16 v[74:77], v[166:169], v[232:235], v[74:77]
	v_mfma_f32_16x16x32_bf16 v[126:129], v[134:137], v[212:215], v[126:129]
	v_mfma_f32_16x16x32_bf16 v[122:125], v[170:173], v[212:215], v[122:125]
	v_mfma_f32_16x16x32_bf16 v[110:113], v[134:137], v[220:223], v[110:113]
	v_mfma_f32_16x16x32_bf16 v[106:109], v[170:173], v[220:223], v[106:109]
	v_mfma_f32_16x16x32_bf16 v[94:97], v[134:137], v[228:231], v[94:97]
	v_mfma_f32_16x16x32_bf16 v[90:93], v[170:173], v[228:231], v[90:93]
	v_mfma_f32_16x16x32_bf16 v[78:81], v[134:137], v[236:239], v[78:81]
	v_mfma_f32_16x16x32_bf16 v[74:77], v[170:173], v[236:239], v[74:77]
	s_setprio 0
	s_setprio 1
	v_mfma_f32_16x16x32_bf16 v[118:121], v[178:181], v[208:211], v[118:121]
	v_mfma_f32_16x16x32_bf16 v[114:117], v[186:189], v[208:211], v[114:117]
	v_mfma_f32_16x16x32_bf16 v[102:105], v[178:181], v[216:219], v[102:105]
	v_mfma_f32_16x16x32_bf16 v[98:101], v[186:189], v[216:219], v[98:101]
	v_mfma_f32_16x16x32_bf16 v[86:89], v[178:181], v[224:227], v[86:89]
	v_mfma_f32_16x16x32_bf16 v[82:85], v[186:189], v[224:227], v[82:85]
	v_mfma_f32_16x16x32_bf16 v[70:73], v[178:181], v[232:235], v[70:73]
	v_mfma_f32_16x16x32_bf16 v[66:69], v[186:189], v[232:235], v[66:69]
	v_mfma_f32_16x16x32_bf16 v[118:121], v[182:185], v[212:215], v[118:121]
	v_mfma_f32_16x16x32_bf16 v[114:117], v[190:193], v[212:215], v[114:117]
	v_mfma_f32_16x16x32_bf16 v[102:105], v[182:185], v[220:223], v[102:105]
	v_mfma_f32_16x16x32_bf16 v[98:101], v[190:193], v[220:223], v[98:101]
	v_mfma_f32_16x16x32_bf16 v[86:89], v[182:185], v[228:231], v[86:89]
	v_mfma_f32_16x16x32_bf16 v[82:85], v[190:193], v[228:231], v[82:85]
	v_mfma_f32_16x16x32_bf16 v[70:73], v[182:185], v[236:239], v[70:73]
	v_mfma_f32_16x16x32_bf16 v[66:69], v[190:193], v[236:239], v[66:69]
	s_setprio 0
	s_barrier
; #define PG8_STAGE(bufoff, gbase, voff) do { _Pragma("unroll") for (int _i = 0; _i < 2; ++_i) \
;         __builtin_amdgcn_global_load_lds((const unsigned*)((const char*)(gbase) + (voff)[_i]), (LAS unsigned*)(lds + (bufoff) + ldsw + _i * 8192), 16, 0, 0); } while (0)
; #define PG8_LDA(dst, b, h) do { _Pragma("unroll") for (int m = 0; m < 4; ++m) _Pragma("unroll") for (int k = 0; k < 2; ++k) dst[m][k] = *(const LAS bf16x8*)(lds + PG8_SA(b, h) + aoff + m * 2048 + k * 1024); } while (0)
; #define PG8_MMA(ai, bj, At, Bt) do { __builtin_amdgcn_s_setprio(1); _Pragma("unroll") for (int m = 0; m < 4; ++m) _Pragma("unroll") for (int n = 0; n < 2; ++n) _Pragma("unroll") for (int k = 0; k < 2; ++k) \
;         acc[ai][bj][m][n] = __builtin_amdgcn_mfma_f32_16x16x32_bf16(Bt[n][k], At[m][k], acc[ai][bj][m][n], 0, 0, 0); __builtin_amdgcn_s_setprio(0); } while (0)
; #define PG8_WAIT_V(n) asm volatile("s_waitcnt vmcnt(" #n ")" ::: "memory")
; #define PG8_WAIT_L(n) asm volatile("s_waitcnt lgkmcnt(" #n ")" ::: "memory")
; #define PG8_BAR __builtin_amdgcn_s_barrier()
; #define PG8_SCHED __builtin_amdgcn_sched_barrier(0)
; template <class Epi, class Sched>
; __device__ __forceinline__ void gemm_phase(LAS unsigned char* lds, const Gemm g, const Sched& S, const Epi& E) {
;     ...
;             PG8_LDA(At, 1, 1); PG8_STAGE(PG8_SB(1, 0), b3, voffB); PG8_STAGE(PG8_SB(1, 1), b3 + hstepB, voffB); PG8_STAGE(PG8_SA(1, 0), a3, voffA);
;             PG8_WAIT_V(8); PG8_WAIT_L(0); PG8_BAR; PG8_MMA(1, 0, At, B0); PG8_MMA(1, 1, At, B1); PG8_BAR; PG8_SCHED;
;         }
;         if (wr == 0) PG8_BAR;
	s_add_i32 s24, s46, s30
	v_lshl_add_u64 v[174:175], v[174:175], 0, s[56:57]
	s_mov_b32 m0, s24
	ds_read_b128 v[208:211], v176 offset:49152
	ds_read_b128 v[212:215], v176 offset:50176
	ds_read_b128 v[216:219], v176 offset:51200
	ds_read_b128 v[220:223], v176 offset:52224
	ds_read_b128 v[224:227], v176 offset:53248
	ds_read_b128 v[228:231], v176 offset:54272
	ds_read_b128 v[232:235], v176 offset:55296
	ds_read_b128 v[236:239], v176 offset:56320
	global_load_lds_dwordx4 v[174:175], off
	s_add_i32 m0, s24, 0x2000
	s_add_u32 s22, s22, 0x80080
	v_lshl_add_u64 v[174:175], v[240:241], 0, s[56:57]
	s_addc_u32 s23, s23, 0
	s_add_i32 s24, s47, s30
	global_load_lds_dwordx4 v[174:175], off
	v_lshl_add_u64 v[174:175], s[22:23], 0, v[140:141]
	s_mov_b32 m0, s24
	s_nop 0
	global_load_lds_dwordx4 v[174:175], off
	v_lshl_add_u64 v[174:175], s[22:23], 0, v[144:145]
	s_add_i32 m0, s24, 0x2000
	s_nop 0
	global_load_lds_dwordx4 v[174:175], off
	v_lshl_add_u64 v[174:175], v[242:243], 0, s[56:57]
	s_mov_b32 m0, s39
	s_nop 0
	global_load_lds_dwordx4 v[174:175], off
	v_lshl_add_u64 v[174:175], v[244:245], 0, s[56:57]
	s_mov_b32 m0, s40
	s_nop 0
	global_load_lds_dwordx4 v[174:175], off
	s_nop 0
	s_nop 0
	s_waitcnt vmcnt(8)
	s_waitcnt lgkmcnt(0)
	s_barrier
	s_setprio 1
	s_waitcnt lgkmcnt(0)
	v_mfma_f32_16x16x32_bf16 v[62:65], v[130:133], v[208:211], v[62:65]
	v_mfma_f32_16x16x32_bf16 v[58:61], v[166:169], v[208:211], v[58:61]
	v_mfma_f32_16x16x32_bf16 v[46:49], v[130:133], v[216:219], v[46:49]
	v_mfma_f32_16x16x32_bf16 v[42:45], v[166:169], v[216:219], v[42:45]
	v_mfma_f32_16x16x32_bf16 v[30:33], v[130:133], v[224:227], v[30:33]
	v_mfma_f32_16x16x32_bf16 v[26:29], v[166:169], v[224:227], v[26:29]
	v_mfma_f32_16x16x32_bf16 v[14:17], v[130:133], v[232:235], v[14:17]
	v_mfma_f32_16x16x32_bf16 v[10:13], v[166:169], v[232:235], v[10:13]
	v_mfma_f32_16x16x32_bf16 v[62:65], v[134:137], v[212:215], v[62:65]
	v_mfma_f32_16x16x32_bf16 v[58:61], v[170:173], v[212:215], v[58:61]
	v_mfma_f32_16x16x32_bf16 v[46:49], v[134:137], v[220:223], v[46:49]
	v_mfma_f32_16x16x32_bf16 v[42:45], v[170:173], v[220:223], v[42:45]
	v_mfma_f32_16x16x32_bf16 v[30:33], v[134:137], v[228:231], v[30:33]
	v_mfma_f32_16x16x32_bf16 v[26:29], v[170:173], v[228:231], v[26:29]
	v_mfma_f32_16x16x32_bf16 v[14:17], v[134:137], v[236:239], v[14:17]
	v_mfma_f32_16x16x32_bf16 v[10:13], v[170:173], v[236:239], v[10:13]
	s_setprio 0
	s_setprio 1
	v_mfma_f32_16x16x32_bf16 v[54:57], v[178:181], v[208:211], v[54:57]
	v_mfma_f32_16x16x32_bf16 v[50:53], v[186:189], v[208:211], v[50:53]
	v_mfma_f32_16x16x32_bf16 v[38:41], v[178:181], v[216:219], v[38:41]
	v_mfma_f32_16x16x32_bf16 v[34:37], v[186:189], v[216:219], v[34:37]
	v_mfma_f32_16x16x32_bf16 v[22:25], v[178:181], v[224:227], v[22:25]
	v_mfma_f32_16x16x32_bf16 v[18:21], v[186:189], v[224:227], v[18:21]
	v_mfma_f32_16x16x32_bf16 v[6:9], v[178:181], v[232:235], v[6:9]
	v_mfma_f32_16x16x32_bf16 v[2:5], v[186:189], v[232:235], v[2:5]
	v_mfma_f32_16x16x32_bf16 v[54:57], v[182:185], v[212:215], v[54:57]
	v_mfma_f32_16x16x32_bf16 v[50:53], v[190:193], v[212:215], v[50:53]
	v_mfma_f32_16x16x32_bf16 v[38:41], v[182:185], v[220:223], v[38:41]
	v_mfma_f32_16x16x32_bf16 v[34:37], v[190:193], v[220:223], v[34:37]
	v_mfma_f32_16x16x32_bf16 v[22:25], v[182:185], v[228:231], v[22:25]
	v_mfma_f32_16x16x32_bf16 v[18:21], v[190:193], v[228:231], v[18:21]
	v_mfma_f32_16x16x32_bf16 v[6:9], v[182:185], v[236:239], v[6:9]
	v_mfma_f32_16x16x32_bf16 v[2:5], v[190:193], v[236:239], v[2:5]
	s_setprio 0
	s_barrier
	s_add_i32 s45, s45, 2
	s_add_u32 s20, s20, 0x100
	s_addc_u32 s21, s21, 0
	s_add_u32 s43, s43, 0x100
	s_addc_u32 s44, s44, 0
	s_cmp_gt_u32 s45, 29
	s_cbranch_scc0 .LBB0_4095
	s_and_b64 vcc, exec, s[4:5]
	s_cbranch_vccz .LBB0_4098
	s_barrier

; #define PG8_STAGE(bufoff, gbase, voff) do { _Pragma("unroll") for (int _i = 0; _i < 2; ++_i) \
;         __builtin_amdgcn_global_load_lds((const unsigned*)((const char*)(gbase) + (voff)[_i]), (LAS unsigned*)(lds + (bufoff) + ldsw + _i * 8192), 16, 0, 0); } while (0)
; #define PG8_LDA(dst, b, h) do { _Pragma("unroll") for (int m = 0; m < 4; ++m) _Pragma("unroll") for (int k = 0; k < 2; ++k) dst[m][k] = *(const LAS bf16x8*)(lds + PG8_SA(b, h) + aoff + m * 2048 + k * 1024); } while (0)
; #define PG8_LDB(dst, b, h) do { _Pragma("unroll") for (int n = 0; n < 2; ++n) _Pragma("unroll") for (int k = 0; k < 2; ++k) dst[n][k] = *(const LAS bf16x8*)(lds + PG8_SB(b, h) + boff + n * 2048 + k * 1024); } while (0)
; #define PG8_MMA(ai, bj, At, Bt) do { __builtin_amdgcn_s_setprio(1); _Pragma("unroll") for (int m = 0; m < 4; ++m) _Pragma("unroll") for (int n = 0; n < 2; ++n) _Pragma("unroll") for (int k = 0; k < 2; ++k) \
;         acc[ai][bj][m][n] = __builtin_amdgcn_mfma_f32_16x16x32_bf16(Bt[n][k], At[m][k], acc[ai][bj][m][n], 0, 0, 0); __builtin_amdgcn_s_setprio(0); } while (0)
; #define PG8_WAIT_V(n) asm volatile("s_waitcnt vmcnt(" #n ")" ::: "memory")
; #define PG8_WAIT_L(n) asm volatile("s_waitcnt lgkmcnt(" #n ")" ::: "memory")
; #define PG8_BAR __builtin_amdgcn_s_barrier()
; #define PG8_SCHED __builtin_amdgcn_sched_barrier(0)
; template <class Epi, class Sched>
; __device__ __forceinline__ void gemm_phase(LAS unsigned char* lds, const Gemm g, const Sched& S, const Epi& E) {
;     ...
;             const bool last = (t == nt - 2);
;             const char* a1 = cA + (size_t)(t + 1) * kstep;
;             const char* a2 = last ? nA : cA + (size_t)(t + 2) * kstep; const char* b2 = last ? nB : cB + (size_t)(t + 2) * kstep;
;             const char* a3 = a2 + kstep; const char* b3 = b2 + kstep;
;             PG8_LDB(B0, 0, 0); PG8_LDB(B1, 0, 1); PG8_SCHED; PG8_LDA(At, 0, 0); PG8_STAGE(PG8_SA(1, 1), a1 + hstepA, voffA);
;             PG8_WAIT_V(8); PG8_WAIT_L(0); PG8_BAR; PG8_MMA(0, 0, At, B0); PG8_MMA(0, 1, At, B1); PG8_BAR; PG8_SCHED;
;             PG8_LDA(At, 0, 1); PG8_STAGE(PG8_SB(0, 0), b2, voffB); PG8_STAGE(PG8_SB(0, 1), b2 + hstepB, voffB); PG8_STAGE(PG8_SA(0, 0), a2, voffA);
.LBB0_4132:
	s_add_u32 s23, s16, s22
	s_addc_u32 s28, s17, 0
	s_add_u32 s26, s23, 0x100
	s_addc_u32 s27, s28, 0
	s_and_b64 s[24:25], s[20:21], exec
	s_cselect_b32 s25, s9, s27
	s_cselect_b32 s24, s53, s26
	s_add_u32 s22, s14, s22
	s_addc_u32 s26, s15, 0
	s_add_u32 s22, s22, 0x100
	s_addc_u32 s26, s26, 0
	s_add_i32 s63, 0, 0x10000
	s_and_b64 s[20:21], s[20:21], exec
	s_cselect_b32 s27, s7, s26
	s_cselect_b32 s26, s54, s22
	s_add_i32 s21, 0, 0x14000
	s_add_u32 s30, s23, 0x10080
	s_addc_u32 s31, s28, 0
	s_add_i32 s62, s63, s39
	s_add_i32 m0, s40, 0xc000
	s_add_i32 s65, s40, 0xe000
	s_add_i32 s59, s62, 0x2000
	v_add_u32_e32 v138, s63, v1
	s_add_u32 s28, s26, 0x10000
	ds_read_b128 v[142:145], v138
	ds_read_b128 v[162:165], v138 offset:1024
	ds_read_b128 v[166:169], v138 offset:2048
	ds_read_b128 v[170:173], v138 offset:3072
	v_add_u32_e32 v138, s21, v1
	s_addc_u32 s29, s27, 0
	s_add_i32 s61, s21, s39
	ds_read_b128 v[174:177], v138
	ds_read_b128 v[178:181], v138 offset:1024
	ds_read_b128 v[182:185], v138 offset:2048
	ds_read_b128 v[186:189], v138 offset:3072
	s_add_i32 s60, s61, 0x2000
	s_add_i32 s58, 0, 0x18000
	s_add_i32 s57, 0, 0x1c000
	s_add_u32 s22, s24, 0x10000
	s_addc_u32 s23, s25, 0
	s_add_i32 s56, s58, s39
	s_add_i32 s55, s56, 0x2000
	s_add_u32 s20, s26, 0x10080
	s_addc_u32 s21, s27, 0
	s_add_i32 s64, s57, s39
	s_add_i32 s63, s64, 0x2000
	v_lshl_add_u64 v[138:139], s[30:31], 0, v[136:137]
	ds_read_b128 v[190:193], v140
	ds_read_b128 v[208:211], v140 offset:1024
	ds_read_b128 v[212:215], v140 offset:2048
	ds_read_b128 v[216:219], v140 offset:3072
	ds_read_b128 v[220:223], v140 offset:4096
	ds_read_b128 v[224:227], v140 offset:5120
	ds_read_b128 v[228:231], v140 offset:6144
	ds_read_b128 v[232:235], v140 offset:7168
	global_load_lds_dwordx4 v[138:139], off
	v_lshl_add_u64 v[138:139], s[30:31], 0, v[132:133]
	s_mov_b32 m0, s65
	s_nop 0
	global_load_lds_dwordx4 v[138:139], off
	s_nop 0
	s_nop 0
	s_waitcnt vmcnt(8)
	s_waitcnt lgkmcnt(0)
	s_barrier
	s_setprio 1
	s_waitcnt lgkmcnt(0)
	v_mfma_f32_16x16x32_bf16 v[126:129], v[142:145], v[190:193], v[126:129]
	v_mfma_f32_16x16x32_bf16 v[122:125], v[166:169], v[190:193], v[122:125]
	v_mfma_f32_16x16x32_bf16 v[114:117], v[142:145], v[212:215], v[114:117]
	v_mfma_f32_16x16x32_bf16 v[106:109], v[166:169], v[212:215], v[106:109]
	v_mfma_f32_16x16x32_bf16 v[98:101], v[142:145], v[220:223], v[98:101]
	v_mfma_f32_16x16x32_bf16 v[90:93], v[166:169], v[220:223], v[90:93]
	v_mfma_f32_16x16x32_bf16 v[78:81], v[142:145], v[228:231], v[78:81]
	v_mfma_f32_16x16x32_bf16 v[74:77], v[166:169], v[228:231], v[74:77]
	v_mfma_f32_16x16x32_bf16 v[126:129], v[162:165], v[208:211], v[126:129]
	v_mfma_f32_16x16x32_bf16 v[122:125], v[170:173], v[208:211], v[122:125]
	v_mfma_f32_16x16x32_bf16 v[114:117], v[162:165], v[216:219], v[114:117]
	v_mfma_f32_16x16x32_bf16 v[106:109], v[170:173], v[216:219], v[106:109]
	v_mfma_f32_16x16x32_bf16 v[98:101], v[162:165], v[224:227], v[98:101]
	v_mfma_f32_16x16x32_bf16 v[90:93], v[170:173], v[224:227], v[90:93]
	v_mfma_f32_16x16x32_bf16 v[78:81], v[162:165], v[232:235], v[78:81]
	v_mfma_f32_16x16x32_bf16 v[74:77], v[170:173], v[232:235], v[74:77]
	s_setprio 0
	s_setprio 1
	v_mfma_f32_16x16x32_bf16 v[118:121], v[174:177], v[190:193], v[118:121]
	v_mfma_f32_16x16x32_bf16 v[110:113], v[182:185], v[190:193], v[110:113]
	v_mfma_f32_16x16x32_bf16 v[102:105], v[174:177], v[212:215], v[102:105]
	v_mfma_f32_16x16x32_bf16 v[94:97], v[182:185], v[212:215], v[94:97]
	v_mfma_f32_16x16x32_bf16 v[86:89], v[174:177], v[220:223], v[86:89]
	v_mfma_f32_16x16x32_bf16 v[82:85], v[182:185], v[220:223], v[82:85]
	v_mfma_f32_16x16x32_bf16 v[70:73], v[174:177], v[228:231], v[70:73]
	v_mfma_f32_16x16x32_bf16 v[66:69], v[182:185], v[228:231], v[66:69]
	v_mfma_f32_16x16x32_bf16 v[118:121], v[178:181], v[208:211], v[118:121]
	v_mfma_f32_16x16x32_bf16 v[110:113], v[186:189], v[208:211], v[110:113]
	v_mfma_f32_16x16x32_bf16 v[102:105], v[178:181], v[216:219], v[102:105]
	v_mfma_f32_16x16x32_bf16 v[94:97], v[186:189], v[216:219], v[94:97]
	v_mfma_f32_16x16x32_bf16 v[86:89], v[178:181], v[224:227], v[86:89]
	v_mfma_f32_16x16x32_bf16 v[82:85], v[186:189], v[224:227], v[82:85]
	v_mfma_f32_16x16x32_bf16 v[70:73], v[178:181], v[232:235], v[70:73]
	v_mfma_f32_16x16x32_bf16 v[66:69], v[186:189], v[232:235], v[66:69]
	s_setprio 0
	s_barrier
	s_mov_b32 m0, s62
	v_lshl_add_u64 v[138:139], s[26:27], 0, v[134:135]
	ds_read_b128 v[190:193], v140 offset:16384
	ds_read_b128 v[208:211], v140 offset:17408
	ds_read_b128 v[212:215], v140 offset:18432
	ds_read_b128 v[216:219], v140 offset:19456
	ds_read_b128 v[220:223], v140 offset:20480
	ds_read_b128 v[224:227], v140 offset:21504
	ds_read_b128 v[228:231], v140 offset:22528
	ds_read_b128 v[232:235], v140 offset:23552
	global_load_lds_dwordx4 v[138:139], off
	v_lshl_add_u64 v[236:237], s[26:27], 0, v[130:131]
	s_mov_b32 m0, s59
	v_lshl_add_u64 v[238:239], s[28:29], 0, v[134:135]
	global_load_lds_dwordx4 v[236:237], off
	s_mov_b32 m0, s61
	v_lshl_add_u64 v[240:241], s[24:25], 0, v[132:133]
	global_load_lds_dwordx4 v[238:239], off
	v_lshl_add_u64 v[238:239], s[28:29], 0, v[130:131]
	s_mov_b32 m0, s60
	s_nop 0
	global_load_lds_dwordx4 v[238:239], off
	v_lshl_add_u64 v[238:239], s[24:25], 0, v[136:137]
	s_mov_b32 m0, s40
	s_nop 0
	global_load_lds_dwordx4 v[238:239], off
	s_mov_b32 m0, s41
	s_nop 0
	global_load_lds_dwordx4 v[240:241], off
	s_nop 0
	s_nop 0
	s_waitcnt vmcnt(8)
	s_waitcnt lgkmcnt(0)
	s_barrier
; #define PG8_STAGE(bufoff, gbase, voff) do { _Pragma("unroll") for (int _i = 0; _i < 2; ++_i) \
;         __builtin_amdgcn_global_load_lds((const unsigned*)((const char*)(gbase) + (voff)[_i]), (LAS unsigned*)(lds + (bufoff) + ldsw + _i * 8192), 16, 0, 0); } while (0)
; #define PG8_LDA(dst, b, h) do { _Pragma("unroll") for (int m = 0; m < 4; ++m) _Pragma("unroll") for (int k = 0; k < 2; ++k) dst[m][k] = *(const LAS bf16x8*)(lds + PG8_SA(b, h) + aoff + m * 2048 + k * 1024); } while (0)
; #define PG8_LDB(dst, b, h) do { _Pragma("unroll") for (int n = 0; n < 2; ++n) _Pragma("unroll") for (int k = 0; k < 2; ++k) dst[n][k] = *(const LAS bf16x8*)(lds + PG8_SB(b, h) + boff + n * 2048 + k * 1024); } while (0)
; #define PG8_MMA(ai, bj, At, Bt) do { __builtin_amdgcn_s_setprio(1); _Pragma("unroll") for (int m = 0; m < 4; ++m) _Pragma("unroll") for (int n = 0; n < 2; ++n) _Pragma("unroll") for (int k = 0; k < 2; ++k) \
;         acc[ai][bj][m][n] = __builtin_amdgcn_mfma_f32_16x16x32_bf16(Bt[n][k], At[m][k], acc[ai][bj][m][n], 0, 0, 0); __builtin_amdgcn_s_setprio(0); } while (0)
; #define PG8_WAIT_V(n) asm volatile("s_waitcnt vmcnt(" #n ")" ::: "memory")
; #define PG8_WAIT_L(n) asm volatile("s_waitcnt lgkmcnt(" #n ")" ::: "memory")
; #define PG8_BAR __builtin_amdgcn_s_barrier()
; #define PG8_SCHED __builtin_amdgcn_sched_barrier(0)
; template <class Epi, class Sched>
; __device__ __forceinline__ void gemm_phase(LAS unsigned char* lds, const Gemm g, const Sched& S, const Epi& E) {
;     ...
;             PG8_WAIT_V(8); PG8_WAIT_L(0); PG8_BAR; PG8_MMA(1, 0, At, B0); PG8_MMA(1, 1, At, B1); PG8_BAR; PG8_SCHED;
;             PG8_LDB(B0, 1, 0); PG8_LDB(B1, 1, 1); PG8_SCHED; PG8_LDA(At, 1, 0); PG8_STAGE(PG8_SA(0, 1), a2 + hstepA, voffA);
;             PG8_WAIT_V(8); PG8_WAIT_L(0); PG8_BAR; PG8_MMA(0, 0, At, B0); PG8_MMA(0, 1, At, B1); PG8_BAR; PG8_SCHED;
	s_setprio 1
	s_waitcnt lgkmcnt(0)
	v_mfma_f32_16x16x32_bf16 v[62:65], v[142:145], v[190:193], v[62:65]
	v_mfma_f32_16x16x32_bf16 v[58:61], v[166:169], v[190:193], v[58:61]
	v_mfma_f32_16x16x32_bf16 v[50:53], v[142:145], v[212:215], v[50:53]
	v_mfma_f32_16x16x32_bf16 v[42:45], v[166:169], v[212:215], v[42:45]
	v_mfma_f32_16x16x32_bf16 v[34:37], v[142:145], v[220:223], v[34:37]
	v_mfma_f32_16x16x32_bf16 v[26:29], v[166:169], v[220:223], v[26:29]
	v_mfma_f32_16x16x32_bf16 v[18:21], v[142:145], v[228:231], v[18:21]
	v_mfma_f32_16x16x32_bf16 v[10:13], v[166:169], v[228:231], v[10:13]
	v_mfma_f32_16x16x32_bf16 v[62:65], v[162:165], v[208:211], v[62:65]
	v_mfma_f32_16x16x32_bf16 v[58:61], v[170:173], v[208:211], v[58:61]
	v_mfma_f32_16x16x32_bf16 v[50:53], v[162:165], v[216:219], v[50:53]
	v_mfma_f32_16x16x32_bf16 v[42:45], v[170:173], v[216:219], v[42:45]
	v_mfma_f32_16x16x32_bf16 v[34:37], v[162:165], v[224:227], v[34:37]
	v_mfma_f32_16x16x32_bf16 v[26:29], v[170:173], v[224:227], v[26:29]
	v_mfma_f32_16x16x32_bf16 v[18:21], v[162:165], v[232:235], v[18:21]
	v_mfma_f32_16x16x32_bf16 v[10:13], v[170:173], v[232:235], v[10:13]
	s_setprio 0
	s_setprio 1
	v_mfma_f32_16x16x32_bf16 v[54:57], v[174:177], v[190:193], v[54:57]
	v_mfma_f32_16x16x32_bf16 v[46:49], v[182:185], v[190:193], v[46:49]
	v_mfma_f32_16x16x32_bf16 v[38:41], v[174:177], v[212:215], v[38:41]
	v_mfma_f32_16x16x32_bf16 v[30:33], v[182:185], v[212:215], v[30:33]
	v_mfma_f32_16x16x32_bf16 v[22:25], v[174:177], v[220:223], v[22:25]
	v_mfma_f32_16x16x32_bf16 v[14:17], v[182:185], v[220:223], v[14:17]
	v_mfma_f32_16x16x32_bf16 v[6:9], v[174:177], v[228:231], v[6:9]
	v_mfma_f32_16x16x32_bf16 v[2:5], v[182:185], v[228:231], v[2:5]
	v_mfma_f32_16x16x32_bf16 v[54:57], v[178:181], v[208:211], v[54:57]
	v_mfma_f32_16x16x32_bf16 v[46:49], v[186:189], v[208:211], v[46:49]
	v_mfma_f32_16x16x32_bf16 v[38:41], v[178:181], v[216:219], v[38:41]
	v_mfma_f32_16x16x32_bf16 v[30:33], v[186:189], v[216:219], v[30:33]
	v_mfma_f32_16x16x32_bf16 v[22:25], v[178:181], v[224:227], v[22:25]
	v_mfma_f32_16x16x32_bf16 v[14:17], v[186:189], v[224:227], v[14:17]
	v_mfma_f32_16x16x32_bf16 v[6:9], v[178:181], v[232:235], v[6:9]
	v_mfma_f32_16x16x32_bf16 v[2:5], v[186:189], v[232:235], v[2:5]
	s_setprio 0
	s_barrier
	v_add_u32_e32 v141, s58, v1
	ds_read_b128 v[142:145], v141
	ds_read_b128 v[162:165], v141 offset:1024
	ds_read_b128 v[166:169], v141 offset:2048
	ds_read_b128 v[170:173], v141 offset:3072
	v_add_u32_e32 v141, s57, v1
	ds_read_b128 v[174:177], v141
	ds_read_b128 v[178:181], v141 offset:1024
	ds_read_b128 v[182:185], v141 offset:2048
	ds_read_b128 v[186:189], v141 offset:3072
	s_mov_b32 m0, s42
	v_lshl_add_u64 v[242:243], s[22:23], 0, v[136:137]
	ds_read_b128 v[190:193], v140 offset:32768
	ds_read_b128 v[208:211], v140 offset:33792
	ds_read_b128 v[212:215], v140 offset:34816
	ds_read_b128 v[216:219], v140 offset:35840
	ds_read_b128 v[220:223], v140 offset:36864
	ds_read_b128 v[224:227], v140 offset:37888
	ds_read_b128 v[228:231], v140 offset:38912
	ds_read_b128 v[232:235], v140 offset:39936
	global_load_lds_dwordx4 v[242:243], off
	v_lshl_add_u64 v[242:243], s[22:23], 0, v[132:133]
	s_mov_b32 m0, s43
	s_nop 0
	global_load_lds_dwordx4 v[242:243], off
	s_nop 0
	s_nop 0
	s_waitcnt vmcnt(8)
	s_waitcnt lgkmcnt(0)
	s_barrier
	s_setprio 1
	s_waitcnt lgkmcnt(0)
	v_mfma_f32_16x16x32_bf16 v[126:129], v[142:145], v[190:193], v[126:129]
	v_mfma_f32_16x16x32_bf16 v[122:125], v[166:169], v[190:193], v[122:125]
	v_mfma_f32_16x16x32_bf16 v[114:117], v[142:145], v[212:215], v[114:117]
	v_mfma_f32_16x16x32_bf16 v[106:109], v[166:169], v[212:215], v[106:109]
	v_mfma_f32_16x16x32_bf16 v[98:101], v[142:145], v[220:223], v[98:101]
	v_mfma_f32_16x16x32_bf16 v[90:93], v[166:169], v[220:223], v[90:93]
	v_mfma_f32_16x16x32_bf16 v[78:81], v[142:145], v[228:231], v[78:81]
	v_mfma_f32_16x16x32_bf16 v[74:77], v[166:169], v[228:231], v[74:77]
	v_mfma_f32_16x16x32_bf16 v[126:129], v[162:165], v[208:211], v[126:129]
	v_mfma_f32_16x16x32_bf16 v[122:125], v[170:173], v[208:211], v[122:125]
	v_mfma_f32_16x16x32_bf16 v[114:117], v[162:165], v[216:219], v[114:117]
	v_mfma_f32_16x16x32_bf16 v[106:109], v[170:173], v[216:219], v[106:109]
	v_mfma_f32_16x16x32_bf16 v[98:101], v[162:165], v[224:227], v[98:101]
	v_mfma_f32_16x16x32_bf16 v[90:93], v[170:173], v[224:227], v[90:93]
	v_mfma_f32_16x16x32_bf16 v[78:81], v[162:165], v[232:235], v[78:81]
	v_mfma_f32_16x16x32_bf16 v[74:77], v[170:173], v[232:235], v[74:77]
	s_setprio 0
	s_setprio 1
	v_mfma_f32_16x16x32_bf16 v[118:121], v[174:177], v[190:193], v[118:121]
	v_mfma_f32_16x16x32_bf16 v[110:113], v[182:185], v[190:193], v[110:113]
	v_mfma_f32_16x16x32_bf16 v[102:105], v[174:177], v[212:215], v[102:105]
	v_mfma_f32_16x16x32_bf16 v[94:97], v[182:185], v[212:215], v[94:97]
	v_mfma_f32_16x16x32_bf16 v[86:89], v[174:177], v[220:223], v[86:89]
	v_mfma_f32_16x16x32_bf16 v[82:85], v[182:185], v[220:223], v[82:85]
	v_mfma_f32_16x16x32_bf16 v[70:73], v[174:177], v[228:231], v[70:73]
	v_mfma_f32_16x16x32_bf16 v[66:69], v[182:185], v[228:231], v[66:69]
	v_mfma_f32_16x16x32_bf16 v[118:121], v[178:181], v[208:211], v[118:121]
	v_mfma_f32_16x16x32_bf16 v[110:113], v[186:189], v[208:211], v[110:113]
	v_mfma_f32_16x16x32_bf16 v[102:105], v[178:181], v[216:219], v[102:105]
	v_mfma_f32_16x16x32_bf16 v[94:97], v[186:189], v[216:219], v[94:97]
	v_mfma_f32_16x16x32_bf16 v[86:89], v[178:181], v[224:227], v[86:89]
	v_mfma_f32_16x16x32_bf16 v[82:85], v[186:189], v[224:227], v[82:85]
	v_mfma_f32_16x16x32_bf16 v[70:73], v[178:181], v[232:235], v[70:73]
	v_mfma_f32_16x16x32_bf16 v[66:69], v[186:189], v[232:235], v[66:69]
	s_setprio 0
	s_barrier
; #define PG8_STAGE(bufoff, gbase, voff) do { _Pragma("unroll") for (int _i = 0; _i < 2; ++_i) \
;         __builtin_amdgcn_global_load_lds((const unsigned*)((const char*)(gbase) + (voff)[_i]), (LAS unsigned*)(lds + (bufoff) + ldsw + _i * 8192), 16, 0, 0); } while (0)
; #define PG8_LDA(dst, b, h) do { _Pragma("unroll") for (int m = 0; m < 4; ++m) _Pragma("unroll") for (int k = 0; k < 2; ++k) dst[m][k] = *(const LAS bf16x8*)(lds + PG8_SA(b, h) + aoff + m * 2048 + k * 1024); } while (0)
; #define PG8_MMA(ai, bj, At, Bt) do { __builtin_amdgcn_s_setprio(1); _Pragma("unroll") for (int m = 0; m < 4; ++m) _Pragma("unroll") for (int n = 0; n < 2; ++n) _Pragma("unroll") for (int k = 0; k < 2; ++k) \
;         acc[ai][bj][m][n] = __builtin_amdgcn_mfma_f32_16x16x32_bf16(Bt[n][k], At[m][k], acc[ai][bj][m][n], 0, 0, 0); __builtin_amdgcn_s_setprio(0); } while (0)
; #define PG8_WAIT_V(n) asm volatile("s_waitcnt vmcnt(" #n ")" ::: "memory")
; #define PG8_WAIT_L(n) asm volatile("s_waitcnt lgkmcnt(" #n ")" ::: "memory")
; #define PG8_BAR __builtin_amdgcn_s_barrier()
; #define PG8_SCHED __builtin_amdgcn_sched_barrier(0)
; template <class Epi, class Sched>
; __device__ __forceinline__ void gemm_phase(LAS unsigned char* lds, const Gemm g, const Sched& S, const Epi& E) {
;     ...
;             PG8_LDA(At, 1, 1); PG8_STAGE(PG8_SB(1, 0), b3, voffB); PG8_STAGE(PG8_SB(1, 1), b3 + hstepB, voffB); PG8_STAGE(PG8_SA(1, 0), a3, voffA);
;             PG8_WAIT_V(8); PG8_WAIT_L(0); PG8_BAR; PG8_MMA(1, 0, At, B0); PG8_MMA(1, 1, At, B1); PG8_BAR; PG8_SCHED;
;         }
;         if (wr == 0) PG8_BAR;
	s_mov_b32 m0, s56
	v_lshl_add_u64 v[138:139], v[138:139], 0, s[68:69]
	ds_read_b128 v[190:193], v140 offset:49152
	ds_read_b128 v[208:211], v140 offset:50176
	ds_read_b128 v[212:215], v140 offset:51200
	ds_read_b128 v[216:219], v140 offset:52224
	ds_read_b128 v[220:223], v140 offset:53248
	ds_read_b128 v[224:227], v140 offset:54272
	ds_read_b128 v[228:231], v140 offset:55296
	ds_read_b128 v[232:235], v140 offset:56320
	global_load_lds_dwordx4 v[138:139], off
	v_lshl_add_u64 v[138:139], v[236:237], 0, s[68:69]
	s_mov_b32 m0, s55
	s_nop 0
	global_load_lds_dwordx4 v[138:139], off
	v_lshl_add_u64 v[138:139], s[20:21], 0, v[134:135]
	s_mov_b32 m0, s64
	s_nop 0
	global_load_lds_dwordx4 v[138:139], off
	v_lshl_add_u64 v[138:139], s[20:21], 0, v[130:131]
	s_mov_b32 m0, s63
	s_nop 0
	global_load_lds_dwordx4 v[138:139], off
	v_lshl_add_u64 v[138:139], v[238:239], 0, s[68:69]
	s_mov_b32 m0, s46
	s_nop 0
	global_load_lds_dwordx4 v[138:139], off
	v_lshl_add_u64 v[138:139], v[240:241], 0, s[68:69]
	s_mov_b32 m0, s47
	s_nop 0
	global_load_lds_dwordx4 v[138:139], off
	s_waitcnt vmcnt(8)
	s_waitcnt lgkmcnt(0)
	s_barrier
	s_setprio 1
	s_waitcnt lgkmcnt(0)
	v_mfma_f32_16x16x32_bf16 v[62:65], v[142:145], v[190:193], v[62:65]
	v_mfma_f32_16x16x32_bf16 v[58:61], v[166:169], v[190:193], v[58:61]
	v_mfma_f32_16x16x32_bf16 v[50:53], v[142:145], v[212:215], v[50:53]
	v_mfma_f32_16x16x32_bf16 v[42:45], v[166:169], v[212:215], v[42:45]
	v_mfma_f32_16x16x32_bf16 v[34:37], v[142:145], v[220:223], v[34:37]
	v_mfma_f32_16x16x32_bf16 v[26:29], v[166:169], v[220:223], v[26:29]
	v_mfma_f32_16x16x32_bf16 v[18:21], v[142:145], v[228:231], v[18:21]
	v_mfma_f32_16x16x32_bf16 v[10:13], v[166:169], v[228:231], v[10:13]
	v_mfma_f32_16x16x32_bf16 v[62:65], v[162:165], v[208:211], v[62:65]
	v_mfma_f32_16x16x32_bf16 v[58:61], v[170:173], v[208:211], v[58:61]
	v_mfma_f32_16x16x32_bf16 v[50:53], v[162:165], v[216:219], v[50:53]
	v_mfma_f32_16x16x32_bf16 v[42:45], v[170:173], v[216:219], v[42:45]
	v_mfma_f32_16x16x32_bf16 v[34:37], v[162:165], v[224:227], v[34:37]
	v_mfma_f32_16x16x32_bf16 v[26:29], v[170:173], v[224:227], v[26:29]
	v_mfma_f32_16x16x32_bf16 v[18:21], v[162:165], v[232:235], v[18:21]
	v_mfma_f32_16x16x32_bf16 v[10:13], v[170:173], v[232:235], v[10:13]
	s_setprio 0
	s_setprio 1
	v_mfma_f32_16x16x32_bf16 v[54:57], v[174:177], v[190:193], v[54:57]
	v_mfma_f32_16x16x32_bf16 v[46:49], v[182:185], v[190:193], v[46:49]
	v_mfma_f32_16x16x32_bf16 v[38:41], v[174:177], v[212:215], v[38:41]
	v_mfma_f32_16x16x32_bf16 v[30:33], v[182:185], v[212:215], v[30:33]
	v_mfma_f32_16x16x32_bf16 v[22:25], v[174:177], v[220:223], v[22:25]
	v_mfma_f32_16x16x32_bf16 v[14:17], v[182:185], v[220:223], v[14:17]
	v_mfma_f32_16x16x32_bf16 v[6:9], v[174:177], v[228:231], v[6:9]
	v_mfma_f32_16x16x32_bf16 v[2:5], v[182:185], v[228:231], v[2:5]
	v_mfma_f32_16x16x32_bf16 v[54:57], v[178:181], v[208:211], v[54:57]
	v_mfma_f32_16x16x32_bf16 v[46:49], v[186:189], v[208:211], v[46:49]
	v_mfma_f32_16x16x32_bf16 v[38:41], v[178:181], v[216:219], v[38:41]
	v_mfma_f32_16x16x32_bf16 v[30:33], v[186:189], v[216:219], v[30:33]
	v_mfma_f32_16x16x32_bf16 v[22:25], v[178:181], v[224:227], v[22:25]
	v_mfma_f32_16x16x32_bf16 v[14:17], v[186:189], v[224:227], v[14:17]
	v_mfma_f32_16x16x32_bf16 v[6:9], v[178:181], v[232:235], v[6:9]
	v_mfma_f32_16x16x32_bf16 v[2:5], v[186:189], v[232:235], v[2:5]
	s_setprio 0
	s_barrier
	s_movk_i32 s22, 0x100
	s_andn2_b64 vcc, exec, s[18:19]
	s_mov_b64 s[20:21], -1
	s_mov_b64 s[18:19], 0
	s_cbranch_vccz .LBB0_4132
	s_and_b64 vcc, exec, s[4:5]
	s_mov_b32 s55, s67
	s_cbranch_vccz .LBB0_4135
	s_barrier

; #define PG8_STAGE(bufoff, gbase, voff) do { _Pragma("unroll") for (int _i = 0; _i < 2; ++_i) \
;         __builtin_amdgcn_global_load_lds((const unsigned*)((const char*)(gbase) + (voff)[_i]), (LAS unsigned*)(lds + (bufoff) + ldsw + _i * 8192), 16, 0, 0); } while (0)
; #define PG8_LDA(dst, b, h) do { _Pragma("unroll") for (int m = 0; m < 4; ++m) _Pragma("unroll") for (int k = 0; k < 2; ++k) dst[m][k] = *(const LAS bf16x8*)(lds + PG8_SA(b, h) + aoff + m * 2048 + k * 1024); } while (0)
; #define PG8_LDB(dst, b, h) do { _Pragma("unroll") for (int n = 0; n < 2; ++n) _Pragma("unroll") for (int k = 0; k < 2; ++k) dst[n][k] = *(const LAS bf16x8*)(lds + PG8_SB(b, h) + boff + n * 2048 + k * 1024); } while (0)
; #define PG8_MMA(ai, bj, At, Bt) do { __builtin_amdgcn_s_setprio(1); _Pragma("unroll") for (int m = 0; m < 4; ++m) _Pragma("unroll") for (int n = 0; n < 2; ++n) _Pragma("unroll") for (int k = 0; k < 2; ++k) \
;         acc[ai][bj][m][n] = __builtin_amdgcn_mfma_f32_16x16x32_bf16(Bt[n][k], At[m][k], acc[ai][bj][m][n], 0, 0, 0); __builtin_amdgcn_s_setprio(0); } while (0)
; #define PG8_WAIT_V(n) asm volatile("s_waitcnt vmcnt(" #n ")" ::: "memory")
; #define PG8_WAIT_L(n) asm volatile("s_waitcnt lgkmcnt(" #n ")" ::: "memory")
; #define PG8_BAR __builtin_amdgcn_s_barrier()
; #define PG8_SCHED __builtin_amdgcn_sched_barrier(0)
; template <class Epi, class Sched>
; __device__ __forceinline__ void gemm_phase(LAS unsigned char* lds, const Gemm g, const Sched& S, const Epi& E) {
;     ...
;             const bool last = (t == nt - 2);
;             const char* a1 = cA + (size_t)(t + 1) * kstep;
;             const char* a2 = last ? nA : cA + (size_t)(t + 2) * kstep; const char* b2 = last ? nB : cB + (size_t)(t + 2) * kstep;
;             const char* a3 = a2 + kstep; const char* b3 = b2 + kstep;
;             PG8_LDB(B0, 0, 0); PG8_LDB(B1, 0, 1); PG8_SCHED; PG8_LDA(At, 0, 0); PG8_STAGE(PG8_SA(1, 1), a1 + hstepA, voffA);
;             PG8_WAIT_V(8); PG8_WAIT_L(0); PG8_BAR; PG8_MMA(0, 0, At, B0); PG8_MMA(0, 1, At, B1); PG8_BAR; PG8_SCHED;
;             PG8_LDA(At, 0, 1); PG8_STAGE(PG8_SB(0, 0), b2, voffB); PG8_STAGE(PG8_SB(0, 1), b2 + hstepB, voffB); PG8_STAGE(PG8_SA(0, 0), a2, voffA);
.LBB0_4223:
	s_add_u32 s16, s14, 0xfff80080
	s_addc_u32 s17, s15, -1
	s_add_i32 s44, 0, 0x10000
	s_cmp_eq_u32 s43, 28
	s_cselect_b32 s19, s7, s17
	s_cselect_b32 s18, s39, s16
	v_add_u32_e32 v167, s44, v1
	s_cselect_b32 s17, s5, s42
	s_cselect_b32 s16, s40, s41
	s_add_i32 s46, 0, 0x14000
	ds_read_b128 v[142:145], v167
	ds_read_b128 v[162:165], v167 offset:1024
	ds_read_b128 v[168:171], v167 offset:2048
	ds_read_b128 v[172:175], v167 offset:3072
	v_add_u32_e32 v167, s46, v1
	ds_read_b128 v[176:179], v167
	ds_read_b128 v[180:183], v167 offset:1024
	ds_read_b128 v[184:187], v167 offset:2048
	ds_read_b128 v[188:191], v167 offset:3072
	v_lshl_add_u64 v[192:193], s[14:15], 0, v[138:139]
	s_add_i32 m0, s25, 0xc000
	ds_read_b128 v[208:211], v166
	ds_read_b128 v[212:215], v166 offset:1024
	ds_read_b128 v[216:219], v166 offset:2048
	ds_read_b128 v[220:223], v166 offset:3072
	ds_read_b128 v[224:227], v166 offset:4096
	ds_read_b128 v[228:231], v166 offset:5120
	ds_read_b128 v[232:235], v166 offset:6144
	ds_read_b128 v[236:239], v166 offset:7168
	global_load_lds_dwordx4 v[192:193], off
	v_lshl_add_u64 v[192:193], s[14:15], 0, v[140:141]
	s_add_i32 m0, s25, 0xe000
	s_nop 0
	global_load_lds_dwordx4 v[192:193], off
	s_nop 0
	s_nop 0
	s_waitcnt vmcnt(8)
	s_waitcnt lgkmcnt(0)
	s_barrier
	s_setprio 1
	s_waitcnt lgkmcnt(0)
	v_mfma_f32_16x16x32_bf16 v[126:129], v[142:145], v[208:211], v[126:129]
	v_mfma_f32_16x16x32_bf16 v[122:125], v[168:171], v[208:211], v[122:125]
	v_mfma_f32_16x16x32_bf16 v[110:113], v[142:145], v[216:219], v[110:113]
	v_mfma_f32_16x16x32_bf16 v[106:109], v[168:171], v[216:219], v[106:109]
	v_mfma_f32_16x16x32_bf16 v[94:97], v[142:145], v[224:227], v[94:97]
	v_mfma_f32_16x16x32_bf16 v[90:93], v[168:171], v[224:227], v[90:93]
	v_mfma_f32_16x16x32_bf16 v[78:81], v[142:145], v[232:235], v[78:81]
	v_mfma_f32_16x16x32_bf16 v[74:77], v[168:171], v[232:235], v[74:77]
	v_mfma_f32_16x16x32_bf16 v[126:129], v[162:165], v[212:215], v[126:129]
	v_mfma_f32_16x16x32_bf16 v[122:125], v[172:175], v[212:215], v[122:125]
	v_mfma_f32_16x16x32_bf16 v[110:113], v[162:165], v[220:223], v[110:113]
	v_mfma_f32_16x16x32_bf16 v[106:109], v[172:175], v[220:223], v[106:109]
	v_mfma_f32_16x16x32_bf16 v[94:97], v[162:165], v[228:231], v[94:97]
	v_mfma_f32_16x16x32_bf16 v[90:93], v[172:175], v[228:231], v[90:93]
	v_mfma_f32_16x16x32_bf16 v[78:81], v[162:165], v[236:239], v[78:81]
	v_mfma_f32_16x16x32_bf16 v[74:77], v[172:175], v[236:239], v[74:77]
	s_setprio 0
	s_setprio 1
	v_mfma_f32_16x16x32_bf16 v[118:121], v[176:179], v[208:211], v[118:121]
	v_mfma_f32_16x16x32_bf16 v[114:117], v[184:187], v[208:211], v[114:117]
	v_mfma_f32_16x16x32_bf16 v[102:105], v[176:179], v[216:219], v[102:105]
	v_mfma_f32_16x16x32_bf16 v[98:101], v[184:187], v[216:219], v[98:101]
	v_mfma_f32_16x16x32_bf16 v[86:89], v[176:179], v[224:227], v[86:89]
	v_mfma_f32_16x16x32_bf16 v[82:85], v[184:187], v[224:227], v[82:85]
	v_mfma_f32_16x16x32_bf16 v[70:73], v[176:179], v[232:235], v[70:73]
	v_mfma_f32_16x16x32_bf16 v[66:69], v[184:187], v[232:235], v[66:69]
	v_mfma_f32_16x16x32_bf16 v[118:121], v[180:183], v[212:215], v[118:121]
	v_mfma_f32_16x16x32_bf16 v[114:117], v[188:191], v[212:215], v[114:117]
	v_mfma_f32_16x16x32_bf16 v[102:105], v[180:183], v[220:223], v[102:105]
	v_mfma_f32_16x16x32_bf16 v[98:101], v[188:191], v[220:223], v[98:101]
	v_mfma_f32_16x16x32_bf16 v[86:89], v[180:183], v[228:231], v[86:89]
	v_mfma_f32_16x16x32_bf16 v[82:85], v[188:191], v[228:231], v[82:85]
	v_mfma_f32_16x16x32_bf16 v[70:73], v[180:183], v[236:239], v[70:73]
	v_mfma_f32_16x16x32_bf16 v[66:69], v[188:191], v[236:239], v[66:69]
	s_setprio 0
	s_barrier
	s_add_i32 s44, s44, s22
	v_lshl_add_u64 v[192:193], s[16:17], 0, v[134:135]
	s_mov_b32 m0, s44
	ds_read_b128 v[208:211], v166 offset:16384
	ds_read_b128 v[212:215], v166 offset:17408
	ds_read_b128 v[216:219], v166 offset:18432
	ds_read_b128 v[220:223], v166 offset:19456
	ds_read_b128 v[224:227], v166 offset:20480
	ds_read_b128 v[228:231], v166 offset:21504
	ds_read_b128 v[232:235], v166 offset:22528
	ds_read_b128 v[236:239], v166 offset:23552
	global_load_lds_dwordx4 v[192:193], off
	s_add_i32 m0, s44, 0x2000
	s_add_u32 s44, s16, 0x80000
	v_lshl_add_u64 v[240:241], s[16:17], 0, v[130:131]
	s_addc_u32 s45, s17, 0
	s_add_i32 s46, s46, s22
	global_load_lds_dwordx4 v[240:241], off
	v_lshl_add_u64 v[242:243], s[44:45], 0, v[134:135]
	s_mov_b32 m0, s46
	v_lshl_add_u64 v[244:245], s[18:19], 0, v[132:133]
	global_load_lds_dwordx4 v[242:243], off
	v_lshl_add_u64 v[242:243], s[44:45], 0, v[130:131]
	s_add_i32 m0, s46, 0x2000
	s_nop 0
	global_load_lds_dwordx4 v[242:243], off
	v_lshl_add_u64 v[242:243], s[18:19], 0, v[136:137]
	s_mov_b32 m0, s25
	s_nop 0
	global_load_lds_dwordx4 v[242:243], off
	s_mov_b32 m0, s26
	s_nop 0
	global_load_lds_dwordx4 v[244:245], off
	s_nop 0
	s_nop 0
	s_nop 0
	s_waitcnt vmcnt(8)
	s_waitcnt lgkmcnt(0)
	s_barrier
; #define PG8_STAGE(bufoff, gbase, voff) do { _Pragma("unroll") for (int _i = 0; _i < 2; ++_i) \
;         __builtin_amdgcn_global_load_lds((const unsigned*)((const char*)(gbase) + (voff)[_i]), (LAS unsigned*)(lds + (bufoff) + ldsw + _i * 8192), 16, 0, 0); } while (0)
; #define PG8_LDA(dst, b, h) do { _Pragma("unroll") for (int m = 0; m < 4; ++m) _Pragma("unroll") for (int k = 0; k < 2; ++k) dst[m][k] = *(const LAS bf16x8*)(lds + PG8_SA(b, h) + aoff + m * 2048 + k * 1024); } while (0)
; #define PG8_LDB(dst, b, h) do { _Pragma("unroll") for (int n = 0; n < 2; ++n) _Pragma("unroll") for (int k = 0; k < 2; ++k) dst[n][k] = *(const LAS bf16x8*)(lds + PG8_SB(b, h) + boff + n * 2048 + k * 1024); } while (0)
; #define PG8_MMA(ai, bj, At, Bt) do { __builtin_amdgcn_s_setprio(1); _Pragma("unroll") for (int m = 0; m < 4; ++m) _Pragma("unroll") for (int n = 0; n < 2; ++n) _Pragma("unroll") for (int k = 0; k < 2; ++k) \
;         acc[ai][bj][m][n] = __builtin_amdgcn_mfma_f32_16x16x32_bf16(Bt[n][k], At[m][k], acc[ai][bj][m][n], 0, 0, 0); __builtin_amdgcn_s_setprio(0); } while (0)
; #define PG8_WAIT_V(n) asm volatile("s_waitcnt vmcnt(" #n ")" ::: "memory")
; #define PG8_WAIT_L(n) asm volatile("s_waitcnt lgkmcnt(" #n ")" ::: "memory")
; #define PG8_BAR __builtin_amdgcn_s_barrier()
; #define PG8_SCHED __builtin_amdgcn_sched_barrier(0)
; template <class Epi, class Sched>
; __device__ __forceinline__ void gemm_phase(LAS unsigned char* lds, const Gemm g, const Sched& S, const Epi& E) {
;     ...
;             PG8_WAIT_V(8); PG8_WAIT_L(0); PG8_BAR; PG8_MMA(1, 0, At, B0); PG8_MMA(1, 1, At, B1); PG8_BAR; PG8_SCHED;
;             PG8_LDB(B0, 1, 0); PG8_LDB(B1, 1, 1); PG8_SCHED; PG8_LDA(At, 1, 0); PG8_STAGE(PG8_SA(0, 1), a2 + hstepA, voffA);
;             PG8_WAIT_V(8); PG8_WAIT_L(0); PG8_BAR; PG8_MMA(0, 0, At, B0); PG8_MMA(0, 1, At, B1); PG8_BAR; PG8_SCHED;
	s_setprio 1
	s_waitcnt lgkmcnt(0)
	v_mfma_f32_16x16x32_bf16 v[62:65], v[142:145], v[208:211], v[62:65]
	v_mfma_f32_16x16x32_bf16 v[58:61], v[168:171], v[208:211], v[58:61]
	v_mfma_f32_16x16x32_bf16 v[46:49], v[142:145], v[216:219], v[46:49]
	v_mfma_f32_16x16x32_bf16 v[42:45], v[168:171], v[216:219], v[42:45]
	v_mfma_f32_16x16x32_bf16 v[30:33], v[142:145], v[224:227], v[30:33]
	v_mfma_f32_16x16x32_bf16 v[26:29], v[168:171], v[224:227], v[26:29]
	v_mfma_f32_16x16x32_bf16 v[14:17], v[142:145], v[232:235], v[14:17]
	v_mfma_f32_16x16x32_bf16 v[10:13], v[168:171], v[232:235], v[10:13]
	v_mfma_f32_16x16x32_bf16 v[62:65], v[162:165], v[212:215], v[62:65]
	v_mfma_f32_16x16x32_bf16 v[58:61], v[172:175], v[212:215], v[58:61]
	v_mfma_f32_16x16x32_bf16 v[46:49], v[162:165], v[220:223], v[46:49]
	v_mfma_f32_16x16x32_bf16 v[42:45], v[172:175], v[220:223], v[42:45]
	v_mfma_f32_16x16x32_bf16 v[30:33], v[162:165], v[228:231], v[30:33]
	v_mfma_f32_16x16x32_bf16 v[26:29], v[172:175], v[228:231], v[26:29]
	v_mfma_f32_16x16x32_bf16 v[14:17], v[162:165], v[236:239], v[14:17]
	v_mfma_f32_16x16x32_bf16 v[10:13], v[172:175], v[236:239], v[10:13]
	s_setprio 0
	s_setprio 1
	v_mfma_f32_16x16x32_bf16 v[54:57], v[176:179], v[208:211], v[54:57]
	v_mfma_f32_16x16x32_bf16 v[50:53], v[184:187], v[208:211], v[50:53]
	v_mfma_f32_16x16x32_bf16 v[38:41], v[176:179], v[216:219], v[38:41]
	v_mfma_f32_16x16x32_bf16 v[34:37], v[184:187], v[216:219], v[34:37]
	v_mfma_f32_16x16x32_bf16 v[22:25], v[176:179], v[224:227], v[22:25]
	v_mfma_f32_16x16x32_bf16 v[18:21], v[184:187], v[224:227], v[18:21]
	v_mfma_f32_16x16x32_bf16 v[6:9], v[176:179], v[232:235], v[6:9]
	v_mfma_f32_16x16x32_bf16 v[2:5], v[184:187], v[232:235], v[2:5]
	v_mfma_f32_16x16x32_bf16 v[54:57], v[180:183], v[212:215], v[54:57]
	v_mfma_f32_16x16x32_bf16 v[50:53], v[188:191], v[212:215], v[50:53]
	v_mfma_f32_16x16x32_bf16 v[38:41], v[180:183], v[220:223], v[38:41]
	v_mfma_f32_16x16x32_bf16 v[34:37], v[188:191], v[220:223], v[34:37]
	v_mfma_f32_16x16x32_bf16 v[22:25], v[180:183], v[228:231], v[22:25]
	v_mfma_f32_16x16x32_bf16 v[18:21], v[188:191], v[228:231], v[18:21]
	v_mfma_f32_16x16x32_bf16 v[6:9], v[180:183], v[236:239], v[6:9]
	v_mfma_f32_16x16x32_bf16 v[2:5], v[188:191], v[236:239], v[2:5]
	s_setprio 0
	s_barrier
	s_add_i32 s44, 0, 0x18000
	v_add_u32_e32 v167, s44, v1
	s_add_i32 s45, 0, 0x1c000
	ds_read_b128 v[142:145], v167
	ds_read_b128 v[162:165], v167 offset:1024
	ds_read_b128 v[168:171], v167 offset:2048
	ds_read_b128 v[172:175], v167 offset:3072
	v_add_u32_e32 v167, s45, v1
	ds_read_b128 v[176:179], v167
	ds_read_b128 v[180:183], v167 offset:1024
	ds_read_b128 v[184:187], v167 offset:2048
	ds_read_b128 v[188:191], v167 offset:3072
	s_add_u32 s18, s18, 0x80000
	s_addc_u32 s19, s19, 0
	s_mov_b32 m0, s27
	v_lshl_add_u64 v[246:247], s[18:19], 0, v[136:137]
	ds_read_b128 v[208:211], v166 offset:32768
	ds_read_b128 v[212:215], v166 offset:33792
	ds_read_b128 v[216:219], v166 offset:34816
	ds_read_b128 v[220:223], v166 offset:35840
	ds_read_b128 v[224:227], v166 offset:36864
	ds_read_b128 v[228:231], v166 offset:37888
	ds_read_b128 v[232:235], v166 offset:38912
	ds_read_b128 v[236:239], v166 offset:39936
	global_load_lds_dwordx4 v[246:247], off
	v_lshl_add_u64 v[246:247], s[18:19], 0, v[132:133]
	s_mov_b32 m0, s28
	s_nop 0
	global_load_lds_dwordx4 v[246:247], off
	s_nop 0
	s_nop 0
	s_nop 0
	s_waitcnt vmcnt(8)
	s_waitcnt lgkmcnt(0)
	s_barrier
	s_setprio 1
	s_waitcnt lgkmcnt(0)
	v_mfma_f32_16x16x32_bf16 v[126:129], v[142:145], v[208:211], v[126:129]
	v_mfma_f32_16x16x32_bf16 v[122:125], v[168:171], v[208:211], v[122:125]
	v_mfma_f32_16x16x32_bf16 v[110:113], v[142:145], v[216:219], v[110:113]
	v_mfma_f32_16x16x32_bf16 v[106:109], v[168:171], v[216:219], v[106:109]
	v_mfma_f32_16x16x32_bf16 v[94:97], v[142:145], v[224:227], v[94:97]
	v_mfma_f32_16x16x32_bf16 v[90:93], v[168:171], v[224:227], v[90:93]
	v_mfma_f32_16x16x32_bf16 v[78:81], v[142:145], v[232:235], v[78:81]
	v_mfma_f32_16x16x32_bf16 v[74:77], v[168:171], v[232:235], v[74:77]
	v_mfma_f32_16x16x32_bf16 v[126:129], v[162:165], v[212:215], v[126:129]
	v_mfma_f32_16x16x32_bf16 v[122:125], v[172:175], v[212:215], v[122:125]
	v_mfma_f32_16x16x32_bf16 v[110:113], v[162:165], v[220:223], v[110:113]
	v_mfma_f32_16x16x32_bf16 v[106:109], v[172:175], v[220:223], v[106:109]
	v_mfma_f32_16x16x32_bf16 v[94:97], v[162:165], v[228:231], v[94:97]
	v_mfma_f32_16x16x32_bf16 v[90:93], v[172:175], v[228:231], v[90:93]
	v_mfma_f32_16x16x32_bf16 v[78:81], v[162:165], v[236:239], v[78:81]
	v_mfma_f32_16x16x32_bf16 v[74:77], v[172:175], v[236:239], v[74:77]
	s_setprio 0
	s_setprio 1
	v_mfma_f32_16x16x32_bf16 v[118:121], v[176:179], v[208:211], v[118:121]
	v_mfma_f32_16x16x32_bf16 v[114:117], v[184:187], v[208:211], v[114:117]
	v_mfma_f32_16x16x32_bf16 v[102:105], v[176:179], v[216:219], v[102:105]
	v_mfma_f32_16x16x32_bf16 v[98:101], v[184:187], v[216:219], v[98:101]
	v_mfma_f32_16x16x32_bf16 v[86:89], v[176:179], v[224:227], v[86:89]
	v_mfma_f32_16x16x32_bf16 v[82:85], v[184:187], v[224:227], v[82:85]
	v_mfma_f32_16x16x32_bf16 v[70:73], v[176:179], v[232:235], v[70:73]
	v_mfma_f32_16x16x32_bf16 v[66:69], v[184:187], v[232:235], v[66:69]
	v_mfma_f32_16x16x32_bf16 v[118:121], v[180:183], v[212:215], v[118:121]
	v_mfma_f32_16x16x32_bf16 v[114:117], v[188:191], v[212:215], v[114:117]
	v_mfma_f32_16x16x32_bf16 v[102:105], v[180:183], v[220:223], v[102:105]
	v_mfma_f32_16x16x32_bf16 v[98:101], v[188:191], v[220:223], v[98:101]
	v_mfma_f32_16x16x32_bf16 v[86:89], v[180:183], v[228:231], v[86:89]
	v_mfma_f32_16x16x32_bf16 v[82:85], v[188:191], v[228:231], v[82:85]
	v_mfma_f32_16x16x32_bf16 v[70:73], v[180:183], v[236:239], v[70:73]
	v_mfma_f32_16x16x32_bf16 v[66:69], v[188:191], v[236:239], v[66:69]
	s_setprio 0
	s_barrier
; #define PG8_STAGE(bufoff, gbase, voff) do { _Pragma("unroll") for (int _i = 0; _i < 2; ++_i) \
;         __builtin_amdgcn_global_load_lds((const unsigned*)((const char*)(gbase) + (voff)[_i]), (LAS unsigned*)(lds + (bufoff) + ldsw + _i * 8192), 16, 0, 0); } while (0)
; #define PG8_LDA(dst, b, h) do { _Pragma("unroll") for (int m = 0; m < 4; ++m) _Pragma("unroll") for (int k = 0; k < 2; ++k) dst[m][k] = *(const LAS bf16x8*)(lds + PG8_SA(b, h) + aoff + m * 2048 + k * 1024); } while (0)
; #define PG8_MMA(ai, bj, At, Bt) do { __builtin_amdgcn_s_setprio(1); _Pragma("unroll") for (int m = 0; m < 4; ++m) _Pragma("unroll") for (int n = 0; n < 2; ++n) _Pragma("unroll") for (int k = 0; k < 2; ++k) \
;         acc[ai][bj][m][n] = __builtin_amdgcn_mfma_f32_16x16x32_bf16(Bt[n][k], At[m][k], acc[ai][bj][m][n], 0, 0, 0); __builtin_amdgcn_s_setprio(0); } while (0)
; #define PG8_WAIT_V(n) asm volatile("s_waitcnt vmcnt(" #n ")" ::: "memory")
; #define PG8_WAIT_L(n) asm volatile("s_waitcnt lgkmcnt(" #n ")" ::: "memory")
; #define PG8_BAR __builtin_amdgcn_s_barrier()
; #define PG8_SCHED __builtin_amdgcn_sched_barrier(0)
; template <class Epi, class Sched>
; __device__ __forceinline__ void gemm_phase(LAS unsigned char* lds, const Gemm g, const Sched& S, const Epi& E) {
;     ...
;             PG8_LDA(At, 1, 1); PG8_STAGE(PG8_SB(1, 0), b3, voffB); PG8_STAGE(PG8_SB(1, 1), b3 + hstepB, voffB); PG8_STAGE(PG8_SA(1, 0), a3, voffA);
;             PG8_WAIT_V(8); PG8_WAIT_L(0); PG8_BAR; PG8_MMA(1, 0, At, B0); PG8_MMA(1, 1, At, B1); PG8_BAR; PG8_SCHED;
;         }
;         if (wr == 0) PG8_BAR;
	s_add_i32 s18, s44, s22
	v_lshl_add_u64 v[192:193], v[192:193], 0, s[56:57]
	s_mov_b32 m0, s18
	ds_read_b128 v[208:211], v166 offset:49152
	ds_read_b128 v[212:215], v166 offset:50176
	ds_read_b128 v[216:219], v166 offset:51200
	ds_read_b128 v[220:223], v166 offset:52224
	ds_read_b128 v[224:227], v166 offset:53248
	ds_read_b128 v[228:231], v166 offset:54272
	ds_read_b128 v[232:235], v166 offset:55296
	ds_read_b128 v[236:239], v166 offset:56320
	global_load_lds_dwordx4 v[192:193], off
	s_add_i32 m0, s18, 0x2000
	s_add_u32 s16, s16, 0x80080
	v_lshl_add_u64 v[192:193], v[240:241], 0, s[56:57]
	s_addc_u32 s17, s17, 0
	s_add_i32 s18, s45, s22
	global_load_lds_dwordx4 v[192:193], off
	v_lshl_add_u64 v[192:193], s[16:17], 0, v[134:135]
	s_mov_b32 m0, s18
	s_nop 0
	global_load_lds_dwordx4 v[192:193], off
	v_lshl_add_u64 v[192:193], s[16:17], 0, v[130:131]
	s_add_i32 m0, s18, 0x2000
	s_nop 0
	global_load_lds_dwordx4 v[192:193], off
	v_lshl_add_u64 v[192:193], v[242:243], 0, s[56:57]
	s_mov_b32 m0, s31
	s_nop 0
	global_load_lds_dwordx4 v[192:193], off
	v_lshl_add_u64 v[192:193], v[244:245], 0, s[56:57]
	s_mov_b32 m0, s33
	s_nop 0
	global_load_lds_dwordx4 v[192:193], off
	s_nop 0
	s_nop 0
	s_waitcnt vmcnt(8)
	s_waitcnt lgkmcnt(0)
	s_barrier
	s_setprio 1
	s_waitcnt lgkmcnt(0)
	v_mfma_f32_16x16x32_bf16 v[62:65], v[142:145], v[208:211], v[62:65]
	v_mfma_f32_16x16x32_bf16 v[58:61], v[168:171], v[208:211], v[58:61]
	v_mfma_f32_16x16x32_bf16 v[46:49], v[142:145], v[216:219], v[46:49]
	v_mfma_f32_16x16x32_bf16 v[42:45], v[168:171], v[216:219], v[42:45]
	v_mfma_f32_16x16x32_bf16 v[30:33], v[142:145], v[224:227], v[30:33]
	v_mfma_f32_16x16x32_bf16 v[26:29], v[168:171], v[224:227], v[26:29]
	v_mfma_f32_16x16x32_bf16 v[14:17], v[142:145], v[232:235], v[14:17]
	v_mfma_f32_16x16x32_bf16 v[10:13], v[168:171], v[232:235], v[10:13]
	v_mfma_f32_16x16x32_bf16 v[62:65], v[162:165], v[212:215], v[62:65]
	v_mfma_f32_16x16x32_bf16 v[58:61], v[172:175], v[212:215], v[58:61]
	v_mfma_f32_16x16x32_bf16 v[46:49], v[162:165], v[220:223], v[46:49]
	v_mfma_f32_16x16x32_bf16 v[42:45], v[172:175], v[220:223], v[42:45]
	v_mfma_f32_16x16x32_bf16 v[30:33], v[162:165], v[228:231], v[30:33]
	v_mfma_f32_16x16x32_bf16 v[26:29], v[172:175], v[228:231], v[26:29]
	v_mfma_f32_16x16x32_bf16 v[14:17], v[162:165], v[236:239], v[14:17]
	v_mfma_f32_16x16x32_bf16 v[10:13], v[172:175], v[236:239], v[10:13]
	s_setprio 0
	s_setprio 1
	v_mfma_f32_16x16x32_bf16 v[54:57], v[176:179], v[208:211], v[54:57]
	v_mfma_f32_16x16x32_bf16 v[50:53], v[184:187], v[208:211], v[50:53]
	v_mfma_f32_16x16x32_bf16 v[38:41], v[176:179], v[216:219], v[38:41]
	v_mfma_f32_16x16x32_bf16 v[34:37], v[184:187], v[216:219], v[34:37]
	v_mfma_f32_16x16x32_bf16 v[22:25], v[176:179], v[224:227], v[22:25]
	v_mfma_f32_16x16x32_bf16 v[18:21], v[184:187], v[224:227], v[18:21]
	v_mfma_f32_16x16x32_bf16 v[6:9], v[176:179], v[232:235], v[6:9]
	v_mfma_f32_16x16x32_bf16 v[2:5], v[184:187], v[232:235], v[2:5]
	v_mfma_f32_16x16x32_bf16 v[54:57], v[180:183], v[212:215], v[54:57]
	v_mfma_f32_16x16x32_bf16 v[50:53], v[188:191], v[212:215], v[50:53]
	v_mfma_f32_16x16x32_bf16 v[38:41], v[180:183], v[220:223], v[38:41]
	v_mfma_f32_16x16x32_bf16 v[34:37], v[188:191], v[220:223], v[34:37]
	v_mfma_f32_16x16x32_bf16 v[22:25], v[180:183], v[228:231], v[22:25]
	v_mfma_f32_16x16x32_bf16 v[18:21], v[188:191], v[228:231], v[18:21]
	v_mfma_f32_16x16x32_bf16 v[6:9], v[180:183], v[236:239], v[6:9]
	v_mfma_f32_16x16x32_bf16 v[2:5], v[188:191], v[236:239], v[2:5]
	s_setprio 0
	s_barrier
	s_add_i32 s43, s43, 2
	s_add_u32 s14, s14, 0x100
	s_addc_u32 s15, s15, 0
	s_add_u32 s41, s41, 0x100
	s_addc_u32 s42, s42, 0
	s_cmp_gt_u32 s43, 29
	s_cbranch_scc0 .LBB0_4223
	s_and_b64 vcc, exec, s[2:3]
	s_cbranch_vccz .LBB0_4226
	s_barrier

; #define PG8_STAGE(bufoff, gbase, voff) do { _Pragma("unroll") for (int _i = 0; _i < 2; ++_i) \
;         __builtin_amdgcn_global_load_lds((const unsigned*)((const char*)(gbase) + (voff)[_i]), (LAS unsigned*)(lds + (bufoff) + ldsw + _i * 8192), 16, 0, 0); } while (0)
; #define PG8_LDA(dst, b, h) do { _Pragma("unroll") for (int m = 0; m < 4; ++m) _Pragma("unroll") for (int k = 0; k < 2; ++k) dst[m][k] = *(const LAS bf16x8*)(lds + PG8_SA(b, h) + aoff + m * 2048 + k * 1024); } while (0)
; #define PG8_LDB(dst, b, h) do { _Pragma("unroll") for (int n = 0; n < 2; ++n) _Pragma("unroll") for (int k = 0; k < 2; ++k) dst[n][k] = *(const LAS bf16x8*)(lds + PG8_SB(b, h) + boff + n * 2048 + k * 1024); } while (0)
; #define PG8_MMA(ai, bj, At, Bt) do { __builtin_amdgcn_s_setprio(1); _Pragma("unroll") for (int m = 0; m < 4; ++m) _Pragma("unroll") for (int n = 0; n < 2; ++n) _Pragma("unroll") for (int k = 0; k < 2; ++k) \
;         acc[ai][bj][m][n] = __builtin_amdgcn_mfma_f32_16x16x32_bf16(Bt[n][k], At[m][k], acc[ai][bj][m][n], 0, 0, 0); __builtin_amdgcn_s_setprio(0); } while (0)
; #define PG8_WAIT_V(n) asm volatile("s_waitcnt vmcnt(" #n ")" ::: "memory")
; #define PG8_WAIT_L(n) asm volatile("s_waitcnt lgkmcnt(" #n ")" ::: "memory")
; #define PG8_BAR __builtin_amdgcn_s_barrier()
; #define PG8_SCHED __builtin_amdgcn_sched_barrier(0)
; template <class Epi, class Sched>
; __device__ __forceinline__ void gemm_phase(LAS unsigned char* lds, const Gemm g, const Sched& S, const Epi& E) {
;     ...
;             const bool last = (t == nt - 2);
;             const char* a1 = cA + (size_t)(t + 1) * kstep;
;             const char* a2 = last ? nA : cA + (size_t)(t + 2) * kstep; const char* b2 = last ? nB : cB + (size_t)(t + 2) * kstep;
;             const char* a3 = a2 + kstep; const char* b3 = b2 + kstep;
;             PG8_LDB(B0, 0, 0); PG8_LDB(B1, 0, 1); PG8_SCHED; PG8_LDA(At, 0, 0); PG8_STAGE(PG8_SA(1, 1), a1 + hstepA, voffA);
;             PG8_WAIT_V(8); PG8_WAIT_L(0); PG8_BAR; PG8_MMA(0, 0, At, B0); PG8_MMA(0, 1, At, B1); PG8_BAR; PG8_SCHED;
;             PG8_LDA(At, 0, 1); PG8_STAGE(PG8_SB(0, 0), b2, voffB); PG8_STAGE(PG8_SB(0, 1), b2 + hstepB, voffB); PG8_STAGE(PG8_SA(0, 0), a2, voffA);
.LBB0_4314:
	s_add_u32 s22, s20, 0xffe00080
	s_addc_u32 s23, s21, -1
	s_add_i32 s46, 0, 0x10000
	s_cmpk_eq_i32 s45, 0x7c
	s_cselect_b32 s25, s11, s23
	s_cselect_b32 s24, s17, s22
	s_cselect_b32 s23, s7, s44
	s_cselect_b32 s22, s19, s43
	s_add_i32 s49, 0, 0x14000
	v_add_u32_e32 v170, s46, v1
	v_add_u32_e32 v174, s49, v1
	ds_read_b128 v[130:133], v170
	ds_read_b128 v[134:137], v170 offset:1024
	ds_read_b128 v[166:169], v170 offset:2048
	ds_read_b128 v[170:173], v170 offset:3072
	ds_read_b128 v[178:181], v174
	ds_read_b128 v[182:185], v174 offset:1024
	ds_read_b128 v[186:189], v174 offset:2048
	ds_read_b128 v[190:193], v174 offset:3072
	v_lshl_add_u64 v[174:175], s[20:21], 0, v[162:163]
	s_add_i32 m0, s31, 0xc000
	ds_read_b128 v[208:211], v176
	ds_read_b128 v[212:215], v176 offset:1024
	ds_read_b128 v[216:219], v176 offset:2048
	ds_read_b128 v[220:223], v176 offset:3072
	ds_read_b128 v[224:227], v176 offset:4096
	ds_read_b128 v[228:231], v176 offset:5120
	ds_read_b128 v[232:235], v176 offset:6144
	ds_read_b128 v[236:239], v176 offset:7168
	global_load_lds_dwordx4 v[174:175], off
	v_lshl_add_u64 v[174:175], s[20:21], 0, v[164:165]
	s_add_i32 m0, s31, 0xe000
	s_nop 0
	global_load_lds_dwordx4 v[174:175], off
	s_waitcnt vmcnt(8)
	s_waitcnt lgkmcnt(0)
	s_barrier
	s_setprio 1
	s_waitcnt lgkmcnt(0)
	v_mfma_f32_16x16x32_bf16 v[126:129], v[130:133], v[208:211], v[126:129]
	v_mfma_f32_16x16x32_bf16 v[122:125], v[166:169], v[208:211], v[122:125]
	v_mfma_f32_16x16x32_bf16 v[110:113], v[130:133], v[216:219], v[110:113]
	v_mfma_f32_16x16x32_bf16 v[106:109], v[166:169], v[216:219], v[106:109]
	v_mfma_f32_16x16x32_bf16 v[94:97], v[130:133], v[224:227], v[94:97]
	v_mfma_f32_16x16x32_bf16 v[90:93], v[166:169], v[224:227], v[90:93]
	v_mfma_f32_16x16x32_bf16 v[78:81], v[130:133], v[232:235], v[78:81]
	v_mfma_f32_16x16x32_bf16 v[74:77], v[166:169], v[232:235], v[74:77]
	v_mfma_f32_16x16x32_bf16 v[126:129], v[134:137], v[212:215], v[126:129]
	v_mfma_f32_16x16x32_bf16 v[122:125], v[170:173], v[212:215], v[122:125]
	v_mfma_f32_16x16x32_bf16 v[110:113], v[134:137], v[220:223], v[110:113]
	v_mfma_f32_16x16x32_bf16 v[106:109], v[170:173], v[220:223], v[106:109]
	v_mfma_f32_16x16x32_bf16 v[94:97], v[134:137], v[228:231], v[94:97]
	v_mfma_f32_16x16x32_bf16 v[90:93], v[170:173], v[228:231], v[90:93]
	v_mfma_f32_16x16x32_bf16 v[78:81], v[134:137], v[236:239], v[78:81]
	v_mfma_f32_16x16x32_bf16 v[74:77], v[170:173], v[236:239], v[74:77]
	s_setprio 0
	s_setprio 1
	v_mfma_f32_16x16x32_bf16 v[118:121], v[178:181], v[208:211], v[118:121]
	v_mfma_f32_16x16x32_bf16 v[114:117], v[186:189], v[208:211], v[114:117]
	v_mfma_f32_16x16x32_bf16 v[102:105], v[178:181], v[216:219], v[102:105]
	v_mfma_f32_16x16x32_bf16 v[98:101], v[186:189], v[216:219], v[98:101]
	v_mfma_f32_16x16x32_bf16 v[86:89], v[178:181], v[224:227], v[86:89]
	v_mfma_f32_16x16x32_bf16 v[82:85], v[186:189], v[224:227], v[82:85]
	v_mfma_f32_16x16x32_bf16 v[70:73], v[178:181], v[232:235], v[70:73]
	v_mfma_f32_16x16x32_bf16 v[66:69], v[186:189], v[232:235], v[66:69]
	v_mfma_f32_16x16x32_bf16 v[118:121], v[182:185], v[212:215], v[118:121]
	v_mfma_f32_16x16x32_bf16 v[114:117], v[190:193], v[212:215], v[114:117]
	v_mfma_f32_16x16x32_bf16 v[102:105], v[182:185], v[220:223], v[102:105]
	v_mfma_f32_16x16x32_bf16 v[98:101], v[190:193], v[220:223], v[98:101]
	v_mfma_f32_16x16x32_bf16 v[86:89], v[182:185], v[228:231], v[86:89]
	v_mfma_f32_16x16x32_bf16 v[82:85], v[190:193], v[228:231], v[82:85]
	v_mfma_f32_16x16x32_bf16 v[70:73], v[182:185], v[236:239], v[70:73]
	v_mfma_f32_16x16x32_bf16 v[66:69], v[190:193], v[236:239], v[66:69]
	s_setprio 0
	s_barrier
	s_add_i32 s46, s46, s30
	v_lshl_add_u64 v[174:175], s[22:23], 0, v[140:141]
	s_mov_b32 m0, s46
	ds_read_b128 v[208:211], v176 offset:16384
	ds_read_b128 v[212:215], v176 offset:17408
	ds_read_b128 v[216:219], v176 offset:18432
	ds_read_b128 v[220:223], v176 offset:19456
	ds_read_b128 v[224:227], v176 offset:20480
	ds_read_b128 v[228:231], v176 offset:21504
	ds_read_b128 v[232:235], v176 offset:22528
	ds_read_b128 v[236:239], v176 offset:23552
	global_load_lds_dwordx4 v[174:175], off
	s_add_i32 m0, s46, 0x2000
	s_add_u32 s46, s22, 0x200000
	v_lshl_add_u64 v[240:241], s[22:23], 0, v[144:145]
	s_addc_u32 s47, s23, 0
	s_add_i32 s49, s49, s30
	global_load_lds_dwordx4 v[240:241], off
	v_lshl_add_u64 v[242:243], s[46:47], 0, v[140:141]
	s_mov_b32 m0, s49
	v_lshl_add_u64 v[244:245], s[24:25], 0, v[142:143]
	global_load_lds_dwordx4 v[242:243], off
	v_lshl_add_u64 v[242:243], s[46:47], 0, v[144:145]
	s_add_i32 m0, s49, 0x2000
	s_nop 0
	global_load_lds_dwordx4 v[242:243], off
	v_lshl_add_u64 v[242:243], s[24:25], 0, v[138:139]
	s_mov_b32 m0, s31
	s_nop 0
	global_load_lds_dwordx4 v[242:243], off
	s_mov_b32 m0, s33
	s_nop 0
	global_load_lds_dwordx4 v[244:245], off
	s_nop 0
	s_nop 0
	s_nop 0
	s_waitcnt vmcnt(8)
	s_waitcnt lgkmcnt(0)
	s_barrier
; #define PG8_STAGE(bufoff, gbase, voff) do { _Pragma("unroll") for (int _i = 0; _i < 2; ++_i) \
;         __builtin_amdgcn_global_load_lds((const unsigned*)((const char*)(gbase) + (voff)[_i]), (LAS unsigned*)(lds + (bufoff) + ldsw + _i * 8192), 16, 0, 0); } while (0)
; #define PG8_LDA(dst, b, h) do { _Pragma("unroll") for (int m = 0; m < 4; ++m) _Pragma("unroll") for (int k = 0; k < 2; ++k) dst[m][k] = *(const LAS bf16x8*)(lds + PG8_SA(b, h) + aoff + m * 2048 + k * 1024); } while (0)
; #define PG8_LDB(dst, b, h) do { _Pragma("unroll") for (int n = 0; n < 2; ++n) _Pragma("unroll") for (int k = 0; k < 2; ++k) dst[n][k] = *(const LAS bf16x8*)(lds + PG8_SB(b, h) + boff + n * 2048 + k * 1024); } while (0)
; #define PG8_MMA(ai, bj, At, Bt) do { __builtin_amdgcn_s_setprio(1); _Pragma("unroll") for (int m = 0; m < 4; ++m) _Pragma("unroll") for (int n = 0; n < 2; ++n) _Pragma("unroll") for (int k = 0; k < 2; ++k) \
;         acc[ai][bj][m][n] = __builtin_amdgcn_mfma_f32_16x16x32_bf16(Bt[n][k], At[m][k], acc[ai][bj][m][n], 0, 0, 0); __builtin_amdgcn_s_setprio(0); } while (0)
; #define PG8_WAIT_V(n) asm volatile("s_waitcnt vmcnt(" #n ")" ::: "memory")
; #define PG8_WAIT_L(n) asm volatile("s_waitcnt lgkmcnt(" #n ")" ::: "memory")
; #define PG8_BAR __builtin_amdgcn_s_barrier()
; #define PG8_SCHED __builtin_amdgcn_sched_barrier(0)
; template <class Epi, class Sched>
; __device__ __forceinline__ void gemm_phase(LAS unsigned char* lds, const Gemm g, const Sched& S, const Epi& E) {
;     ...
;             PG8_WAIT_V(8); PG8_WAIT_L(0); PG8_BAR; PG8_MMA(1, 0, At, B0); PG8_MMA(1, 1, At, B1); PG8_BAR; PG8_SCHED;
;             PG8_LDB(B0, 1, 0); PG8_LDB(B1, 1, 1); PG8_SCHED; PG8_LDA(At, 1, 0); PG8_STAGE(PG8_SA(0, 1), a2 + hstepA, voffA);
;             PG8_WAIT_V(8); PG8_WAIT_L(0); PG8_BAR; PG8_MMA(0, 0, At, B0); PG8_MMA(0, 1, At, B1); PG8_BAR; PG8_SCHED;
	s_setprio 1
	s_waitcnt lgkmcnt(0)
	v_mfma_f32_16x16x32_bf16 v[62:65], v[130:133], v[208:211], v[62:65]
	v_mfma_f32_16x16x32_bf16 v[58:61], v[166:169], v[208:211], v[58:61]
	v_mfma_f32_16x16x32_bf16 v[46:49], v[130:133], v[216:219], v[46:49]
	v_mfma_f32_16x16x32_bf16 v[42:45], v[166:169], v[216:219], v[42:45]
	v_mfma_f32_16x16x32_bf16 v[30:33], v[130:133], v[224:227], v[30:33]
	v_mfma_f32_16x16x32_bf16 v[26:29], v[166:169], v[224:227], v[26:29]
	v_mfma_f32_16x16x32_bf16 v[14:17], v[130:133], v[232:235], v[14:17]
	v_mfma_f32_16x16x32_bf16 v[10:13], v[166:169], v[232:235], v[10:13]
	v_mfma_f32_16x16x32_bf16 v[62:65], v[134:137], v[212:215], v[62:65]
	v_mfma_f32_16x16x32_bf16 v[58:61], v[170:173], v[212:215], v[58:61]
	v_mfma_f32_16x16x32_bf16 v[46:49], v[134:137], v[220:223], v[46:49]
	v_mfma_f32_16x16x32_bf16 v[42:45], v[170:173], v[220:223], v[42:45]
	v_mfma_f32_16x16x32_bf16 v[30:33], v[134:137], v[228:231], v[30:33]
	v_mfma_f32_16x16x32_bf16 v[26:29], v[170:173], v[228:231], v[26:29]
	v_mfma_f32_16x16x32_bf16 v[14:17], v[134:137], v[236:239], v[14:17]
	v_mfma_f32_16x16x32_bf16 v[10:13], v[170:173], v[236:239], v[10:13]
	s_setprio 0
	s_setprio 1
	v_mfma_f32_16x16x32_bf16 v[54:57], v[178:181], v[208:211], v[54:57]
	v_mfma_f32_16x16x32_bf16 v[50:53], v[186:189], v[208:211], v[50:53]
	v_mfma_f32_16x16x32_bf16 v[38:41], v[178:181], v[216:219], v[38:41]
	v_mfma_f32_16x16x32_bf16 v[34:37], v[186:189], v[216:219], v[34:37]
	v_mfma_f32_16x16x32_bf16 v[22:25], v[178:181], v[224:227], v[22:25]
	v_mfma_f32_16x16x32_bf16 v[18:21], v[186:189], v[224:227], v[18:21]
	v_mfma_f32_16x16x32_bf16 v[6:9], v[178:181], v[232:235], v[6:9]
	v_mfma_f32_16x16x32_bf16 v[2:5], v[186:189], v[232:235], v[2:5]
	v_mfma_f32_16x16x32_bf16 v[54:57], v[182:185], v[212:215], v[54:57]
	v_mfma_f32_16x16x32_bf16 v[50:53], v[190:193], v[212:215], v[50:53]
	v_mfma_f32_16x16x32_bf16 v[38:41], v[182:185], v[220:223], v[38:41]
	v_mfma_f32_16x16x32_bf16 v[34:37], v[190:193], v[220:223], v[34:37]
	v_mfma_f32_16x16x32_bf16 v[22:25], v[182:185], v[228:231], v[22:25]
	v_mfma_f32_16x16x32_bf16 v[18:21], v[190:193], v[228:231], v[18:21]
	v_mfma_f32_16x16x32_bf16 v[6:9], v[182:185], v[236:239], v[6:9]
	v_mfma_f32_16x16x32_bf16 v[2:5], v[190:193], v[236:239], v[2:5]
	s_setprio 0
	s_barrier
	s_add_i32 s46, 0, 0x18000
	s_add_i32 s47, 0, 0x1c000
	v_add_u32_e32 v170, s46, v1
	v_add_u32_e32 v177, s47, v1
	ds_read_b128 v[130:133], v170
	ds_read_b128 v[134:137], v170 offset:1024
	ds_read_b128 v[166:169], v170 offset:2048
	ds_read_b128 v[170:173], v170 offset:3072
	ds_read_b128 v[178:181], v177
	ds_read_b128 v[182:185], v177 offset:1024
	ds_read_b128 v[186:189], v177 offset:2048
	ds_read_b128 v[190:193], v177 offset:3072
	s_add_u32 s24, s24, 0x200000
	s_addc_u32 s25, s25, 0
	s_mov_b32 m0, s34
	v_lshl_add_u64 v[246:247], s[24:25], 0, v[138:139]
	ds_read_b128 v[208:211], v176 offset:32768
	ds_read_b128 v[212:215], v176 offset:33792
	ds_read_b128 v[216:219], v176 offset:34816
	ds_read_b128 v[220:223], v176 offset:35840
	ds_read_b128 v[224:227], v176 offset:36864
	ds_read_b128 v[228:231], v176 offset:37888
	ds_read_b128 v[232:235], v176 offset:38912
	ds_read_b128 v[236:239], v176 offset:39936
	global_load_lds_dwordx4 v[246:247], off
	v_lshl_add_u64 v[246:247], s[24:25], 0, v[142:143]
	s_mov_b32 m0, s35
	s_nop 0
	global_load_lds_dwordx4 v[246:247], off
	s_nop 0
	s_nop 0
	s_nop 0
	s_waitcnt vmcnt(8)
	s_waitcnt lgkmcnt(0)
	s_barrier
	s_setprio 1
	s_waitcnt lgkmcnt(0)
	v_mfma_f32_16x16x32_bf16 v[126:129], v[130:133], v[208:211], v[126:129]
	v_mfma_f32_16x16x32_bf16 v[122:125], v[166:169], v[208:211], v[122:125]
	v_mfma_f32_16x16x32_bf16 v[110:113], v[130:133], v[216:219], v[110:113]
	v_mfma_f32_16x16x32_bf16 v[106:109], v[166:169], v[216:219], v[106:109]
	v_mfma_f32_16x16x32_bf16 v[94:97], v[130:133], v[224:227], v[94:97]
	v_mfma_f32_16x16x32_bf16 v[90:93], v[166:169], v[224:227], v[90:93]
	v_mfma_f32_16x16x32_bf16 v[78:81], v[130:133], v[232:235], v[78:81]
	v_mfma_f32_16x16x32_bf16 v[74:77], v[166:169], v[232:235], v[74:77]
	v_mfma_f32_16x16x32_bf16 v[126:129], v[134:137], v[212:215], v[126:129]
	v_mfma_f32_16x16x32_bf16 v[122:125], v[170:173], v[212:215], v[122:125]
	v_mfma_f32_16x16x32_bf16 v[110:113], v[134:137], v[220:223], v[110:113]
	v_mfma_f32_16x16x32_bf16 v[106:109], v[170:173], v[220:223], v[106:109]
	v_mfma_f32_16x16x32_bf16 v[94:97], v[134:137], v[228:231], v[94:97]
	v_mfma_f32_16x16x32_bf16 v[90:93], v[170:173], v[228:231], v[90:93]
	v_mfma_f32_16x16x32_bf16 v[78:81], v[134:137], v[236:239], v[78:81]
	v_mfma_f32_16x16x32_bf16 v[74:77], v[170:173], v[236:239], v[74:77]
	s_setprio 0
	s_setprio 1
	v_mfma_f32_16x16x32_bf16 v[118:121], v[178:181], v[208:211], v[118:121]
	v_mfma_f32_16x16x32_bf16 v[114:117], v[186:189], v[208:211], v[114:117]
	v_mfma_f32_16x16x32_bf16 v[102:105], v[178:181], v[216:219], v[102:105]
	v_mfma_f32_16x16x32_bf16 v[98:101], v[186:189], v[216:219], v[98:101]
	v_mfma_f32_16x16x32_bf16 v[86:89], v[178:181], v[224:227], v[86:89]
	v_mfma_f32_16x16x32_bf16 v[82:85], v[186:189], v[224:227], v[82:85]
	v_mfma_f32_16x16x32_bf16 v[70:73], v[178:181], v[232:235], v[70:73]
	v_mfma_f32_16x16x32_bf16 v[66:69], v[186:189], v[232:235], v[66:69]
	v_mfma_f32_16x16x32_bf16 v[118:121], v[182:185], v[212:215], v[118:121]
	v_mfma_f32_16x16x32_bf16 v[114:117], v[190:193], v[212:215], v[114:117]
	v_mfma_f32_16x16x32_bf16 v[102:105], v[182:185], v[220:223], v[102:105]
	v_mfma_f32_16x16x32_bf16 v[98:101], v[190:193], v[220:223], v[98:101]
	v_mfma_f32_16x16x32_bf16 v[86:89], v[182:185], v[228:231], v[86:89]
	v_mfma_f32_16x16x32_bf16 v[82:85], v[190:193], v[228:231], v[82:85]
	v_mfma_f32_16x16x32_bf16 v[70:73], v[182:185], v[236:239], v[70:73]
	v_mfma_f32_16x16x32_bf16 v[66:69], v[190:193], v[236:239], v[66:69]
	s_setprio 0
	s_barrier
; #define PG8_STAGE(bufoff, gbase, voff) do { _Pragma("unroll") for (int _i = 0; _i < 2; ++_i) \
;         __builtin_amdgcn_global_load_lds((const unsigned*)((const char*)(gbase) + (voff)[_i]), (LAS unsigned*)(lds + (bufoff) + ldsw + _i * 8192), 16, 0, 0); } while (0)
; #define PG8_LDA(dst, b, h) do { _Pragma("unroll") for (int m = 0; m < 4; ++m) _Pragma("unroll") for (int k = 0; k < 2; ++k) dst[m][k] = *(const LAS bf16x8*)(lds + PG8_SA(b, h) + aoff + m * 2048 + k * 1024); } while (0)
; #define PG8_MMA(ai, bj, At, Bt) do { __builtin_amdgcn_s_setprio(1); _Pragma("unroll") for (int m = 0; m < 4; ++m) _Pragma("unroll") for (int n = 0; n < 2; ++n) _Pragma("unroll") for (int k = 0; k < 2; ++k) \
;         acc[ai][bj][m][n] = __builtin_amdgcn_mfma_f32_16x16x32_bf16(Bt[n][k], At[m][k], acc[ai][bj][m][n], 0, 0, 0); __builtin_amdgcn_s_setprio(0); } while (0)
; #define PG8_WAIT_V(n) asm volatile("s_waitcnt vmcnt(" #n ")" ::: "memory")
; #define PG8_WAIT_L(n) asm volatile("s_waitcnt lgkmcnt(" #n ")" ::: "memory")
; #define PG8_BAR __builtin_amdgcn_s_barrier()
; #define PG8_SCHED __builtin_amdgcn_sched_barrier(0)
; template <class Epi, class Sched>
; __device__ __forceinline__ void gemm_phase(LAS unsigned char* lds, const Gemm g, const Sched& S, const Epi& E) {
;     ...
;             PG8_LDA(At, 1, 1); PG8_STAGE(PG8_SB(1, 0), b3, voffB); PG8_STAGE(PG8_SB(1, 1), b3 + hstepB, voffB); PG8_STAGE(PG8_SA(1, 0), a3, voffA);
;             PG8_WAIT_V(8); PG8_WAIT_L(0); PG8_BAR; PG8_MMA(1, 0, At, B0); PG8_MMA(1, 1, At, B1); PG8_BAR; PG8_SCHED;
;         }
;         if (wr == 0) PG8_BAR;
	s_add_i32 s24, s46, s30
	v_lshl_add_u64 v[174:175], v[174:175], 0, s[56:57]
	s_mov_b32 m0, s24
	ds_read_b128 v[208:211], v176 offset:49152
	ds_read_b128 v[212:215], v176 offset:50176
	ds_read_b128 v[216:219], v176 offset:51200
	ds_read_b128 v[220:223], v176 offset:52224
	ds_read_b128 v[224:227], v176 offset:53248
	ds_read_b128 v[228:231], v176 offset:54272
	ds_read_b128 v[232:235], v176 offset:55296
	ds_read_b128 v[236:239], v176 offset:56320
	global_load_lds_dwordx4 v[174:175], off
	s_add_i32 m0, s24, 0x2000
	s_add_u32 s22, s22, 0x200080
	v_lshl_add_u64 v[174:175], v[240:241], 0, s[56:57]
	s_addc_u32 s23, s23, 0
	s_add_i32 s24, s47, s30
	global_load_lds_dwordx4 v[174:175], off
	v_lshl_add_u64 v[174:175], s[22:23], 0, v[140:141]
	s_mov_b32 m0, s24
	s_nop 0
	global_load_lds_dwordx4 v[174:175], off
	v_lshl_add_u64 v[174:175], s[22:23], 0, v[144:145]
	s_add_i32 m0, s24, 0x2000
	s_nop 0
	global_load_lds_dwordx4 v[174:175], off
	v_lshl_add_u64 v[174:175], v[242:243], 0, s[56:57]
	s_mov_b32 m0, s39
	s_nop 0
	global_load_lds_dwordx4 v[174:175], off
	v_lshl_add_u64 v[174:175], v[244:245], 0, s[56:57]
	s_mov_b32 m0, s40
	s_nop 0
	global_load_lds_dwordx4 v[174:175], off
	s_nop 0
	s_nop 0
	s_waitcnt vmcnt(8)
	s_waitcnt lgkmcnt(0)
	s_barrier
	s_setprio 1
	s_waitcnt lgkmcnt(0)
	v_mfma_f32_16x16x32_bf16 v[62:65], v[130:133], v[208:211], v[62:65]
	v_mfma_f32_16x16x32_bf16 v[58:61], v[166:169], v[208:211], v[58:61]
	v_mfma_f32_16x16x32_bf16 v[46:49], v[130:133], v[216:219], v[46:49]
	v_mfma_f32_16x16x32_bf16 v[42:45], v[166:169], v[216:219], v[42:45]
	v_mfma_f32_16x16x32_bf16 v[30:33], v[130:133], v[224:227], v[30:33]
	v_mfma_f32_16x16x32_bf16 v[26:29], v[166:169], v[224:227], v[26:29]
	v_mfma_f32_16x16x32_bf16 v[14:17], v[130:133], v[232:235], v[14:17]
	v_mfma_f32_16x16x32_bf16 v[10:13], v[166:169], v[232:235], v[10:13]
	v_mfma_f32_16x16x32_bf16 v[62:65], v[134:137], v[212:215], v[62:65]
	v_mfma_f32_16x16x32_bf16 v[58:61], v[170:173], v[212:215], v[58:61]
	v_mfma_f32_16x16x32_bf16 v[46:49], v[134:137], v[220:223], v[46:49]
	v_mfma_f32_16x16x32_bf16 v[42:45], v[170:173], v[220:223], v[42:45]
	v_mfma_f32_16x16x32_bf16 v[30:33], v[134:137], v[228:231], v[30:33]
	v_mfma_f32_16x16x32_bf16 v[26:29], v[170:173], v[228:231], v[26:29]
	v_mfma_f32_16x16x32_bf16 v[14:17], v[134:137], v[236:239], v[14:17]
	v_mfma_f32_16x16x32_bf16 v[10:13], v[170:173], v[236:239], v[10:13]
	s_setprio 0
	s_setprio 1
	v_mfma_f32_16x16x32_bf16 v[54:57], v[178:181], v[208:211], v[54:57]
	v_mfma_f32_16x16x32_bf16 v[50:53], v[186:189], v[208:211], v[50:53]
	v_mfma_f32_16x16x32_bf16 v[38:41], v[178:181], v[216:219], v[38:41]
	v_mfma_f32_16x16x32_bf16 v[34:37], v[186:189], v[216:219], v[34:37]
	v_mfma_f32_16x16x32_bf16 v[22:25], v[178:181], v[224:227], v[22:25]
	v_mfma_f32_16x16x32_bf16 v[18:21], v[186:189], v[224:227], v[18:21]
	v_mfma_f32_16x16x32_bf16 v[6:9], v[178:181], v[232:235], v[6:9]
	v_mfma_f32_16x16x32_bf16 v[2:5], v[186:189], v[232:235], v[2:5]
	v_mfma_f32_16x16x32_bf16 v[54:57], v[182:185], v[212:215], v[54:57]
	v_mfma_f32_16x16x32_bf16 v[50:53], v[190:193], v[212:215], v[50:53]
	v_mfma_f32_16x16x32_bf16 v[38:41], v[182:185], v[220:223], v[38:41]
	v_mfma_f32_16x16x32_bf16 v[34:37], v[190:193], v[220:223], v[34:37]
	v_mfma_f32_16x16x32_bf16 v[22:25], v[182:185], v[228:231], v[22:25]
	v_mfma_f32_16x16x32_bf16 v[18:21], v[190:193], v[228:231], v[18:21]
	v_mfma_f32_16x16x32_bf16 v[6:9], v[182:185], v[236:239], v[6:9]
	v_mfma_f32_16x16x32_bf16 v[2:5], v[190:193], v[236:239], v[2:5]
	s_setprio 0
	s_barrier
	s_add_i32 s45, s45, 2
	s_add_u32 s20, s20, 0x100
	s_addc_u32 s21, s21, 0
	s_add_u32 s43, s43, 0x100
	s_addc_u32 s44, s44, 0
	s_cmpk_gt_u32 s45, 0x7d
	s_cbranch_scc0 .LBB0_4314
	s_and_b64 vcc, exec, s[4:5]
	s_cbranch_vccz .LBB0_4317
	s_barrier

; #define PG8_STAGE(bufoff, gbase, voff) do { _Pragma("unroll") for (int _i = 0; _i < 2; ++_i) \
;         __builtin_amdgcn_global_load_lds((const unsigned*)((const char*)(gbase) + (voff)[_i]), (LAS unsigned*)(lds + (bufoff) + ldsw + _i * 8192), 16, 0, 0); } while (0)
; #define PG8_LDA(dst, b, h) do { _Pragma("unroll") for (int m = 0; m < 4; ++m) _Pragma("unroll") for (int k = 0; k < 2; ++k) dst[m][k] = *(const LAS bf16x8*)(lds + PG8_SA(b, h) + aoff + m * 2048 + k * 1024); } while (0)
; #define PG8_LDB(dst, b, h) do { _Pragma("unroll") for (int n = 0; n < 2; ++n) _Pragma("unroll") for (int k = 0; k < 2; ++k) dst[n][k] = *(const LAS bf16x8*)(lds + PG8_SB(b, h) + boff + n * 2048 + k * 1024); } while (0)
; #define PG8_MMA(ai, bj, At, Bt) do { __builtin_amdgcn_s_setprio(1); _Pragma("unroll") for (int m = 0; m < 4; ++m) _Pragma("unroll") for (int n = 0; n < 2; ++n) _Pragma("unroll") for (int k = 0; k < 2; ++k) \
;         acc[ai][bj][m][n] = __builtin_amdgcn_mfma_f32_16x16x32_bf16(Bt[n][k], At[m][k], acc[ai][bj][m][n], 0, 0, 0); __builtin_amdgcn_s_setprio(0); } while (0)
; #define PG8_WAIT_V(n) asm volatile("s_waitcnt vmcnt(" #n ")" ::: "memory")
; #define PG8_WAIT_L(n) asm volatile("s_waitcnt lgkmcnt(" #n ")" ::: "memory")
; #define PG8_BAR __builtin_amdgcn_s_barrier()
; #define PG8_SCHED __builtin_amdgcn_sched_barrier(0)
; template <class Epi, class Sched>
; __device__ __forceinline__ void gemm_phase(LAS unsigned char* lds, const Gemm g, const Sched& S, const Epi& E) {
;     ...
;             const bool last = (t == nt - 2);
;             const char* a1 = cA + (size_t)(t + 1) * kstep;
;             const char* a2 = last ? nA : cA + (size_t)(t + 2) * kstep; const char* b2 = last ? nB : cB + (size_t)(t + 2) * kstep;
;             const char* a3 = a2 + kstep; const char* b3 = b2 + kstep;
;             PG8_LDB(B0, 0, 0); PG8_LDB(B1, 0, 1); PG8_SCHED; PG8_LDA(At, 0, 0); PG8_STAGE(PG8_SA(1, 1), a1 + hstepA, voffA);
;             PG8_WAIT_V(8); PG8_WAIT_L(0); PG8_BAR; PG8_MMA(0, 0, At, B0); PG8_MMA(0, 1, At, B1); PG8_BAR; PG8_SCHED;
;             PG8_LDA(At, 0, 1); PG8_STAGE(PG8_SB(0, 0), b2, voffB); PG8_STAGE(PG8_SB(0, 1), b2 + hstepB, voffB); PG8_STAGE(PG8_SA(0, 0), a2, voffA);
.LBB0_4423:
	s_add_u32 s24, s22, 0xfff80080
	s_addc_u32 s25, s23, -1
	s_add_i32 s50, 0, 0x10000
	s_cmp_eq_u32 s49, 28
	s_cselect_b32 s27, s13, s25
	s_cselect_b32 s26, s19, s24
	s_cselect_b32 s25, s11, s47
	s_cselect_b32 s24, s21, s46
	s_add_i32 s52, 0, 0x14000
	v_add_u32_e32 v142, s50, v1
	v_add_u32_e32 v186, s52, v1
	ds_read_b128 v[130:133], v142
	ds_read_b128 v[134:137], v142 offset:1024
	ds_read_b128 v[138:141], v142 offset:2048
	ds_read_b128 v[142:145], v142 offset:3072
	ds_read_b128 v[174:177], v186
	ds_read_b128 v[178:181], v186 offset:1024
	ds_read_b128 v[182:185], v186 offset:2048
	ds_read_b128 v[186:189], v186 offset:3072
	v_lshl_add_u64 v[192:193], s[22:23], 0, v[170:171]
	s_add_i32 m0, s34, 0xc000
	ds_read_b128 v[208:211], v190
	ds_read_b128 v[212:215], v190 offset:1024
	ds_read_b128 v[216:219], v190 offset:2048
	ds_read_b128 v[220:223], v190 offset:3072
	ds_read_b128 v[224:227], v190 offset:4096
	ds_read_b128 v[228:231], v190 offset:5120
	ds_read_b128 v[232:235], v190 offset:6144
	ds_read_b128 v[236:239], v190 offset:7168
	global_load_lds_dwordx4 v[192:193], off
	v_lshl_add_u64 v[192:193], s[22:23], 0, v[172:173]
	s_add_i32 m0, s34, 0xe000
	s_nop 0
	global_load_lds_dwordx4 v[192:193], off
	s_nop 0
	s_nop 0
	s_waitcnt vmcnt(8)
	s_waitcnt lgkmcnt(0)
	s_barrier
	s_setprio 1
	s_waitcnt lgkmcnt(0)
	v_mfma_f32_16x16x32_bf16 v[126:129], v[130:133], v[208:211], v[126:129]
	v_mfma_f32_16x16x32_bf16 v[122:125], v[138:141], v[208:211], v[122:125]
	v_mfma_f32_16x16x32_bf16 v[110:113], v[130:133], v[216:219], v[110:113]
	v_mfma_f32_16x16x32_bf16 v[106:109], v[138:141], v[216:219], v[106:109]
	v_mfma_f32_16x16x32_bf16 v[94:97], v[130:133], v[224:227], v[94:97]
	v_mfma_f32_16x16x32_bf16 v[90:93], v[138:141], v[224:227], v[90:93]
	v_mfma_f32_16x16x32_bf16 v[78:81], v[130:133], v[232:235], v[78:81]
	v_mfma_f32_16x16x32_bf16 v[74:77], v[138:141], v[232:235], v[74:77]
	v_mfma_f32_16x16x32_bf16 v[126:129], v[134:137], v[212:215], v[126:129]
	v_mfma_f32_16x16x32_bf16 v[122:125], v[142:145], v[212:215], v[122:125]
	v_mfma_f32_16x16x32_bf16 v[110:113], v[134:137], v[220:223], v[110:113]
	v_mfma_f32_16x16x32_bf16 v[106:109], v[142:145], v[220:223], v[106:109]
	v_mfma_f32_16x16x32_bf16 v[94:97], v[134:137], v[228:231], v[94:97]
	v_mfma_f32_16x16x32_bf16 v[90:93], v[142:145], v[228:231], v[90:93]
	v_mfma_f32_16x16x32_bf16 v[78:81], v[134:137], v[236:239], v[78:81]
	v_mfma_f32_16x16x32_bf16 v[74:77], v[142:145], v[236:239], v[74:77]
	s_setprio 0
	s_setprio 1
	v_mfma_f32_16x16x32_bf16 v[118:121], v[174:177], v[208:211], v[118:121]
	v_mfma_f32_16x16x32_bf16 v[114:117], v[182:185], v[208:211], v[114:117]
	v_mfma_f32_16x16x32_bf16 v[102:105], v[174:177], v[216:219], v[102:105]
	v_mfma_f32_16x16x32_bf16 v[98:101], v[182:185], v[216:219], v[98:101]
	v_mfma_f32_16x16x32_bf16 v[86:89], v[174:177], v[224:227], v[86:89]
	v_mfma_f32_16x16x32_bf16 v[82:85], v[182:185], v[224:227], v[82:85]
	v_mfma_f32_16x16x32_bf16 v[70:73], v[174:177], v[232:235], v[70:73]
	v_mfma_f32_16x16x32_bf16 v[66:69], v[182:185], v[232:235], v[66:69]
	v_mfma_f32_16x16x32_bf16 v[118:121], v[178:181], v[212:215], v[118:121]
	v_mfma_f32_16x16x32_bf16 v[114:117], v[186:189], v[212:215], v[114:117]
	v_mfma_f32_16x16x32_bf16 v[102:105], v[178:181], v[220:223], v[102:105]
	v_mfma_f32_16x16x32_bf16 v[98:101], v[186:189], v[220:223], v[98:101]
	v_mfma_f32_16x16x32_bf16 v[86:89], v[178:181], v[228:231], v[86:89]
	v_mfma_f32_16x16x32_bf16 v[82:85], v[186:189], v[228:231], v[82:85]
	v_mfma_f32_16x16x32_bf16 v[70:73], v[178:181], v[236:239], v[70:73]
	v_mfma_f32_16x16x32_bf16 v[66:69], v[186:189], v[236:239], v[66:69]
	s_setprio 0
	s_barrier
	s_add_i32 s50, s50, s33
	v_lshl_add_u64 v[192:193], s[24:25], 0, v[164:165]
	s_mov_b32 m0, s50
	ds_read_b128 v[208:211], v190 offset:16384
	ds_read_b128 v[212:215], v190 offset:17408
	ds_read_b128 v[216:219], v190 offset:18432
	ds_read_b128 v[220:223], v190 offset:19456
	ds_read_b128 v[224:227], v190 offset:20480
	ds_read_b128 v[228:231], v190 offset:21504
	ds_read_b128 v[232:235], v190 offset:22528
	ds_read_b128 v[236:239], v190 offset:23552
	global_load_lds_dwordx4 v[192:193], off
	s_add_i32 m0, s50, 0x2000
	s_add_u32 s50, s24, 0x80000
	v_lshl_add_u64 v[240:241], s[24:25], 0, v[168:169]
	s_addc_u32 s51, s25, 0
	s_add_i32 s52, s52, s33
	global_load_lds_dwordx4 v[240:241], off
	v_lshl_add_u64 v[242:243], s[50:51], 0, v[164:165]
	s_mov_b32 m0, s52
	v_lshl_add_u64 v[244:245], s[26:27], 0, v[166:167]
	global_load_lds_dwordx4 v[242:243], off
	v_lshl_add_u64 v[242:243], s[50:51], 0, v[168:169]
	s_add_i32 m0, s52, 0x2000
	s_nop 0
	global_load_lds_dwordx4 v[242:243], off
	v_lshl_add_u64 v[242:243], s[26:27], 0, v[162:163]
	s_mov_b32 m0, s34
	s_nop 0
	global_load_lds_dwordx4 v[242:243], off
	s_mov_b32 m0, s35
	s_nop 0
	global_load_lds_dwordx4 v[244:245], off
	s_nop 0
	s_nop 0
	s_nop 0
	s_waitcnt vmcnt(8)
	s_waitcnt lgkmcnt(0)
	s_barrier
; #define PG8_STAGE(bufoff, gbase, voff) do { _Pragma("unroll") for (int _i = 0; _i < 2; ++_i) \
;         __builtin_amdgcn_global_load_lds((const unsigned*)((const char*)(gbase) + (voff)[_i]), (LAS unsigned*)(lds + (bufoff) + ldsw + _i * 8192), 16, 0, 0); } while (0)
; #define PG8_LDA(dst, b, h) do { _Pragma("unroll") for (int m = 0; m < 4; ++m) _Pragma("unroll") for (int k = 0; k < 2; ++k) dst[m][k] = *(const LAS bf16x8*)(lds + PG8_SA(b, h) + aoff + m * 2048 + k * 1024); } while (0)
; #define PG8_LDB(dst, b, h) do { _Pragma("unroll") for (int n = 0; n < 2; ++n) _Pragma("unroll") for (int k = 0; k < 2; ++k) dst[n][k] = *(const LAS bf16x8*)(lds + PG8_SB(b, h) + boff + n * 2048 + k * 1024); } while (0)
; #define PG8_MMA(ai, bj, At, Bt) do { __builtin_amdgcn_s_setprio(1); _Pragma("unroll") for (int m = 0; m < 4; ++m) _Pragma("unroll") for (int n = 0; n < 2; ++n) _Pragma("unroll") for (int k = 0; k < 2; ++k) \
;         acc[ai][bj][m][n] = __builtin_amdgcn_mfma_f32_16x16x32_bf16(Bt[n][k], At[m][k], acc[ai][bj][m][n], 0, 0, 0); __builtin_amdgcn_s_setprio(0); } while (0)
; #define PG8_WAIT_V(n) asm volatile("s_waitcnt vmcnt(" #n ")" ::: "memory")
; #define PG8_WAIT_L(n) asm volatile("s_waitcnt lgkmcnt(" #n ")" ::: "memory")
; #define PG8_BAR __builtin_amdgcn_s_barrier()
; #define PG8_SCHED __builtin_amdgcn_sched_barrier(0)
; template <class Epi, class Sched>
; __device__ __forceinline__ void gemm_phase(LAS unsigned char* lds, const Gemm g, const Sched& S, const Epi& E) {
;     ...
;             PG8_WAIT_V(8); PG8_WAIT_L(0); PG8_BAR; PG8_MMA(1, 0, At, B0); PG8_MMA(1, 1, At, B1); PG8_BAR; PG8_SCHED;
;             PG8_LDB(B0, 1, 0); PG8_LDB(B1, 1, 1); PG8_SCHED; PG8_LDA(At, 1, 0); PG8_STAGE(PG8_SA(0, 1), a2 + hstepA, voffA);
;             PG8_WAIT_V(8); PG8_WAIT_L(0); PG8_BAR; PG8_MMA(0, 0, At, B0); PG8_MMA(0, 1, At, B1); PG8_BAR; PG8_SCHED;
	s_setprio 1
	s_waitcnt lgkmcnt(0)
	v_mfma_f32_16x16x32_bf16 v[62:65], v[130:133], v[208:211], v[62:65]
	v_mfma_f32_16x16x32_bf16 v[58:61], v[138:141], v[208:211], v[58:61]
	v_mfma_f32_16x16x32_bf16 v[46:49], v[130:133], v[216:219], v[46:49]
	v_mfma_f32_16x16x32_bf16 v[42:45], v[138:141], v[216:219], v[42:45]
	v_mfma_f32_16x16x32_bf16 v[30:33], v[130:133], v[224:227], v[30:33]
	v_mfma_f32_16x16x32_bf16 v[26:29], v[138:141], v[224:227], v[26:29]
	v_mfma_f32_16x16x32_bf16 v[14:17], v[130:133], v[232:235], v[14:17]
	v_mfma_f32_16x16x32_bf16 v[10:13], v[138:141], v[232:235], v[10:13]
	v_mfma_f32_16x16x32_bf16 v[62:65], v[134:137], v[212:215], v[62:65]
	v_mfma_f32_16x16x32_bf16 v[58:61], v[142:145], v[212:215], v[58:61]
	v_mfma_f32_16x16x32_bf16 v[46:49], v[134:137], v[220:223], v[46:49]
	v_mfma_f32_16x16x32_bf16 v[42:45], v[142:145], v[220:223], v[42:45]
	v_mfma_f32_16x16x32_bf16 v[30:33], v[134:137], v[228:231], v[30:33]
	v_mfma_f32_16x16x32_bf16 v[26:29], v[142:145], v[228:231], v[26:29]
	v_mfma_f32_16x16x32_bf16 v[14:17], v[134:137], v[236:239], v[14:17]
	v_mfma_f32_16x16x32_bf16 v[10:13], v[142:145], v[236:239], v[10:13]
	s_setprio 0
	s_setprio 1
	v_mfma_f32_16x16x32_bf16 v[54:57], v[174:177], v[208:211], v[54:57]
	v_mfma_f32_16x16x32_bf16 v[50:53], v[182:185], v[208:211], v[50:53]
	v_mfma_f32_16x16x32_bf16 v[38:41], v[174:177], v[216:219], v[38:41]
	v_mfma_f32_16x16x32_bf16 v[34:37], v[182:185], v[216:219], v[34:37]
	v_mfma_f32_16x16x32_bf16 v[22:25], v[174:177], v[224:227], v[22:25]
	v_mfma_f32_16x16x32_bf16 v[18:21], v[182:185], v[224:227], v[18:21]
	v_mfma_f32_16x16x32_bf16 v[6:9], v[174:177], v[232:235], v[6:9]
	v_mfma_f32_16x16x32_bf16 v[2:5], v[182:185], v[232:235], v[2:5]
	v_mfma_f32_16x16x32_bf16 v[54:57], v[178:181], v[212:215], v[54:57]
	v_mfma_f32_16x16x32_bf16 v[50:53], v[186:189], v[212:215], v[50:53]
	v_mfma_f32_16x16x32_bf16 v[38:41], v[178:181], v[220:223], v[38:41]
	v_mfma_f32_16x16x32_bf16 v[34:37], v[186:189], v[220:223], v[34:37]
	v_mfma_f32_16x16x32_bf16 v[22:25], v[178:181], v[228:231], v[22:25]
	v_mfma_f32_16x16x32_bf16 v[18:21], v[186:189], v[228:231], v[18:21]
	v_mfma_f32_16x16x32_bf16 v[6:9], v[178:181], v[236:239], v[6:9]
	v_mfma_f32_16x16x32_bf16 v[2:5], v[186:189], v[236:239], v[2:5]
	s_setprio 0
	s_barrier
	s_add_i32 s50, 0, 0x18000
	s_add_i32 s51, 0, 0x1c000
	v_add_u32_e32 v142, s50, v1
	v_add_u32_e32 v186, s51, v1
	ds_read_b128 v[130:133], v142
	ds_read_b128 v[134:137], v142 offset:1024
	ds_read_b128 v[138:141], v142 offset:2048
	ds_read_b128 v[142:145], v142 offset:3072
	ds_read_b128 v[174:177], v186
	ds_read_b128 v[178:181], v186 offset:1024
	ds_read_b128 v[182:185], v186 offset:2048
	ds_read_b128 v[186:189], v186 offset:3072
	s_add_u32 s26, s26, 0x80000
	s_addc_u32 s27, s27, 0
	s_mov_b32 m0, s36
	v_lshl_add_u64 v[246:247], s[26:27], 0, v[162:163]
	ds_read_b128 v[208:211], v190 offset:32768
	ds_read_b128 v[212:215], v190 offset:33792
	ds_read_b128 v[216:219], v190 offset:34816
	ds_read_b128 v[220:223], v190 offset:35840
	ds_read_b128 v[224:227], v190 offset:36864
	ds_read_b128 v[228:231], v190 offset:37888
	ds_read_b128 v[232:235], v190 offset:38912
	ds_read_b128 v[236:239], v190 offset:39936
	global_load_lds_dwordx4 v[246:247], off
	v_lshl_add_u64 v[246:247], s[26:27], 0, v[166:167]
	s_mov_b32 m0, s37
	s_nop 0
	global_load_lds_dwordx4 v[246:247], off
	s_nop 0
	s_nop 0
	s_nop 0
	s_waitcnt vmcnt(8)
	s_waitcnt lgkmcnt(0)
	s_barrier
	s_setprio 1
	s_waitcnt lgkmcnt(0)
	v_mfma_f32_16x16x32_bf16 v[126:129], v[130:133], v[208:211], v[126:129]
	v_mfma_f32_16x16x32_bf16 v[122:125], v[138:141], v[208:211], v[122:125]
	v_mfma_f32_16x16x32_bf16 v[110:113], v[130:133], v[216:219], v[110:113]
	v_mfma_f32_16x16x32_bf16 v[106:109], v[138:141], v[216:219], v[106:109]
	v_mfma_f32_16x16x32_bf16 v[94:97], v[130:133], v[224:227], v[94:97]
	v_mfma_f32_16x16x32_bf16 v[90:93], v[138:141], v[224:227], v[90:93]
	v_mfma_f32_16x16x32_bf16 v[78:81], v[130:133], v[232:235], v[78:81]
	v_mfma_f32_16x16x32_bf16 v[74:77], v[138:141], v[232:235], v[74:77]
	v_mfma_f32_16x16x32_bf16 v[126:129], v[134:137], v[212:215], v[126:129]
	v_mfma_f32_16x16x32_bf16 v[122:125], v[142:145], v[212:215], v[122:125]
	v_mfma_f32_16x16x32_bf16 v[110:113], v[134:137], v[220:223], v[110:113]
	v_mfma_f32_16x16x32_bf16 v[106:109], v[142:145], v[220:223], v[106:109]
	v_mfma_f32_16x16x32_bf16 v[94:97], v[134:137], v[228:231], v[94:97]
	v_mfma_f32_16x16x32_bf16 v[90:93], v[142:145], v[228:231], v[90:93]
	v_mfma_f32_16x16x32_bf16 v[78:81], v[134:137], v[236:239], v[78:81]
	v_mfma_f32_16x16x32_bf16 v[74:77], v[142:145], v[236:239], v[74:77]
	s_setprio 0
	s_setprio 1
	v_mfma_f32_16x16x32_bf16 v[118:121], v[174:177], v[208:211], v[118:121]
	v_mfma_f32_16x16x32_bf16 v[114:117], v[182:185], v[208:211], v[114:117]
	v_mfma_f32_16x16x32_bf16 v[102:105], v[174:177], v[216:219], v[102:105]
	v_mfma_f32_16x16x32_bf16 v[98:101], v[182:185], v[216:219], v[98:101]
	v_mfma_f32_16x16x32_bf16 v[86:89], v[174:177], v[224:227], v[86:89]
	v_mfma_f32_16x16x32_bf16 v[82:85], v[182:185], v[224:227], v[82:85]
	v_mfma_f32_16x16x32_bf16 v[70:73], v[174:177], v[232:235], v[70:73]
	v_mfma_f32_16x16x32_bf16 v[66:69], v[182:185], v[232:235], v[66:69]
	v_mfma_f32_16x16x32_bf16 v[118:121], v[178:181], v[212:215], v[118:121]
	v_mfma_f32_16x16x32_bf16 v[114:117], v[186:189], v[212:215], v[114:117]
	v_mfma_f32_16x16x32_bf16 v[102:105], v[178:181], v[220:223], v[102:105]
	v_mfma_f32_16x16x32_bf16 v[98:101], v[186:189], v[220:223], v[98:101]
	v_mfma_f32_16x16x32_bf16 v[86:89], v[178:181], v[228:231], v[86:89]
	v_mfma_f32_16x16x32_bf16 v[82:85], v[186:189], v[228:231], v[82:85]
	v_mfma_f32_16x16x32_bf16 v[70:73], v[178:181], v[236:239], v[70:73]
	v_mfma_f32_16x16x32_bf16 v[66:69], v[186:189], v[236:239], v[66:69]
	s_setprio 0
	s_barrier
; #define PG8_STAGE(bufoff, gbase, voff) do { _Pragma("unroll") for (int _i = 0; _i < 2; ++_i) \
;         __builtin_amdgcn_global_load_lds((const unsigned*)((const char*)(gbase) + (voff)[_i]), (LAS unsigned*)(lds + (bufoff) + ldsw + _i * 8192), 16, 0, 0); } while (0)
; #define PG8_LDA(dst, b, h) do { _Pragma("unroll") for (int m = 0; m < 4; ++m) _Pragma("unroll") for (int k = 0; k < 2; ++k) dst[m][k] = *(const LAS bf16x8*)(lds + PG8_SA(b, h) + aoff + m * 2048 + k * 1024); } while (0)
; #define PG8_MMA(ai, bj, At, Bt) do { __builtin_amdgcn_s_setprio(1); _Pragma("unroll") for (int m = 0; m < 4; ++m) _Pragma("unroll") for (int n = 0; n < 2; ++n) _Pragma("unroll") for (int k = 0; k < 2; ++k) \
;         acc[ai][bj][m][n] = __builtin_amdgcn_mfma_f32_16x16x32_bf16(Bt[n][k], At[m][k], acc[ai][bj][m][n], 0, 0, 0); __builtin_amdgcn_s_setprio(0); } while (0)
; #define PG8_WAIT_V(n) asm volatile("s_waitcnt vmcnt(" #n ")" ::: "memory")
; #define PG8_WAIT_L(n) asm volatile("s_waitcnt lgkmcnt(" #n ")" ::: "memory")
; #define PG8_BAR __builtin_amdgcn_s_barrier()
; #define PG8_SCHED __builtin_amdgcn_sched_barrier(0)
; template <class Epi, class Sched>
; __device__ __forceinline__ void gemm_phase(LAS unsigned char* lds, const Gemm g, const Sched& S, const Epi& E) {
;     ...
;             PG8_LDA(At, 1, 1); PG8_STAGE(PG8_SB(1, 0), b3, voffB); PG8_STAGE(PG8_SB(1, 1), b3 + hstepB, voffB); PG8_STAGE(PG8_SA(1, 0), a3, voffA);
;             PG8_WAIT_V(8); PG8_WAIT_L(0); PG8_BAR; PG8_MMA(1, 0, At, B0); PG8_MMA(1, 1, At, B1); PG8_BAR; PG8_SCHED;
;         }
;         if (wr == 0) PG8_BAR;
	s_add_i32 s26, s50, s33
	v_lshl_add_u64 v[192:193], v[192:193], 0, s[56:57]
	s_mov_b32 m0, s26
	ds_read_b128 v[208:211], v190 offset:49152
	ds_read_b128 v[212:215], v190 offset:50176
	ds_read_b128 v[216:219], v190 offset:51200
	ds_read_b128 v[220:223], v190 offset:52224
	ds_read_b128 v[224:227], v190 offset:53248
	ds_read_b128 v[228:231], v190 offset:54272
	ds_read_b128 v[232:235], v190 offset:55296
	ds_read_b128 v[236:239], v190 offset:56320
	global_load_lds_dwordx4 v[192:193], off
	s_add_i32 m0, s26, 0x2000
	s_add_u32 s24, s24, 0x80080
	v_lshl_add_u64 v[192:193], v[240:241], 0, s[56:57]
	s_addc_u32 s25, s25, 0
	s_add_i32 s26, s51, s33
	global_load_lds_dwordx4 v[192:193], off
	v_lshl_add_u64 v[192:193], s[24:25], 0, v[164:165]
	s_mov_b32 m0, s26
	s_nop 0
	global_load_lds_dwordx4 v[192:193], off
	v_lshl_add_u64 v[192:193], s[24:25], 0, v[168:169]
	s_add_i32 m0, s26, 0x2000
	s_nop 0
	global_load_lds_dwordx4 v[192:193], off
	v_lshl_add_u64 v[192:193], v[242:243], 0, s[56:57]
	s_mov_b32 m0, s41
	s_nop 0
	global_load_lds_dwordx4 v[192:193], off
	v_lshl_add_u64 v[192:193], v[244:245], 0, s[56:57]
	s_mov_b32 m0, s42
	s_nop 0
	global_load_lds_dwordx4 v[192:193], off
	s_nop 0
	s_nop 0
	s_waitcnt vmcnt(8)
	s_waitcnt lgkmcnt(0)
	s_barrier
	s_setprio 1
	s_waitcnt lgkmcnt(0)
	v_mfma_f32_16x16x32_bf16 v[62:65], v[130:133], v[208:211], v[62:65]
	v_mfma_f32_16x16x32_bf16 v[58:61], v[138:141], v[208:211], v[58:61]
	v_mfma_f32_16x16x32_bf16 v[46:49], v[130:133], v[216:219], v[46:49]
	v_mfma_f32_16x16x32_bf16 v[42:45], v[138:141], v[216:219], v[42:45]
	v_mfma_f32_16x16x32_bf16 v[30:33], v[130:133], v[224:227], v[30:33]
	v_mfma_f32_16x16x32_bf16 v[26:29], v[138:141], v[224:227], v[26:29]
	v_mfma_f32_16x16x32_bf16 v[14:17], v[130:133], v[232:235], v[14:17]
	v_mfma_f32_16x16x32_bf16 v[10:13], v[138:141], v[232:235], v[10:13]
	v_mfma_f32_16x16x32_bf16 v[62:65], v[134:137], v[212:215], v[62:65]
	v_mfma_f32_16x16x32_bf16 v[58:61], v[142:145], v[212:215], v[58:61]
	v_mfma_f32_16x16x32_bf16 v[46:49], v[134:137], v[220:223], v[46:49]
	v_mfma_f32_16x16x32_bf16 v[42:45], v[142:145], v[220:223], v[42:45]
	v_mfma_f32_16x16x32_bf16 v[30:33], v[134:137], v[228:231], v[30:33]
	v_mfma_f32_16x16x32_bf16 v[26:29], v[142:145], v[228:231], v[26:29]
	v_mfma_f32_16x16x32_bf16 v[14:17], v[134:137], v[236:239], v[14:17]
	v_mfma_f32_16x16x32_bf16 v[10:13], v[142:145], v[236:239], v[10:13]
	s_setprio 0
	s_setprio 1
	v_mfma_f32_16x16x32_bf16 v[54:57], v[174:177], v[208:211], v[54:57]
	v_mfma_f32_16x16x32_bf16 v[50:53], v[182:185], v[208:211], v[50:53]
	v_mfma_f32_16x16x32_bf16 v[38:41], v[174:177], v[216:219], v[38:41]
	v_mfma_f32_16x16x32_bf16 v[34:37], v[182:185], v[216:219], v[34:37]
	v_mfma_f32_16x16x32_bf16 v[22:25], v[174:177], v[224:227], v[22:25]
	v_mfma_f32_16x16x32_bf16 v[18:21], v[182:185], v[224:227], v[18:21]
	v_mfma_f32_16x16x32_bf16 v[6:9], v[174:177], v[232:235], v[6:9]
	v_mfma_f32_16x16x32_bf16 v[2:5], v[182:185], v[232:235], v[2:5]
	v_mfma_f32_16x16x32_bf16 v[54:57], v[178:181], v[212:215], v[54:57]
	v_mfma_f32_16x16x32_bf16 v[50:53], v[186:189], v[212:215], v[50:53]
	v_mfma_f32_16x16x32_bf16 v[38:41], v[178:181], v[220:223], v[38:41]
	v_mfma_f32_16x16x32_bf16 v[34:37], v[186:189], v[220:223], v[34:37]
	v_mfma_f32_16x16x32_bf16 v[22:25], v[178:181], v[228:231], v[22:25]
	v_mfma_f32_16x16x32_bf16 v[18:21], v[186:189], v[228:231], v[18:21]
	v_mfma_f32_16x16x32_bf16 v[6:9], v[178:181], v[236:239], v[6:9]
	v_mfma_f32_16x16x32_bf16 v[2:5], v[186:189], v[236:239], v[2:5]
	s_setprio 0
	s_barrier
	s_add_i32 s49, s49, 2
	s_add_u32 s22, s22, 0x100
	s_addc_u32 s23, s23, 0
	s_add_u32 s46, s46, 0x100
	s_addc_u32 s47, s47, 0
	s_cmp_gt_u32 s49, 29
	s_cbranch_scc0 .LBB0_4423
	s_and_b64 vcc, exec, s[6:7]
	s_cbranch_vccz .LBB0_4426
	s_barrier
